# speedup vs baseline: 1.0507x; 1.0060x over previous
.LBB0_252:
	s_or_b64 exec, exec, s[10:11]
	v_add_u32_e32 v0, s53, v208
	v_add_u32_e32 v34, 0x80, v0
	v_cmp_le_i32_e32 vcc, v34, v157
	s_mov_b64 s[40:41], 0
	s_and_saveexec_b64 s[10:11], vcc
	s_cbranch_execz .LBB0_262
	v_add_u32_e32 v194, v191, v203
	v_add_u32_e32 v46, s33, v189
	v_mov_b32_e32 v248, s33
	ds_read_b32 v249, v248 offset:36348
	ds_read_b32 v248, v248 offset:35840
	ds_read_b128 v[220:223], v194
	ds_read_b128 v[82:85], v46 offset:35840
	ds_read_b128 v[86:89], v46 offset:35856
	ds_read_b128 v[90:93], v46 offset:35904
	ds_read_b128 v[94:97], v46 offset:35920
	ds_read_b128 v[224:227], v194 offset:4608
	ds_read_b128 v[66:69], v46 offset:35968
	ds_read_b128 v[70:73], v46 offset:35984
	ds_read_b128 v[74:77], v46 offset:36032
	ds_read_b128 v[78:81], v46 offset:36048
	ds_read_b128 v[228:231], v194 offset:9216
	ds_read_b128 v[50:53], v46 offset:36096
	ds_read_b128 v[54:57], v46 offset:36112
	ds_read_b128 v[58:61], v46 offset:36160
	ds_read_b128 v[62:65], v46 offset:36176
	ds_read_b128 v[232:235], v194 offset:13824
	ds_read_b128 v[34:37], v46 offset:36224
	ds_read_b128 v[38:41], v46 offset:36240
	ds_read_b128 v[42:45], v46 offset:36288
	ds_read_b128 v[46:49], v46 offset:36304
	ds_read_b128 v[236:239], v194 offset:32
	ds_read_b128 v[240:243], v194 offset:4640
	v_add_u32_e32 v0, 0xff, v0
	v_cmp_gt_i32_e32 vcc, v0, v160
	s_waitcnt lgkmcnt(15)
	v_mfma_f32_32x32x16_bf16 v[82:97], v[220:223], v[98:101], v[82:97]
	ds_read_b128 v[220:223], v194 offset:9248
	s_waitcnt lgkmcnt(13)
	v_mfma_f32_32x32x16_bf16 v[66:81], v[224:227], v[98:101], v[66:81]
	ds_read_b128 v[224:227], v194 offset:13856
	s_waitcnt lgkmcnt(9)
	v_mfma_f32_32x32x16_bf16 v[50:65], v[228:231], v[98:101], v[50:65]
	ds_read_b128 v[228:231], v194 offset:64
	s_waitcnt lgkmcnt(5)
	v_mfma_f32_32x32x16_bf16 v[34:49], v[232:235], v[98:101], v[34:49]
	ds_read_b128 v[232:235], v194 offset:4672
	s_waitcnt lgkmcnt(5)
	v_mfma_f32_32x32x16_bf16 v[82:97], v[236:239], v[102:105], v[82:97]
	ds_read_b128 v[236:239], v194 offset:9280
	s_waitcnt lgkmcnt(5)
	v_mfma_f32_32x32x16_bf16 v[66:81], v[240:243], v[102:105], v[66:81]
	ds_read_b128 v[240:243], v194 offset:13888
	s_waitcnt lgkmcnt(5)
	v_mfma_f32_32x32x16_bf16 v[50:65], v[220:223], v[102:105], v[50:65]
	ds_read_b128 v[220:223], v194 offset:96
	s_waitcnt lgkmcnt(5)
	v_mfma_f32_32x32x16_bf16 v[34:49], v[224:227], v[102:105], v[34:49]
	ds_read_b128 v[224:227], v194 offset:4704
	s_waitcnt lgkmcnt(5)
	v_mfma_f32_32x32x16_bf16 v[82:97], v[228:231], v[106:109], v[82:97]
	ds_read_b128 v[228:231], v194 offset:9312
	s_waitcnt lgkmcnt(5)
	v_mfma_f32_32x32x16_bf16 v[66:81], v[232:235], v[106:109], v[66:81]
	ds_read_b128 v[232:235], v194 offset:13920
	s_waitcnt lgkmcnt(5)
	v_mfma_f32_32x32x16_bf16 v[50:65], v[236:239], v[106:109], v[50:65]
	s_waitcnt lgkmcnt(4)
	v_mfma_f32_32x32x16_bf16 v[34:49], v[240:243], v[106:109], v[34:49]
	s_waitcnt lgkmcnt(3)
	v_mfma_f32_32x32x16_bf16 v[82:97], v[220:223], v[110:113], v[82:97]
	s_waitcnt lgkmcnt(2)
	v_mfma_f32_32x32x16_bf16 v[66:81], v[224:227], v[110:113], v[66:81]
	s_waitcnt lgkmcnt(1)
	v_mfma_f32_32x32x16_bf16 v[50:65], v[228:231], v[110:113], v[50:65]
	s_waitcnt lgkmcnt(0)
	v_mfma_f32_32x32x16_bf16 v[34:49], v[232:235], v[110:113], v[34:49]
	s_and_saveexec_b64 s[40:41], vcc
	s_cbranch_execz .LBB0_255
	v_add_u32_e32 v0, s53, v155
	v_add_u32_e32 v194, 0x80, v0
	v_cmp_lt_i32_e32 vcc, v194, v162
	s_nop 1
	v_cndmask_b32_e32 v83, v207, v83, vcc
	v_cmp_le_i32_e32 vcc, v194, v162
	v_add_u32_e32 v194, 0x82, v0
	s_nop 0
	v_cndmask_b32_e32 v82, v207, v82, vcc
	v_cmp_le_i32_e32 vcc, v194, v162
	v_add_u32_e32 v194, 0x83, v0
	s_nop 0
	v_cndmask_b32_e32 v84, v207, v84, vcc
	v_cmp_le_i32_e32 vcc, v194, v162
	v_add_u32_e32 v194, 0x84, v0
	s_nop 0
	v_cndmask_b32_e32 v85, v207, v85, vcc
	v_cmp_le_i32_e32 vcc, v194, v162
	v_add_u32_e32 v194, 0x85, v0
	s_nop 0
	v_cndmask_b32_e32 v86, v207, v86, vcc
	v_cmp_le_i32_e32 vcc, v194, v162
	v_add_u32_e32 v194, 0x86, v0
	s_nop 0
	v_cndmask_b32_e32 v87, v207, v87, vcc
	v_cmp_le_i32_e32 vcc, v194, v162
	v_add_u32_e32 v194, 0x87, v0
	s_nop 0
	v_cndmask_b32_e32 v88, v207, v88, vcc
	v_cmp_le_i32_e32 vcc, v194, v162
	v_add_u32_e32 v194, 0x90, v0
	s_nop 0
	v_cndmask_b32_e32 v89, v207, v89, vcc
	v_cmp_le_i32_e32 vcc, v194, v162
	v_add_u32_e32 v194, 0x91, v0
	s_nop 0
	v_cndmask_b32_e32 v90, v207, v90, vcc
	v_cmp_le_i32_e32 vcc, v194, v162
	v_add_u32_e32 v194, 0x92, v0
	s_nop 0
	v_cndmask_b32_e32 v91, v207, v91, vcc
	v_cmp_le_i32_e32 vcc, v194, v162
	v_add_u32_e32 v194, 0x93, v0
	s_nop 0
	v_cndmask_b32_e32 v92, v207, v92, vcc
	v_cmp_le_i32_e32 vcc, v194, v162
	v_add_u32_e32 v194, 0x94, v0
	s_nop 0
	v_cndmask_b32_e32 v93, v207, v93, vcc
	v_cmp_le_i32_e32 vcc, v194, v162
	v_add_u32_e32 v194, 0x95, v0
	s_nop 0
	v_cndmask_b32_e32 v94, v207, v94, vcc
	v_cmp_le_i32_e32 vcc, v194, v162
	v_add_u32_e32 v194, 0x96, v0
	s_nop 0
	v_cndmask_b32_e32 v95, v207, v95, vcc
	v_cmp_le_i32_e32 vcc, v194, v162
	v_add_u32_e32 v194, 0x97, v0
	s_nop 0
	v_cndmask_b32_e32 v96, v207, v96, vcc
	v_cmp_le_i32_e32 vcc, v194, v162
	v_add_u32_e32 v194, 0xa0, v0
	s_nop 0
	v_cndmask_b32_e32 v97, v207, v97, vcc
	v_cmp_le_i32_e32 vcc, v194, v162
	v_add_u32_e32 v194, 0xa1, v0
	s_nop 0
	v_cndmask_b32_e32 v66, v207, v66, vcc
	v_cmp_le_i32_e32 vcc, v194, v162
	v_add_u32_e32 v194, 0xa2, v0
	s_nop 0
	v_cndmask_b32_e32 v67, v207, v67, vcc
	v_cmp_le_i32_e32 vcc, v194, v162
	v_add_u32_e32 v194, 0xa3, v0
	s_nop 0
	v_cndmask_b32_e32 v68, v207, v68, vcc
	v_cmp_le_i32_e32 vcc, v194, v162
	v_add_u32_e32 v194, 0xa4, v0
	s_nop 0
	v_cndmask_b32_e32 v69, v207, v69, vcc
	v_cmp_le_i32_e32 vcc, v194, v162
	v_add_u32_e32 v194, 0xa5, v0
	s_nop 0
	v_cndmask_b32_e32 v70, v207, v70, vcc
	v_cmp_le_i32_e32 vcc, v194, v162
	v_add_u32_e32 v194, 0xa6, v0
	s_nop 0
	v_cndmask_b32_e32 v71, v207, v71, vcc
	v_cmp_le_i32_e32 vcc, v194, v162
	v_add_u32_e32 v194, 0xa7, v0
	s_nop 0
	v_cndmask_b32_e32 v72, v207, v72, vcc
	v_cmp_le_i32_e32 vcc, v194, v162
	v_add_u32_e32 v194, 0xb0, v0
	s_nop 0
	v_cndmask_b32_e32 v73, v207, v73, vcc
	v_cmp_le_i32_e32 vcc, v194, v162
	v_add_u32_e32 v194, 0xb1, v0
	s_nop 0
	v_cndmask_b32_e32 v74, v207, v74, vcc
	v_cmp_le_i32_e32 vcc, v194, v162
	v_add_u32_e32 v194, 0xb2, v0
	s_nop 0
	v_cndmask_b32_e32 v75, v207, v75, vcc
	v_cmp_le_i32_e32 vcc, v194, v162
	v_add_u32_e32 v194, 0xb3, v0
	s_nop 0
	v_cndmask_b32_e32 v76, v207, v76, vcc
	v_cmp_le_i32_e32 vcc, v194, v162
	v_add_u32_e32 v194, 0xb4, v0
	s_nop 0
	v_cndmask_b32_e32 v77, v207, v77, vcc
	v_cmp_le_i32_e32 vcc, v194, v162
	v_add_u32_e32 v194, 0xb5, v0
	s_nop 0
	v_cndmask_b32_e32 v78, v207, v78, vcc
	v_cmp_le_i32_e32 vcc, v194, v162
	v_add_u32_e32 v194, 0xb6, v0
	s_nop 0
	v_cndmask_b32_e32 v79, v207, v79, vcc
	v_cmp_le_i32_e32 vcc, v194, v162
	v_add_u32_e32 v194, 0xb7, v0
	s_nop 0
	v_cndmask_b32_e32 v80, v207, v80, vcc
	v_cmp_le_i32_e32 vcc, v194, v162
	v_add_u32_e32 v194, 0xc0, v0
	s_nop 0
	v_cndmask_b32_e32 v81, v207, v81, vcc
	v_cmp_le_i32_e32 vcc, v194, v162
	v_add_u32_e32 v194, 0xc1, v0
	s_nop 0
	v_cndmask_b32_e32 v50, v207, v50, vcc
	v_cmp_le_i32_e32 vcc, v194, v162
	v_add_u32_e32 v194, 0xc2, v0
	s_nop 0
	v_cndmask_b32_e32 v51, v207, v51, vcc
	v_cmp_le_i32_e32 vcc, v194, v162
	v_add_u32_e32 v194, 0xc3, v0
	s_nop 0
	v_cndmask_b32_e32 v52, v207, v52, vcc
	v_cmp_le_i32_e32 vcc, v194, v162
	v_add_u32_e32 v194, 0xc4, v0
	s_nop 0
	v_cndmask_b32_e32 v53, v207, v53, vcc
	v_cmp_le_i32_e32 vcc, v194, v162
	v_add_u32_e32 v194, 0xc5, v0
	s_nop 0
	v_cndmask_b32_e32 v54, v207, v54, vcc
	v_cmp_le_i32_e32 vcc, v194, v162
	v_add_u32_e32 v194, 0xc6, v0
	s_nop 0
	v_cndmask_b32_e32 v55, v207, v55, vcc
	v_cmp_le_i32_e32 vcc, v194, v162
	v_add_u32_e32 v194, 0xc7, v0
	s_nop 0
	v_cndmask_b32_e32 v56, v207, v56, vcc
	v_cmp_le_i32_e32 vcc, v194, v162
	v_add_u32_e32 v194, 0xd0, v0
	s_nop 0
	v_cndmask_b32_e32 v57, v207, v57, vcc
	v_cmp_le_i32_e32 vcc, v194, v162
	v_add_u32_e32 v194, 0xd1, v0
	s_nop 0
	v_cndmask_b32_e32 v58, v207, v58, vcc
	v_cmp_le_i32_e32 vcc, v194, v162
	v_add_u32_e32 v194, 0xd2, v0
	s_nop 0
	v_cndmask_b32_e32 v59, v207, v59, vcc
	v_cmp_le_i32_e32 vcc, v194, v162
	v_add_u32_e32 v194, 0xd3, v0
	s_nop 0
	v_cndmask_b32_e32 v60, v207, v60, vcc
	v_cmp_le_i32_e32 vcc, v194, v162
	v_add_u32_e32 v194, 0xd4, v0
	s_nop 0
	v_cndmask_b32_e32 v61, v207, v61, vcc
	v_cmp_le_i32_e32 vcc, v194, v162
	v_add_u32_e32 v194, 0xd5, v0
	s_nop 0
	v_cndmask_b32_e32 v62, v207, v62, vcc
	v_cmp_le_i32_e32 vcc, v194, v162
	v_add_u32_e32 v194, 0xd6, v0
	s_nop 0
	v_cndmask_b32_e32 v63, v207, v63, vcc
	v_cmp_le_i32_e32 vcc, v194, v162
	v_add_u32_e32 v194, 0xd7, v0
	s_nop 0
	v_cndmask_b32_e32 v64, v207, v64, vcc
	v_cmp_le_i32_e32 vcc, v194, v162
	v_add_u32_e32 v194, 0xe0, v0
	s_nop 0
	v_cndmask_b32_e32 v65, v207, v65, vcc
	v_cmp_le_i32_e32 vcc, v194, v162
	v_add_u32_e32 v194, 0xe1, v0
	s_nop 0
	v_cndmask_b32_e32 v34, v207, v34, vcc
	v_cmp_le_i32_e32 vcc, v194, v162
	v_add_u32_e32 v194, 0xe2, v0
	s_nop 0
	v_cndmask_b32_e32 v35, v207, v35, vcc
	v_cmp_le_i32_e32 vcc, v194, v162
	v_add_u32_e32 v194, 0xe3, v0
	s_nop 0
	v_cndmask_b32_e32 v36, v207, v36, vcc
	v_cmp_le_i32_e32 vcc, v194, v162
	v_add_u32_e32 v194, 0xe4, v0
	s_nop 0
	v_cndmask_b32_e32 v37, v207, v37, vcc
	v_cmp_le_i32_e32 vcc, v194, v162
	v_add_u32_e32 v194, 0xe5, v0
	s_nop 0
	v_cndmask_b32_e32 v38, v207, v38, vcc
	v_cmp_le_i32_e32 vcc, v194, v162
	v_add_u32_e32 v194, 0xe6, v0
	s_nop 0
	v_cndmask_b32_e32 v39, v207, v39, vcc
	v_cmp_le_i32_e32 vcc, v194, v162
	v_add_u32_e32 v194, 0xe7, v0
	s_nop 0
	v_cndmask_b32_e32 v40, v207, v40, vcc
	v_cmp_le_i32_e32 vcc, v194, v162
	v_add_u32_e32 v194, 0xf0, v0
	s_nop 0
	v_cndmask_b32_e32 v41, v207, v41, vcc
	v_cmp_le_i32_e32 vcc, v194, v162
	v_add_u32_e32 v194, 0xf1, v0
	s_nop 0
	v_cndmask_b32_e32 v42, v207, v42, vcc
	v_cmp_le_i32_e32 vcc, v194, v162
	v_add_u32_e32 v194, 0xf2, v0
	s_nop 0
	v_cndmask_b32_e32 v43, v207, v43, vcc
	v_cmp_le_i32_e32 vcc, v194, v162
	v_add_u32_e32 v194, 0xf3, v0
	s_nop 0
	v_cndmask_b32_e32 v44, v207, v44, vcc
	v_cmp_le_i32_e32 vcc, v194, v162
	v_add_u32_e32 v194, 0xf4, v0
	s_nop 0
	v_cndmask_b32_e32 v45, v207, v45, vcc
	v_cmp_le_i32_e32 vcc, v194, v162
	v_add_u32_e32 v194, 0xf5, v0
	s_nop 0
	v_cndmask_b32_e32 v46, v207, v46, vcc
	v_cmp_le_i32_e32 vcc, v194, v162
	v_add_u32_e32 v194, 0xf6, v0
	v_add_u32_e32 v0, 0xf7, v0
	v_cndmask_b32_e32 v47, v207, v47, vcc
	v_cmp_le_i32_e32 vcc, v194, v162
	s_nop 1
	v_cndmask_b32_e32 v48, v207, v48, vcc
	v_cmp_le_i32_e32 vcc, v0, v162
	s_nop 1
	v_cndmask_b32_e32 v49, v207, v49, vcc

.LBB0_270:
	s_or_b64 exec, exec, s[40:41]
	v_add_u32_e32 v177, s53, v208
	v_cmp_le_i32_e32 vcc, v177, v157
	s_mov_b64 s[42:43], 0
	s_and_saveexec_b64 s[40:41], vcc
	s_cbranch_execz .LBB0_280
	v_add_u32_e32 v194, v191, v203
	v_add_u32_e32 v46, s47, v189
	v_mov_b32_e32 v248, s47
	ds_read_b32 v249, v248 offset:508
	ds_read_b32 v248, v248
	ds_read_b128 v[220:223], v194 offset:39936
	ds_read_b128 v[82:85], v46
	ds_read_b128 v[86:89], v46 offset:16
	ds_read_b128 v[90:93], v46 offset:64
	ds_read_b128 v[94:97], v46 offset:80
	ds_read_b128 v[224:227], v194 offset:44544
	ds_read_b128 v[66:69], v46 offset:128
	ds_read_b128 v[70:73], v46 offset:144
	ds_read_b128 v[74:77], v46 offset:192
	ds_read_b128 v[78:81], v46 offset:208
	ds_read_b128 v[228:231], v194 offset:49152
	ds_read_b128 v[50:53], v46 offset:256
	ds_read_b128 v[54:57], v46 offset:272
	ds_read_b128 v[58:61], v46 offset:320
	ds_read_b128 v[62:65], v46 offset:336
	ds_read_b128 v[232:235], v194 offset:53760
	ds_read_b128 v[34:37], v46 offset:384
	ds_read_b128 v[38:41], v46 offset:400
	ds_read_b128 v[42:45], v46 offset:448
	ds_read_b128 v[46:49], v46 offset:464
	ds_read_b128 v[236:239], v194 offset:39968
	ds_read_b128 v[240:243], v194 offset:44576
	v_add_u32_e32 v177, 0x7f, v177
	v_cmp_gt_i32_e32 vcc, v177, v160
	s_waitcnt lgkmcnt(15)
	v_mfma_f32_32x32x16_bf16 v[82:97], v[220:223], v[98:101], v[82:97]
	ds_read_b128 v[220:223], v194 offset:49184
	s_waitcnt lgkmcnt(13)
	v_mfma_f32_32x32x16_bf16 v[66:81], v[224:227], v[98:101], v[66:81]
	ds_read_b128 v[224:227], v194 offset:53792
	s_waitcnt lgkmcnt(9)
	v_mfma_f32_32x32x16_bf16 v[50:65], v[228:231], v[98:101], v[50:65]
	ds_read_b128 v[228:231], v194 offset:40000
	s_waitcnt lgkmcnt(5)
	v_mfma_f32_32x32x16_bf16 v[34:49], v[232:235], v[98:101], v[34:49]
	ds_read_b128 v[232:235], v194 offset:44608
	s_waitcnt lgkmcnt(5)
	v_mfma_f32_32x32x16_bf16 v[82:97], v[236:239], v[102:105], v[82:97]
	ds_read_b128 v[236:239], v194 offset:49216
	s_waitcnt lgkmcnt(5)
	v_mfma_f32_32x32x16_bf16 v[66:81], v[240:243], v[102:105], v[66:81]
	ds_read_b128 v[240:243], v194 offset:53824
	s_waitcnt lgkmcnt(5)
	v_mfma_f32_32x32x16_bf16 v[50:65], v[220:223], v[102:105], v[50:65]
	ds_read_b128 v[220:223], v194 offset:40032
	s_waitcnt lgkmcnt(5)
	v_mfma_f32_32x32x16_bf16 v[34:49], v[224:227], v[102:105], v[34:49]
	ds_read_b128 v[224:227], v194 offset:44640
	s_waitcnt lgkmcnt(5)
	v_mfma_f32_32x32x16_bf16 v[82:97], v[228:231], v[106:109], v[82:97]
	ds_read_b128 v[228:231], v194 offset:49248
	s_waitcnt lgkmcnt(5)
	v_mfma_f32_32x32x16_bf16 v[66:81], v[232:235], v[106:109], v[66:81]
	ds_read_b128 v[232:235], v194 offset:53856
	s_waitcnt lgkmcnt(5)
	v_mfma_f32_32x32x16_bf16 v[50:65], v[236:239], v[106:109], v[50:65]
	s_waitcnt lgkmcnt(4)
	v_mfma_f32_32x32x16_bf16 v[34:49], v[240:243], v[106:109], v[34:49]
	s_waitcnt lgkmcnt(3)
	v_mfma_f32_32x32x16_bf16 v[82:97], v[220:223], v[110:113], v[82:97]
	s_waitcnt lgkmcnt(2)
	v_mfma_f32_32x32x16_bf16 v[66:81], v[224:227], v[110:113], v[66:81]
	s_waitcnt lgkmcnt(1)
	v_mfma_f32_32x32x16_bf16 v[50:65], v[228:231], v[110:113], v[50:65]
	s_waitcnt lgkmcnt(0)
	v_mfma_f32_32x32x16_bf16 v[34:49], v[232:235], v[110:113], v[34:49]
	s_and_saveexec_b64 s[42:43], vcc
	s_cbranch_execz .LBB0_273
	v_add_u32_e32 v177, s53, v155
	v_cmp_lt_i32_e32 vcc, v177, v162
	v_add_u32_e32 v194, 2, v177
	s_nop 0
	v_cndmask_b32_e32 v83, v207, v83, vcc
	v_cmp_le_i32_e32 vcc, v177, v162
	s_nop 1
	v_cndmask_b32_e32 v82, v207, v82, vcc
	v_cmp_le_i32_e32 vcc, v194, v162
	v_add_u32_e32 v194, 3, v177
	s_nop 0
	v_cndmask_b32_e32 v84, v207, v84, vcc
	v_cmp_le_i32_e32 vcc, v194, v162
	v_add_u32_e32 v194, 4, v177
	s_nop 0
	v_cndmask_b32_e32 v85, v207, v85, vcc
	v_cmp_le_i32_e32 vcc, v194, v162
	v_add_u32_e32 v194, 5, v177
	s_nop 0
	v_cndmask_b32_e32 v86, v207, v86, vcc
	v_cmp_le_i32_e32 vcc, v194, v162
	v_add_u32_e32 v194, 6, v177
	s_nop 0
	v_cndmask_b32_e32 v87, v207, v87, vcc
	v_cmp_le_i32_e32 vcc, v194, v162
	v_add_u32_e32 v194, 7, v177
	s_nop 0
	v_cndmask_b32_e32 v88, v207, v88, vcc
	v_cmp_le_i32_e32 vcc, v194, v162
	v_add_u32_e32 v194, 16, v177
	s_nop 0
	v_cndmask_b32_e32 v89, v207, v89, vcc
	v_cmp_le_i32_e32 vcc, v194, v162
	v_add_u32_e32 v194, 17, v177
	s_nop 0
	v_cndmask_b32_e32 v90, v207, v90, vcc
	v_cmp_le_i32_e32 vcc, v194, v162
	v_add_u32_e32 v194, 18, v177
	s_nop 0
	v_cndmask_b32_e32 v91, v207, v91, vcc
	v_cmp_le_i32_e32 vcc, v194, v162
	v_add_u32_e32 v194, 19, v177
	s_nop 0
	v_cndmask_b32_e32 v92, v207, v92, vcc
	v_cmp_le_i32_e32 vcc, v194, v162
	v_add_u32_e32 v194, 20, v177
	s_nop 0
	v_cndmask_b32_e32 v93, v207, v93, vcc
	v_cmp_le_i32_e32 vcc, v194, v162
	v_add_u32_e32 v194, 21, v177
	s_nop 0
	v_cndmask_b32_e32 v94, v207, v94, vcc
	v_cmp_le_i32_e32 vcc, v194, v162
	v_add_u32_e32 v194, 22, v177
	s_nop 0
	v_cndmask_b32_e32 v95, v207, v95, vcc
	v_cmp_le_i32_e32 vcc, v194, v162
	v_add_u32_e32 v194, 23, v177
	s_nop 0
	v_cndmask_b32_e32 v96, v207, v96, vcc
	v_cmp_le_i32_e32 vcc, v194, v162
	v_add_u32_e32 v194, 32, v177
	s_nop 0
	v_cndmask_b32_e32 v97, v207, v97, vcc
	v_cmp_le_i32_e32 vcc, v194, v162
	v_add_u32_e32 v194, 33, v177
	s_nop 0
	v_cndmask_b32_e32 v66, v207, v66, vcc
	v_cmp_le_i32_e32 vcc, v194, v162
	v_add_u32_e32 v194, 34, v177
	s_nop 0
	v_cndmask_b32_e32 v67, v207, v67, vcc
	v_cmp_le_i32_e32 vcc, v194, v162
	v_add_u32_e32 v194, 35, v177
	s_nop 0
	v_cndmask_b32_e32 v68, v207, v68, vcc
	v_cmp_le_i32_e32 vcc, v194, v162
	v_add_u32_e32 v194, 36, v177
	s_nop 0
	v_cndmask_b32_e32 v69, v207, v69, vcc
	v_cmp_le_i32_e32 vcc, v194, v162
	v_add_u32_e32 v194, 37, v177
	s_nop 0
	v_cndmask_b32_e32 v70, v207, v70, vcc
	v_cmp_le_i32_e32 vcc, v194, v162
	v_add_u32_e32 v194, 38, v177
	s_nop 0
	v_cndmask_b32_e32 v71, v207, v71, vcc
	v_cmp_le_i32_e32 vcc, v194, v162
	v_add_u32_e32 v194, 39, v177
	s_nop 0
	v_cndmask_b32_e32 v72, v207, v72, vcc
	v_cmp_le_i32_e32 vcc, v194, v162
	v_add_u32_e32 v194, 48, v177
	s_nop 0
	v_cndmask_b32_e32 v73, v207, v73, vcc
	v_cmp_le_i32_e32 vcc, v194, v162
	v_add_u32_e32 v194, 49, v177
	s_nop 0
	v_cndmask_b32_e32 v74, v207, v74, vcc
	v_cmp_le_i32_e32 vcc, v194, v162
	v_add_u32_e32 v194, 50, v177
	s_nop 0
	v_cndmask_b32_e32 v75, v207, v75, vcc
	v_cmp_le_i32_e32 vcc, v194, v162
	v_add_u32_e32 v194, 51, v177
	s_nop 0
	v_cndmask_b32_e32 v76, v207, v76, vcc
	v_cmp_le_i32_e32 vcc, v194, v162
	v_add_u32_e32 v194, 52, v177
	s_nop 0
	v_cndmask_b32_e32 v77, v207, v77, vcc
	v_cmp_le_i32_e32 vcc, v194, v162
	v_add_u32_e32 v194, 53, v177
	s_nop 0
	v_cndmask_b32_e32 v78, v207, v78, vcc
	v_cmp_le_i32_e32 vcc, v194, v162
	v_add_u32_e32 v194, 54, v177
	s_nop 0
	v_cndmask_b32_e32 v79, v207, v79, vcc
	v_cmp_le_i32_e32 vcc, v194, v162
	v_add_u32_e32 v194, 55, v177
	s_nop 0
	v_cndmask_b32_e32 v80, v207, v80, vcc
	v_cmp_le_i32_e32 vcc, v194, v162
	v_add_u32_e32 v194, 64, v177
	s_nop 0
	v_cndmask_b32_e32 v81, v207, v81, vcc
	v_cmp_le_i32_e32 vcc, v194, v162
	v_add_u32_e32 v194, 0x41, v177
	s_nop 0
	v_cndmask_b32_e32 v50, v207, v50, vcc
	v_cmp_le_i32_e32 vcc, v194, v162
	v_add_u32_e32 v194, 0x42, v177
	s_nop 0
	v_cndmask_b32_e32 v51, v207, v51, vcc
	v_cmp_le_i32_e32 vcc, v194, v162
	v_add_u32_e32 v194, 0x43, v177
	s_nop 0
	v_cndmask_b32_e32 v52, v207, v52, vcc
	v_cmp_le_i32_e32 vcc, v194, v162
	v_add_u32_e32 v194, 0x44, v177
	s_nop 0
	v_cndmask_b32_e32 v53, v207, v53, vcc
	v_cmp_le_i32_e32 vcc, v194, v162
	v_add_u32_e32 v194, 0x45, v177
	s_nop 0
	v_cndmask_b32_e32 v54, v207, v54, vcc
	v_cmp_le_i32_e32 vcc, v194, v162
	v_add_u32_e32 v194, 0x46, v177
	s_nop 0
	v_cndmask_b32_e32 v55, v207, v55, vcc
	v_cmp_le_i32_e32 vcc, v194, v162
	v_add_u32_e32 v194, 0x47, v177
	s_nop 0
	v_cndmask_b32_e32 v56, v207, v56, vcc
	v_cmp_le_i32_e32 vcc, v194, v162
	v_add_u32_e32 v194, 0x50, v177
	s_nop 0
	v_cndmask_b32_e32 v57, v207, v57, vcc
	v_cmp_le_i32_e32 vcc, v194, v162
	v_add_u32_e32 v194, 0x51, v177
	s_nop 0
	v_cndmask_b32_e32 v58, v207, v58, vcc
	v_cmp_le_i32_e32 vcc, v194, v162
	v_add_u32_e32 v194, 0x52, v177
	s_nop 0
	v_cndmask_b32_e32 v59, v207, v59, vcc
	v_cmp_le_i32_e32 vcc, v194, v162
	v_add_u32_e32 v194, 0x53, v177
	s_nop 0
	v_cndmask_b32_e32 v60, v207, v60, vcc
	v_cmp_le_i32_e32 vcc, v194, v162
	v_add_u32_e32 v194, 0x54, v177
	s_nop 0
	v_cndmask_b32_e32 v61, v207, v61, vcc
	v_cmp_le_i32_e32 vcc, v194, v162
	v_add_u32_e32 v194, 0x55, v177
	s_nop 0
	v_cndmask_b32_e32 v62, v207, v62, vcc
	v_cmp_le_i32_e32 vcc, v194, v162
	v_add_u32_e32 v194, 0x56, v177
	s_nop 0
	v_cndmask_b32_e32 v63, v207, v63, vcc
	v_cmp_le_i32_e32 vcc, v194, v162
	v_add_u32_e32 v194, 0x57, v177
	s_nop 0
	v_cndmask_b32_e32 v64, v207, v64, vcc
	v_cmp_le_i32_e32 vcc, v194, v162
	v_add_u32_e32 v194, 0x60, v177
	s_nop 0
	v_cndmask_b32_e32 v65, v207, v65, vcc
	v_cmp_le_i32_e32 vcc, v194, v162
	v_add_u32_e32 v194, 0x61, v177
	s_nop 0
	v_cndmask_b32_e32 v34, v207, v34, vcc
	v_cmp_le_i32_e32 vcc, v194, v162
	v_add_u32_e32 v194, 0x62, v177
	s_nop 0
	v_cndmask_b32_e32 v35, v207, v35, vcc
	v_cmp_le_i32_e32 vcc, v194, v162
	v_add_u32_e32 v194, 0x63, v177
	s_nop 0
	v_cndmask_b32_e32 v36, v207, v36, vcc
	v_cmp_le_i32_e32 vcc, v194, v162
	v_add_u32_e32 v194, 0x64, v177
	s_nop 0
	v_cndmask_b32_e32 v37, v207, v37, vcc
	v_cmp_le_i32_e32 vcc, v194, v162
	v_add_u32_e32 v194, 0x65, v177
	s_nop 0
	v_cndmask_b32_e32 v38, v207, v38, vcc
	v_cmp_le_i32_e32 vcc, v194, v162
	v_add_u32_e32 v194, 0x66, v177
	s_nop 0
	v_cndmask_b32_e32 v39, v207, v39, vcc
	v_cmp_le_i32_e32 vcc, v194, v162
	v_add_u32_e32 v194, 0x67, v177
	s_nop 0
	v_cndmask_b32_e32 v40, v207, v40, vcc
	v_cmp_le_i32_e32 vcc, v194, v162
	v_add_u32_e32 v194, 0x70, v177
	s_nop 0
	v_cndmask_b32_e32 v41, v207, v41, vcc
	v_cmp_le_i32_e32 vcc, v194, v162
	v_add_u32_e32 v194, 0x71, v177
	s_nop 0
	v_cndmask_b32_e32 v42, v207, v42, vcc
	v_cmp_le_i32_e32 vcc, v194, v162
	v_add_u32_e32 v194, 0x72, v177
	s_nop 0
	v_cndmask_b32_e32 v43, v207, v43, vcc
	v_cmp_le_i32_e32 vcc, v194, v162
	v_add_u32_e32 v194, 0x73, v177
	s_nop 0
	v_cndmask_b32_e32 v44, v207, v44, vcc
	v_cmp_le_i32_e32 vcc, v194, v162
	v_add_u32_e32 v194, 0x74, v177
	s_nop 0
	v_cndmask_b32_e32 v45, v207, v45, vcc
	v_cmp_le_i32_e32 vcc, v194, v162
	v_add_u32_e32 v194, 0x75, v177
	s_nop 0
	v_cndmask_b32_e32 v46, v207, v46, vcc
	v_cmp_le_i32_e32 vcc, v194, v162
	v_add_u32_e32 v194, 0x76, v177
	v_add_u32_e32 v177, 0x77, v177
	v_cndmask_b32_e32 v47, v207, v47, vcc
	v_cmp_le_i32_e32 vcc, v194, v162
	s_nop 1
	v_cndmask_b32_e32 v48, v207, v48, vcc
	v_cmp_le_i32_e32 vcc, v177, v162
	s_nop 1
	v_cndmask_b32_e32 v49, v207, v49, vcc

; DI_ void ssm_conv_tile(int tile, const unsigned char* buf, unsigned char* obuf, const float* cw, const float* cbias, bf16_t* xsT, bf16_t* Btok, bf16_t* BT, bf16_t* Ctok, int tid) {
;     const int ct = tile & 63, tt = tile >> 6, ch0 = ct * 64, tb = tt * 128;
;     const int ch = tid & 63, run = tid >> 6, tl0 = run * 16, chg = ch0 + ch;
;     const float w0 = cw[chg], w1 = cw[4096 + chg], w2 = cw[2 * 4096 + chg], w3 = cw[3 * 4096 + chg], bb = cbias[chg];
.LBB0_559:
	s_and_b32 s8, s26, 0xfc0
	v_or_b32_e32 v234, s8, v25
	v_lshlrev_b32_e32 v236, 2, v234
	v_mov_b32_e32 v237, v48
	v_lshl_add_u64 v[238:239], s[68:69], 0, v[236:237]
	global_load_dword v242, v236, s[68:69]
	global_load_dword v246, v236, s[70:71]
	v_add_co_u32_e32 v240, vcc, 0x4000, v238
	s_nop 1
	v_addc_co_u32_e32 v241, vcc, 0, v239, vcc
	global_load_dword v243, v[240:241], off
	v_add_co_u32_e32 v240, vcc, 0x8000, v238
	s_nop 1
	v_addc_co_u32_e32 v241, vcc, 0, v239, vcc
	global_load_dword v244, v[240:241], off
	v_add_co_u32_e32 v240, vcc, 0xc000, v238
	s_nop 1
	v_addc_co_u32_e32 v241, vcc, 0, v239, vcc
	global_load_dword v245, v[240:241], off
	v_readlane_b32 s0, v252, 61
	s_add_i32 s28, s29, s0
	s_cmpk_lt_i32 s28, 0x2000
	s_cselect_b64 s[6:7], -1, 0
	s_cmpk_gt_i32 s28, 0x1fff
	s_cselect_b64 s[0:1], -1, 0
	s_and_b64 vcc, exec, s[0:1]
	s_cbranch_vccnz .Lmy_cv_skip1
	v_readlane_b32 s4, v254, 10
	s_add_i32 s4, s4, s26
	s_and_b32 s4, s4, 0xfc0
	s_lshl_b32 s8, s4, 1
	v_readlane_b32 s4, v254, 9
	s_add_i32 s4, s4, s27
	s_and_b32 s4, s4, 0xffffff80
	v_mov_b32_e32 v49, v48
	s_waitcnt vmcnt(5)
	v_add_u32_e32 v10, s4, v31
	v_mov_b32_e32 v50, v48
	v_mov_b32_e32 v51, v48
	v_mov_b64_e32 v[0:1], v[48:49]
	v_lshl_add_u64 v[8:9], v[28:29], 0, s[8:9]
	v_cmp_lt_i32_e32 vcc, 2, v10
	v_mov_b64_e32 v[2:3], v[50:51]
	s_and_saveexec_b64 s[10:11], vcc
	v_add_u32_e32 v0, -3, v10
	v_mov_b32_e32 v1, v48
	v_lshlrev_b64 v[0:1], 13, v[0:1]
	v_lshl_add_u64 v[0:1], v[8:9], 0, v[0:1]
	global_load_dwordx4 v[0:3], v[0:1], off
.LBB0_562:
	s_or_b64 exec, exec, s[10:11]
	v_ashrrev_i32_e32 v11, 31, v10
	v_lshlrev_b64 v[10:11], 13, v[10:11]
	v_lshl_add_u64 v[36:37], v[8:9], 0, v[10:11]
	v_add_co_u32_e32 v8, vcc, 0x7a000, v36
	s_nop 1
	v_addc_co_u32_e32 v9, vcc, 0, v37, vcc
	global_load_dwordx4 v[8:11], v[8:9], off
	s_and_saveexec_b64 s[10:11], s[38:39]
	v_add_co_u32_e32 v4, vcc, 0xfa000, v36
	s_nop 1
	v_addc_co_u32_e32 v5, vcc, 0, v37, vcc
	global_load_dwordx4 v[4:7], v[4:5], off
.LBB0_564:
	s_or_b64 exec, exec, s[10:11]
	s_branch .LBB0_565

; DI_ float silu_f(float v) { return v / (1.f + __expf(-v)); }
; DI_ void ssm_conv_tile(int tile, const unsigned char* buf, unsigned char* obuf, const float* cw, const float* cbias, bf16_t* xsT, bf16_t* Btok, bf16_t* BT, bf16_t* Ctok, int tid) {
;     ...
;     const float w0 = cw[chg], w1 = cw[4096 + chg], w2 = cw[2 * 4096 + chg], w3 = cw[3 * 4096 + chg], bb = cbias[chg];
;     const bf16_t* col = (const bf16_t*)buf + ch;
;     float x0 = __uint_as_float((unsigned)col[(tl0 + 0) * 64] << 16), x1 = __uint_as_float((unsigned)col[(tl0 + 1) * 64] << 16), x2 = __uint_as_float((unsigned)col[(tl0 + 2) * 64] << 16);
;     float y[16];
; #pragma unroll
;     for (int i = 0; i < 16; ++i) { const float x3 = __uint_as_float((unsigned)col[(tl0 + 3 + i) * 64] << 16); const float v = bb + w0 * x0 + w1 * x1 + w2 * x2 + w3 * x3; y[i] = silu_f(v); x0 = x1; x1 = x2; x2 = x3; }
.LBB0_565:
	s_and_b32 s8, s26, 0xfc0
	s_nop 0
	s_cmpk_lt_u32 s8, 0xc00
	s_nop 0
	s_nop 0
	ds_read_u16 v37, v39 offset:1792
	ds_read_u16 v49, v39 offset:2048
	ds_read_u16 v47, v43
	s_cselect_b64 s[10:11], -1, 0
	s_cmpk_gt_u32 s8, 0xbff
	s_waitcnt lgkmcnt(2)
	v_lshlrev_b32_e32 v46, 16, v37
	s_waitcnt lgkmcnt(1)
	v_lshlrev_b32_e32 v51, 16, v49
	ds_read_u16 v37, v39 offset:2176
	ds_read_u16 v49, v39 offset:2304
	s_waitcnt lgkmcnt(2)
	v_lshlrev_b32_e32 v47, 16, v47
	v_mov_b32_e32 v50, v47
	v_mov_b32_e32 v54, v51
	s_waitcnt lgkmcnt(1)
	v_lshlrev_b32_e32 v55, 16, v37
	s_waitcnt lgkmcnt(0)
	v_lshlrev_b32_e32 v53, 16, v49
	ds_read_u16 v37, v39 offset:1536
	ds_read_u16 v49, v39 offset:1664
	s_waitcnt lgkmcnt(1)
	v_lshlrev_b32_e32 v58, 16, v37
	s_waitcnt lgkmcnt(0)
	v_lshlrev_b32_e32 v59, 16, v49
	s_waitcnt vmcnt(3)
	v_mov_b32_e32 v36, v242
	v_mov_b32_e32 v38, v243
	v_mov_b32_e32 v40, v244
	v_mov_b32_e32 v42, v245
	v_mov_b32_e32 v44, v246
	v_pk_fma_f32 v[56:57], v[36:37], v[58:59], v[44:45] op_sel_hi:[0,1,0]
	ds_read_u16 v37, v39 offset:1280
	ds_read_u16 v49, v39 offset:1408
	s_waitcnt lgkmcnt(1)
	v_lshlrev_b32_e32 v62, 16, v37
	s_waitcnt lgkmcnt(0)
	v_lshlrev_b32_e32 v63, 16, v49
	v_pk_fma_f32 v[60:61], v[36:37], v[62:63], v[44:45] op_sel_hi:[0,1,0]
	ds_read_u16 v37, v39 offset:1024
	ds_read_u16 v49, v39 offset:1152
	s_waitcnt lgkmcnt(1)
	v_lshlrev_b32_e32 v66, 16, v37
	s_waitcnt lgkmcnt(0)
	v_lshlrev_b32_e32 v67, 16, v49
	v_pk_fma_f32 v[64:65], v[36:37], v[66:67], v[44:45] op_sel_hi:[0,1,0]
	ds_read_u16 v37, v39 offset:768
	ds_read_u16 v49, v39 offset:896
	s_waitcnt lgkmcnt(1)
	v_lshlrev_b32_e32 v70, 16, v37
	s_waitcnt lgkmcnt(0)
	v_lshlrev_b32_e32 v71, 16, v49
	v_pk_fma_f32 v[68:69], v[36:37], v[70:71], v[44:45] op_sel_hi:[0,1,0]
	ds_read_u16 v37, v39 offset:512
	ds_read_u16 v49, v39 offset:640
	s_waitcnt lgkmcnt(1)
	v_lshlrev_b32_e32 v74, 16, v37
	s_waitcnt lgkmcnt(0)
	v_lshlrev_b32_e32 v75, 16, v49
	v_pk_fma_f32 v[72:73], v[36:37], v[74:75], v[44:45] op_sel_hi:[0,1,0]
	ds_read_u16 v37, v39 offset:256
	ds_read_u16 v49, v39 offset:384
	s_waitcnt lgkmcnt(1)
	v_lshlrev_b32_e32 v88, 16, v37
	s_waitcnt lgkmcnt(0)
	v_lshlrev_b32_e32 v89, 16, v49
	v_pk_fma_f32 v[76:77], v[36:37], v[88:89], v[44:45] op_sel_hi:[0,1,0]
	ds_read_u16 v37, v39
	ds_read_u16 v49, v39 offset:128
	v_pk_mov_b32 v[94:95], v[88:89], v[74:75] op_sel:[1,0]
	s_waitcnt lgkmcnt(1)
	v_lshlrev_b32_e32 v90, 16, v37
	s_waitcnt lgkmcnt(0)
; DI_ unsigned pk2(float lo, float hi) { typedef float f2 __attribute__((ext_vector_type(2))); typedef __bf16 b2 __attribute__((ext_vector_type(2))); f2 v = {lo, hi}; b2 b = __builtin_convertvector(v, b2); return __builtin_bit_cast(unsigned, b); }
; DI_ float silu_f(float v) { return v / (1.f + __expf(-v)); }
; DI_ void ssm_conv_tile(int tile, const unsigned char* buf, unsigned char* obuf, const float* cw, const float* cbias, bf16_t* xsT, bf16_t* Btok, bf16_t* BT, bf16_t* Ctok, int tid) {
;     ...
;     for (int i = 0; i < 16; ++i) { const float x3 = __uint_as_float((unsigned)col[(tl0 + 3 + i) * 64] << 16); const float v = bb + w0 * x0 + w1 * x1 + w2 * x2 + w3 * x3; y[i] = silu_f(v); x0 = x1; x1 = x2; x2 = x3; }
;     u32x4 o0, o1; o0.x = pk2(y[0], y[1]); o0.y = pk2(y[2], y[3]); o0.z = pk2(y[4], y[5]); o0.w = pk2(y[6], y[7]); o1.x = pk2(y[8], y[9]); o1.y = pk2(y[10], y[11]); o1.z = pk2(y[12], y[13]); o1.w = pk2(y[14], y[15]);
;     const int tg0 = tb + tl0;
;     unsigned char* obuf2 = obuf + 16384;
;     const bool chmaj = ch0 < 3072, tokmaj = ch0 >= 2048;
;     if (chmaj) { *(u32x4*)(obuf2 + ch * 272 + tl0 * 2) = o0; *(u32x4*)(obuf2 + ch * 272 + tl0 * 2 + 16) = o1; }
	v_lshlrev_b32_e32 v91, 16, v49
	v_pk_fma_f32 v[92:93], v[36:37], v[90:91], v[44:45] op_sel_hi:[0,1,0]
	v_pk_mov_b32 v[90:91], v[90:91], v[88:89] op_sel:[1,0]
	v_pk_fma_f32 v[76:77], v[38:39], v[94:95], v[76:77] op_sel_hi:[0,1,1]
	v_pk_fma_f32 v[90:91], v[38:39], v[90:91], v[92:93] op_sel_hi:[0,1,1]
	v_pk_fma_f32 v[88:89], v[40:41], v[88:89], v[90:91] op_sel_hi:[0,1,1]
	v_pk_fma_f32 v[88:89], v[42:43], v[94:95], v[88:89] op_sel_hi:[0,1,1]
	v_mul_f32_e32 v37, 0xbfb8aa3b, v88
	v_exp_f32_e32 v90, v37
	v_mul_f32_e32 v37, 0xbfb8aa3b, v89
	v_exp_f32_e32 v91, v37
	s_nop 0
	v_pk_add_f32 v[90:91], v[90:91], 1.0 op_sel_hi:[1,0]
	s_nop 0
	v_rcp_f32_e32 v49, v91
	s_nop 0
	v_mul_f32_e32 v87, v89, v49
	v_mov_b32_e32 v37, v87
	v_rcp_f32_e32 v52, v90
	v_mov_b32_e32 v37, v37
	v_mul_f32_e32 v49, v88, v52
	v_pk_mov_b32 v[88:89], v[74:75], v[70:71] op_sel:[1,0]
	v_pk_fma_f32 v[74:75], v[40:41], v[74:75], v[76:77] op_sel_hi:[0,1,1]
	v_pk_fma_f32 v[76:77], v[42:43], v[88:89], v[74:75] op_sel_hi:[0,1,1]
	v_mul_f32_e32 v52, 0xbfb8aa3b, v76
	v_exp_f32_e32 v74, v52
	v_mul_f32_e32 v52, 0xbfb8aa3b, v77
	v_exp_f32_e32 v75, v52
	v_pk_fma_f32 v[72:73], v[38:39], v[88:89], v[72:73] op_sel_hi:[0,1,1]
	v_pk_add_f32 v[90:91], v[74:75], 1.0 op_sel_hi:[1,0]
	s_nop 0
	v_rcp_f32_e32 v74, v91
	s_nop 0
	v_mul_f32_e32 v74, v77, v74
	v_rcp_f32_e32 v75, v90
	s_nop 0
	v_mul_f32_e32 v75, v76, v75
	v_pk_mov_b32 v[76:77], v[70:71], v[66:67] op_sel:[1,0]
	v_pk_fma_f32 v[70:71], v[40:41], v[70:71], v[72:73] op_sel_hi:[0,1,1]
	v_pk_fma_f32 v[72:73], v[42:43], v[76:77], v[70:71] op_sel_hi:[0,1,1]
	v_mul_f32_e32 v52, 0xbfb8aa3b, v72
	v_exp_f32_e32 v70, v52
	v_mul_f32_e32 v52, 0xbfb8aa3b, v73
	v_exp_f32_e32 v71, v52
	v_pk_fma_f32 v[68:69], v[38:39], v[76:77], v[68:69] op_sel_hi:[0,1,1]
	v_pk_add_f32 v[88:89], v[70:71], 1.0 op_sel_hi:[1,0]
	s_nop 0
	v_rcp_f32_e32 v70, v89
	s_nop 0
	v_mul_f32_e32 v70, v73, v70
	v_rcp_f32_e32 v71, v88
	s_nop 0
	v_mul_f32_e32 v71, v72, v71
	v_pk_mov_b32 v[72:73], v[66:67], v[62:63] op_sel:[1,0]
	v_pk_fma_f32 v[66:67], v[40:41], v[66:67], v[68:69] op_sel_hi:[0,1,1]
	v_pk_fma_f32 v[68:69], v[42:43], v[72:73], v[66:67] op_sel_hi:[0,1,1]
	v_mul_f32_e32 v52, 0xbfb8aa3b, v68
	v_exp_f32_e32 v66, v52
	v_mul_f32_e32 v52, 0xbfb8aa3b, v69
	v_exp_f32_e32 v67, v52
	v_pk_fma_f32 v[64:65], v[38:39], v[72:73], v[64:65] op_sel_hi:[0,1,1]
	v_pk_add_f32 v[76:77], v[66:67], 1.0 op_sel_hi:[1,0]
	s_nop 0
	v_rcp_f32_e32 v66, v77
	s_nop 0
	v_mul_f32_e32 v66, v69, v66
	v_rcp_f32_e32 v67, v76
	s_nop 0
	v_mul_f32_e32 v67, v68, v67
	v_pk_mov_b32 v[68:69], v[62:63], v[58:59] op_sel:[1,0]
	v_pk_fma_f32 v[62:63], v[40:41], v[62:63], v[64:65] op_sel_hi:[0,1,1]
	v_pk_fma_f32 v[64:65], v[42:43], v[68:69], v[62:63] op_sel_hi:[0,1,1]
	v_mul_f32_e32 v52, 0xbfb8aa3b, v64
	v_exp_f32_e32 v62, v52
	v_mul_f32_e32 v52, 0xbfb8aa3b, v65
	v_exp_f32_e32 v63, v52
	v_pk_fma_f32 v[60:61], v[38:39], v[68:69], v[60:61] op_sel_hi:[0,1,1]
	v_pk_add_f32 v[72:73], v[62:63], 1.0 op_sel_hi:[1,0]
	s_nop 0
	v_rcp_f32_e32 v62, v73
	s_nop 0
	v_mul_f32_e32 v62, v65, v62
	v_rcp_f32_e32 v63, v72
	s_nop 0
	v_mul_f32_e32 v63, v64, v63
	v_pk_mov_b32 v[64:65], v[58:59], v[46:47] op_sel:[1,0]
	v_pk_fma_f32 v[58:59], v[40:41], v[58:59], v[60:61] op_sel_hi:[0,1,1]
	v_pk_fma_f32 v[60:61], v[42:43], v[64:65], v[58:59] op_sel_hi:[0,1,1]
	v_mul_f32_e32 v52, 0xbfb8aa3b, v60
	v_exp_f32_e32 v58, v52
	v_mul_f32_e32 v52, 0xbfb8aa3b, v61
	v_exp_f32_e32 v59, v52
	v_pk_fma_f32 v[56:57], v[38:39], v[64:65], v[56:57] op_sel_hi:[0,1,1]
	v_pk_fma_f32 v[56:57], v[40:41], v[46:47], v[56:57] op_sel_hi:[0,1,1]
	v_pk_fma_f32 v[46:47], v[36:37], v[46:47], v[44:45] op_sel_hi:[0,1,0]
	v_pk_add_f32 v[68:69], v[58:59], 1.0 op_sel_hi:[1,0]
	v_pk_fma_f32 v[46:47], v[38:39], v[50:51], v[46:47] op_sel_hi:[0,1,1]
	v_rcp_f32_e32 v58, v69
	v_pk_fma_f32 v[46:47], v[40:41], v[54:55], v[46:47] op_sel_hi:[0,1,1]
	v_mul_f32_e32 v58, v61, v58
	v_rcp_f32_e32 v59, v68
	s_nop 0
	v_mul_f32_e32 v59, v60, v59
	v_pk_fma_f32 v[60:61], v[42:43], v[50:51], v[56:57] op_sel_hi:[0,1,1]
	v_mul_f32_e32 v52, 0xbfb8aa3b, v60
	v_exp_f32_e32 v56, v52
	v_mul_f32_e32 v52, 0xbfb8aa3b, v61
	v_exp_f32_e32 v57, v52
	s_nop 0
	v_pk_add_f32 v[64:65], v[56:57], 1.0 op_sel_hi:[1,0]
	s_nop 0
	v_rcp_f32_e32 v56, v65
	s_nop 0
	v_mul_f32_e32 v56, v61, v56
	v_rcp_f32_e32 v57, v64
	s_nop 0
	v_mul_f32_e32 v57, v60, v57
	v_mov_b32_e32 v52, v55
	v_pk_fma_f32 v[46:47], v[42:43], v[52:53], v[46:47] op_sel_hi:[0,1,1]
	v_mul_f32_e32 v36, 0xbfb8aa3b, v46
	v_exp_f32_e32 v50, v36
	v_mul_f32_e32 v36, 0xbfb8aa3b, v47
	v_exp_f32_e32 v51, v36
	s_nop 0
	v_pk_add_f32 v[50:51], v[50:51], 1.0 op_sel_hi:[1,0]
	s_nop 0
	v_rcp_f32_e32 v38, v51
	s_nop 0
	v_mul_f32_e32 v42, v47, v38
	v_mov_b32_e32 v36, v42
	v_rcp_f32_e32 v40, v50
	v_mov_b32_e32 v36, v36
	v_mul_f32_e32 v38, v46, v40
	s_cbranch_scc1 .LBB0_567
	v_cvt_pk_bf16_f32 v50, v49, v37
	v_cvt_pk_bf16_f32 v51, v75, v74
	v_cvt_pk_bf16_f32 v52, v71, v70
	v_cvt_pk_bf16_f32 v53, v67, v66
	v_add_u32_e32 v40, v45, v78
	v_cvt_pk_bf16_f32 v88, v63, v62
	v_cvt_pk_bf16_f32 v89, v59, v58
	v_cvt_pk_bf16_f32 v90, v57, v56
	v_cvt_pk_bf16_f32 v91, v38, v36
	ds_write_b128 v40, v[50:53] offset:49920
	ds_write_b128 v40, v[88:91] offset:49936

; DI_ void ssm_conv_phase(const bf16_t* raw, const float* cw  , const float* cbias, bf16_t* xsT, bf16_t* Btok, bf16_t* BT, bf16_t* Ctok, unsigned char* lds, int tid) {
;     ...
;         __syncthreads();
;         if (tile + G >= NTILE) break;
;         SC_LOAD(b0, b1, b2, tile + 3 * G);
.LBB0_581:
	s_cmpk_gt_i32 s4, 0x1fff
	s_mov_b64 s[10:11], -1
	s_waitcnt lgkmcnt(0)
	s_barrier
	s_cbranch_scc1 .LBB0_558
	v_readlane_b32 s4, v254, 11
	s_add_i32 s4, s4, s26
	s_and_b32 s8, s4, 0xfc0
	v_or_b32_e32 v234, s8, v25
	v_lshlrev_b32_e32 v236, 2, v234
	v_mov_b32_e32 v237, v48
	v_lshl_add_u64 v[238:239], s[68:69], 0, v[236:237]
	global_load_dword v242, v236, s[68:69]
	global_load_dword v246, v236, s[70:71]
	v_add_co_u32_e32 v240, vcc, 0x4000, v238
	s_nop 1
	v_addc_co_u32_e32 v241, vcc, 0, v239, vcc
	global_load_dword v243, v[240:241], off
	v_add_co_u32_e32 v240, vcc, 0x8000, v238
	s_nop 1
	v_addc_co_u32_e32 v241, vcc, 0, v239, vcc
	global_load_dword v244, v[240:241], off
	v_add_co_u32_e32 v240, vcc, 0xc000, v238
	s_nop 1
	v_addc_co_u32_e32 v241, vcc, 0, v239, vcc
	global_load_dword v245, v[240:241], off
	s_mul_i32 s4, s92, 3
	s_add_i32 s4, s4, s29
	s_cmpk_gt_i32 s4, 0x1fff
	s_cbranch_scc1 .Lmy_cv_skip2
	s_mul_i32 s4, s92, 0xc0
	s_add_i32 s4, s4, s26
	s_and_b32 s4, s4, 0xfc0
	s_lshl_b32 s8, s4, 1
	s_mul_i32 s4, s92, 6
	s_add_i32 s4, s4, s27
	s_and_b32 s4, s4, 0xffffff80
	v_mov_b32_e32 v49, v48
	v_add_u32_e32 v22, s4, v31
	v_mov_b32_e32 v50, v48
	v_mov_b32_e32 v51, v48
	v_mov_b64_e32 v[12:13], v[48:49]
	v_lshl_add_u64 v[20:21], v[28:29], 0, s[8:9]
	v_cmp_lt_i32_e32 vcc, 2, v22
	v_mov_b64_e32 v[14:15], v[50:51]
	s_and_saveexec_b64 s[10:11], vcc
	v_add_u32_e32 v12, -3, v22
	v_mov_b32_e32 v13, v48
	v_lshlrev_b64 v[12:13], 13, v[12:13]
	v_lshl_add_u64 v[12:13], v[20:21], 0, v[12:13]
	global_load_dwordx4 v[12:15], v[12:13], off
.LBB0_585:
	s_or_b64 exec, exec, s[10:11]
	v_ashrrev_i32_e32 v23, 31, v22
	v_lshlrev_b64 v[22:23], 13, v[22:23]
	v_lshl_add_u64 v[36:37], v[20:21], 0, v[22:23]
	v_add_co_u32_e32 v20, vcc, 0x7a000, v36
	s_nop 1
	v_addc_co_u32_e32 v21, vcc, 0, v37, vcc
	global_load_dwordx4 v[20:23], v[20:21], off
	s_and_saveexec_b64 s[10:11], s[38:39]
	v_add_co_u32_e32 v16, vcc, 0xfa000, v36
	s_nop 1
	v_addc_co_u32_e32 v17, vcc, 0, v37, vcc
	global_load_dwordx4 v[16:19], v[16:17], off

; DI_ float silu_f(float v) { return v / (1.f + __expf(-v)); }
; DI_ void ssm_conv_tile(int tile, const unsigned char* buf, unsigned char* obuf, const float* cw, const float* cbias, bf16_t* xsT, bf16_t* Btok, bf16_t* BT, bf16_t* Ctok, int tid) {
;     ...
;     const float w0 = cw[chg], w1 = cw[4096 + chg], w2 = cw[2 * 4096 + chg], w3 = cw[3 * 4096 + chg], bb = cbias[chg];
;     const bf16_t* col = (const bf16_t*)buf + ch;
;     float x0 = __uint_as_float((unsigned)col[(tl0 + 0) * 64] << 16), x1 = __uint_as_float((unsigned)col[(tl0 + 1) * 64] << 16), x2 = __uint_as_float((unsigned)col[(tl0 + 2) * 64] << 16);
;     float y[16];
; #pragma unroll
;     for (int i = 0; i < 16; ++i) { const float x3 = __uint_as_float((unsigned)col[(tl0 + 3 + i) * 64] << 16); const float v = bb + w0 * x0 + w1 * x1 + w2 * x2 + w3 * x3; y[i] = silu_f(v); x0 = x1; x1 = x2; x2 = x3; }
.LBB0_588:
	v_readlane_b32 s4, v254, 11
	s_add_i32 s4, s4, s26
	s_and_b32 s8, s4, 0xfc0
	s_nop 0
	s_cmpk_lt_u32 s8, 0xc00
	s_nop 0
	s_nop 0
	ds_read_u16 v37, v39 offset:18560
	ds_read_u16 v46, v43 offset:16768
	s_cselect_b64 s[10:11], -1, 0
	s_cmpk_gt_u32 s8, 0xbff
	s_waitcnt lgkmcnt(0)
	v_lshlrev_b32_e32 v47, 16, v46
	v_lshlrev_b32_e32 v46, 16, v37
	ds_read_u16 v37, v39 offset:18816
	v_mov_b32_e32 v50, v47
	s_waitcnt lgkmcnt(0)
	v_lshlrev_b32_e32 v51, 16, v37
	ds_read_u16 v37, v39 offset:18944
	ds_read_u16 v49, v39 offset:19072
	v_mov_b32_e32 v54, v51
	s_waitcnt lgkmcnt(1)
	v_lshlrev_b32_e32 v55, 16, v37
	s_waitcnt lgkmcnt(0)
	v_lshlrev_b32_e32 v53, 16, v49
	ds_read_u16 v37, v39 offset:18304
	ds_read_u16 v49, v39 offset:18432
	s_waitcnt lgkmcnt(1)
	v_lshlrev_b32_e32 v58, 16, v37
	s_waitcnt lgkmcnt(0)
	v_lshlrev_b32_e32 v59, 16, v49
	s_waitcnt vmcnt(3)
	v_mov_b32_e32 v36, v242
	v_mov_b32_e32 v38, v243
	v_mov_b32_e32 v40, v244
	v_mov_b32_e32 v42, v245
	v_mov_b32_e32 v44, v246
	v_pk_fma_f32 v[56:57], v[36:37], v[58:59], v[44:45] op_sel_hi:[0,1,0]
	ds_read_u16 v37, v39 offset:18048
	ds_read_u16 v49, v39 offset:18176
	s_waitcnt lgkmcnt(1)
	v_lshlrev_b32_e32 v62, 16, v37
	s_waitcnt lgkmcnt(0)
	v_lshlrev_b32_e32 v63, 16, v49
	v_pk_fma_f32 v[60:61], v[36:37], v[62:63], v[44:45] op_sel_hi:[0,1,0]
	ds_read_u16 v37, v39 offset:17792
	ds_read_u16 v49, v39 offset:17920
	s_waitcnt lgkmcnt(1)
	v_lshlrev_b32_e32 v66, 16, v37
	s_waitcnt lgkmcnt(0)
	v_lshlrev_b32_e32 v67, 16, v49
	v_pk_fma_f32 v[64:65], v[36:37], v[66:67], v[44:45] op_sel_hi:[0,1,0]
	ds_read_u16 v37, v39 offset:17536
	ds_read_u16 v49, v39 offset:17664
	s_waitcnt lgkmcnt(1)
	v_lshlrev_b32_e32 v70, 16, v37
	s_waitcnt lgkmcnt(0)
	v_lshlrev_b32_e32 v71, 16, v49
	v_pk_fma_f32 v[68:69], v[36:37], v[70:71], v[44:45] op_sel_hi:[0,1,0]
	ds_read_u16 v37, v39 offset:17280
	ds_read_u16 v49, v39 offset:17408
	s_waitcnt lgkmcnt(1)
	v_lshlrev_b32_e32 v74, 16, v37
	s_waitcnt lgkmcnt(0)
	v_lshlrev_b32_e32 v75, 16, v49
	v_pk_fma_f32 v[72:73], v[36:37], v[74:75], v[44:45] op_sel_hi:[0,1,0]
	ds_read_u16 v37, v39 offset:17024
	ds_read_u16 v49, v39 offset:17152
	s_waitcnt lgkmcnt(1)
	v_lshlrev_b32_e32 v88, 16, v37
	s_waitcnt lgkmcnt(0)
	v_lshlrev_b32_e32 v89, 16, v49
	v_pk_fma_f32 v[76:77], v[36:37], v[88:89], v[44:45] op_sel_hi:[0,1,0]
	ds_read_u16 v37, v39 offset:16768
	ds_read_u16 v49, v39 offset:16896
	v_pk_mov_b32 v[94:95], v[88:89], v[74:75] op_sel:[1,0]
	s_waitcnt lgkmcnt(1)
	v_lshlrev_b32_e32 v90, 16, v37
	s_waitcnt lgkmcnt(0)
; DI_ unsigned pk2(float lo, float hi) { typedef float f2 __attribute__((ext_vector_type(2))); typedef __bf16 b2 __attribute__((ext_vector_type(2))); f2 v = {lo, hi}; b2 b = __builtin_convertvector(v, b2); return __builtin_bit_cast(unsigned, b); }
; DI_ float silu_f(float v) { return v / (1.f + __expf(-v)); }
; DI_ void ssm_conv_tile(int tile, const unsigned char* buf, unsigned char* obuf, const float* cw, const float* cbias, bf16_t* xsT, bf16_t* Btok, bf16_t* BT, bf16_t* Ctok, int tid) {
;     ...
;     for (int i = 0; i < 16; ++i) { const float x3 = __uint_as_float((unsigned)col[(tl0 + 3 + i) * 64] << 16); const float v = bb + w0 * x0 + w1 * x1 + w2 * x2 + w3 * x3; y[i] = silu_f(v); x0 = x1; x1 = x2; x2 = x3; }
;     u32x4 o0, o1; o0.x = pk2(y[0], y[1]); o0.y = pk2(y[2], y[3]); o0.z = pk2(y[4], y[5]); o0.w = pk2(y[6], y[7]); o1.x = pk2(y[8], y[9]); o1.y = pk2(y[10], y[11]); o1.z = pk2(y[12], y[13]); o1.w = pk2(y[14], y[15]);
;     const int tg0 = tb + tl0;
;     unsigned char* obuf2 = obuf + 16384;
;     const bool chmaj = ch0 < 3072, tokmaj = ch0 >= 2048;
;     if (chmaj) { *(u32x4*)(obuf2 + ch * 272 + tl0 * 2) = o0; *(u32x4*)(obuf2 + ch * 272 + tl0 * 2 + 16) = o1; }
	v_lshlrev_b32_e32 v91, 16, v49
	v_pk_fma_f32 v[92:93], v[36:37], v[90:91], v[44:45] op_sel_hi:[0,1,0]
	v_pk_mov_b32 v[90:91], v[90:91], v[88:89] op_sel:[1,0]
	v_pk_fma_f32 v[76:77], v[38:39], v[94:95], v[76:77] op_sel_hi:[0,1,1]
	v_pk_fma_f32 v[90:91], v[38:39], v[90:91], v[92:93] op_sel_hi:[0,1,1]
	v_pk_fma_f32 v[88:89], v[40:41], v[88:89], v[90:91] op_sel_hi:[0,1,1]
	v_pk_fma_f32 v[88:89], v[42:43], v[94:95], v[88:89] op_sel_hi:[0,1,1]
	v_mul_f32_e32 v37, 0xbfb8aa3b, v88
	v_exp_f32_e32 v90, v37
	v_mul_f32_e32 v37, 0xbfb8aa3b, v89
	v_exp_f32_e32 v91, v37
	s_nop 0
	v_pk_add_f32 v[90:91], v[90:91], 1.0 op_sel_hi:[1,0]
	s_nop 0
	v_rcp_f32_e32 v49, v91
	s_nop 0
	v_mul_f32_e32 v87, v89, v49
	v_mov_b32_e32 v37, v87
	v_rcp_f32_e32 v52, v90
	v_mov_b32_e32 v37, v37
	v_mul_f32_e32 v49, v88, v52
	v_pk_mov_b32 v[88:89], v[74:75], v[70:71] op_sel:[1,0]
	v_pk_fma_f32 v[74:75], v[40:41], v[74:75], v[76:77] op_sel_hi:[0,1,1]
	v_pk_fma_f32 v[76:77], v[42:43], v[88:89], v[74:75] op_sel_hi:[0,1,1]
	v_mul_f32_e32 v52, 0xbfb8aa3b, v76
	v_exp_f32_e32 v74, v52
	v_mul_f32_e32 v52, 0xbfb8aa3b, v77
	v_exp_f32_e32 v75, v52
	v_pk_fma_f32 v[72:73], v[38:39], v[88:89], v[72:73] op_sel_hi:[0,1,1]
	v_pk_add_f32 v[90:91], v[74:75], 1.0 op_sel_hi:[1,0]
	s_nop 0
	v_rcp_f32_e32 v74, v91
	s_nop 0
	v_mul_f32_e32 v74, v77, v74
	v_rcp_f32_e32 v75, v90
	s_nop 0
	v_mul_f32_e32 v75, v76, v75
	v_pk_mov_b32 v[76:77], v[70:71], v[66:67] op_sel:[1,0]
	v_pk_fma_f32 v[70:71], v[40:41], v[70:71], v[72:73] op_sel_hi:[0,1,1]
	v_pk_fma_f32 v[72:73], v[42:43], v[76:77], v[70:71] op_sel_hi:[0,1,1]
	v_mul_f32_e32 v52, 0xbfb8aa3b, v72
	v_exp_f32_e32 v70, v52
	v_mul_f32_e32 v52, 0xbfb8aa3b, v73
	v_exp_f32_e32 v71, v52
	v_pk_fma_f32 v[68:69], v[38:39], v[76:77], v[68:69] op_sel_hi:[0,1,1]
	v_pk_add_f32 v[88:89], v[70:71], 1.0 op_sel_hi:[1,0]
	s_nop 0
	v_rcp_f32_e32 v70, v89
	s_nop 0
	v_mul_f32_e32 v70, v73, v70
	v_rcp_f32_e32 v71, v88
	s_nop 0
	v_mul_f32_e32 v71, v72, v71
	v_pk_mov_b32 v[72:73], v[66:67], v[62:63] op_sel:[1,0]
	v_pk_fma_f32 v[66:67], v[40:41], v[66:67], v[68:69] op_sel_hi:[0,1,1]
	v_pk_fma_f32 v[68:69], v[42:43], v[72:73], v[66:67] op_sel_hi:[0,1,1]
	v_mul_f32_e32 v52, 0xbfb8aa3b, v68
	v_exp_f32_e32 v66, v52
	v_mul_f32_e32 v52, 0xbfb8aa3b, v69
	v_exp_f32_e32 v67, v52
	v_pk_fma_f32 v[64:65], v[38:39], v[72:73], v[64:65] op_sel_hi:[0,1,1]
	v_pk_add_f32 v[76:77], v[66:67], 1.0 op_sel_hi:[1,0]
	s_nop 0
	v_rcp_f32_e32 v66, v77
	s_nop 0
	v_mul_f32_e32 v66, v69, v66
	v_rcp_f32_e32 v67, v76
	s_nop 0
	v_mul_f32_e32 v67, v68, v67
	v_pk_mov_b32 v[68:69], v[62:63], v[58:59] op_sel:[1,0]
	v_pk_fma_f32 v[62:63], v[40:41], v[62:63], v[64:65] op_sel_hi:[0,1,1]
	v_pk_fma_f32 v[64:65], v[42:43], v[68:69], v[62:63] op_sel_hi:[0,1,1]
	v_mul_f32_e32 v52, 0xbfb8aa3b, v64
	v_exp_f32_e32 v62, v52
	v_mul_f32_e32 v52, 0xbfb8aa3b, v65
	v_exp_f32_e32 v63, v52
	v_pk_fma_f32 v[60:61], v[38:39], v[68:69], v[60:61] op_sel_hi:[0,1,1]
	v_pk_add_f32 v[72:73], v[62:63], 1.0 op_sel_hi:[1,0]
	s_nop 0
	v_rcp_f32_e32 v62, v73
	s_nop 0
	v_mul_f32_e32 v62, v65, v62
	v_rcp_f32_e32 v63, v72
	s_nop 0
	v_mul_f32_e32 v63, v64, v63
	v_pk_mov_b32 v[64:65], v[58:59], v[46:47] op_sel:[1,0]
	v_pk_fma_f32 v[58:59], v[40:41], v[58:59], v[60:61] op_sel_hi:[0,1,1]
	v_pk_fma_f32 v[60:61], v[42:43], v[64:65], v[58:59] op_sel_hi:[0,1,1]
	v_mul_f32_e32 v52, 0xbfb8aa3b, v60
	v_exp_f32_e32 v58, v52
	v_mul_f32_e32 v52, 0xbfb8aa3b, v61
	v_exp_f32_e32 v59, v52
	v_pk_fma_f32 v[56:57], v[38:39], v[64:65], v[56:57] op_sel_hi:[0,1,1]
	v_pk_fma_f32 v[56:57], v[40:41], v[46:47], v[56:57] op_sel_hi:[0,1,1]
	v_pk_fma_f32 v[46:47], v[36:37], v[46:47], v[44:45] op_sel_hi:[0,1,0]
	v_pk_add_f32 v[68:69], v[58:59], 1.0 op_sel_hi:[1,0]
	v_pk_fma_f32 v[46:47], v[38:39], v[50:51], v[46:47] op_sel_hi:[0,1,1]
	v_rcp_f32_e32 v58, v69
	v_pk_fma_f32 v[46:47], v[40:41], v[54:55], v[46:47] op_sel_hi:[0,1,1]
	v_mul_f32_e32 v58, v61, v58
	v_rcp_f32_e32 v59, v68
	s_nop 0
	v_mul_f32_e32 v59, v60, v59
	v_pk_fma_f32 v[60:61], v[42:43], v[50:51], v[56:57] op_sel_hi:[0,1,1]
	v_mul_f32_e32 v52, 0xbfb8aa3b, v60
	v_exp_f32_e32 v56, v52
	v_mul_f32_e32 v52, 0xbfb8aa3b, v61
	v_exp_f32_e32 v57, v52
	s_nop 0
	v_pk_add_f32 v[64:65], v[56:57], 1.0 op_sel_hi:[1,0]
	s_nop 0
	v_rcp_f32_e32 v56, v65
	s_nop 0
	v_mul_f32_e32 v56, v61, v56
	v_rcp_f32_e32 v57, v64
	s_nop 0
	v_mul_f32_e32 v57, v60, v57
	v_mov_b32_e32 v52, v55
	v_pk_fma_f32 v[46:47], v[42:43], v[52:53], v[46:47] op_sel_hi:[0,1,1]
	v_mul_f32_e32 v36, 0xbfb8aa3b, v46
	v_exp_f32_e32 v50, v36
	v_mul_f32_e32 v36, 0xbfb8aa3b, v47
	v_exp_f32_e32 v51, v36
	s_nop 0
	v_pk_add_f32 v[50:51], v[50:51], 1.0 op_sel_hi:[1,0]
	s_nop 0
	v_rcp_f32_e32 v38, v51
	s_nop 0
	v_mul_f32_e32 v42, v47, v38
	v_mov_b32_e32 v36, v42
	v_rcp_f32_e32 v40, v50
	v_mov_b32_e32 v36, v36
	v_mul_f32_e32 v38, v46, v40
	s_cbranch_scc1 .LBB0_590
	v_cvt_pk_bf16_f32 v50, v49, v37
	v_cvt_pk_bf16_f32 v51, v75, v74
	v_cvt_pk_bf16_f32 v52, v71, v70
	v_cvt_pk_bf16_f32 v53, v67, v66
	v_add_u32_e32 v40, v45, v78
	v_cvt_pk_bf16_f32 v88, v63, v62
	v_cvt_pk_bf16_f32 v89, v59, v58
	v_cvt_pk_bf16_f32 v90, v57, v56
	v_cvt_pk_bf16_f32 v91, v38, v36
	ds_write_b128 v40, v[50:53] offset:49920
	ds_write_b128 v40, v[88:91] offset:49936

; DI_ bf16x8 pack8(float a0, float a1, float a2, float a3, float a4, float a5, float a6, float a7) { u32x4 p; p.x = pk2(a0, a1); p.y = pk2(a2, a3); p.z = pk2(a4, a5); p.w = pk2(a6, a7); return __builtin_bit_cast(bf16x8, p); }
; #define MFMA32(a, b, c) __builtin_amdgcn_mfma_f32_32x32x16_bf16((a), (b), (c), 0, 0, 0)
; DI_ int kvmap(int rho) { return (rho & 0x13) | ((rho & 4) << 1) | ((rho & 8) >> 1); }
; DI_ void ssd_passC(const bf16_t* xsT, const bf16_t* Btok, const bf16_t* Ctok, const bf16_t* Sc, const float* dt, const float* acum, const float* Dskip, const float* norm_w, bf16_t* Z, unsigned char* lds, int tid, int lane, int wid) {
;     ...
;             for (int sb = 0; sb <= tb; ++sb) {
;                 f32x16 cb;
; #pragma unroll
;                 for (int i = 0; i < 16; ++i) cb[i] = 0.f;
;                 const unsigned char* bp = lds + PC_B + (32 * sb + kvmap(r32)) * PC_RS + hi * 16;
; #pragma unroll
;                 for (int ks = 0; ks < 8; ++ks) cb = MFMA32(*(const bf16x8*)(bp + 32 * ks), *(const bf16x8*)(cfp + 32 * ks), cb);
;                 float m[16];
; #pragma unroll
;                 for (int q4 = 0; q4 < 4; ++q4) {
;                     const int sl0 = 32 * sb + 16 * (q4 >> 1) + 8 * hi + 4 * (q4 & 1);
;                     const f32x4 as4 = *(const f32x4*)(sa + hl * 128 + sl0), ds4 = *(const f32x4*)(sd + hl * 128 + sl0);
; #pragma unroll
;                     for (int e = 0; e < 4; ++e) { const int sl = sl0 + e; float v = cb[4 * q4 + e] * __expf(fminf(at - as4[e], 0.f)) * ds4[e]; v = (sl <= tl) ? v : 0.f; if (sl == tl) v += Dh; m[4 * q4 + e] = v; }
;                 }
;                 const bf16x8 pf0 = pack8(m[0], m[1], m[2], m[3], m[4], m[5], m[6], m[7]), pf1 = pack8(m[8], m[9], m[10], m[11], m[12], m[13], m[14], m[15]);
; #pragma unroll
;                 for (int pb = 0; pb < 2; ++pb) {
;                     const unsigned char* xp = lds + PC_X + (hl * 64 + 32 * pb + r32) * PC_RS + (32 * sb + 8 * hi) * 2;
;                     yv[it][pb] = MFMA32(*(const bf16x8*)xp, pf0, yv[it][pb]); yv[it][pb] = MFMA32(*(const bf16x8*)(xp + 32), pf1, yv[it][pb]);
;                 }
.LBB0_765:
	v_add_u32_e32 v106, 0, v99
	ds_read_b128 v[32:35], v106
	ds_read_b128 v[102:105], v106 offset:32
	v_add_u32_e32 v111, 0, v100
	v_add_u32_e32 v110, s7, v137
	v_cmp_gt_u32_e32 vcc, v90, v110
	s_waitcnt lgkmcnt(1)
	v_mfma_f32_32x32x16_bf16 v[32:47], v[32:35], v[50:53], 0
	v_cmp_le_u32_e64 s[0:1], v110, v90
	v_add_u32_e32 v112, 4, v110
	s_add_i32 s7, s7, 32
	v_add_u32_e32 v100, 0x80, v100
	v_add_u32_e32 v99, 0x2200, v99
	s_cmp_lg_u32 s18, s7
	s_waitcnt lgkmcnt(0)
	v_mfma_f32_32x32x16_bf16 v[32:47], v[102:105], v[54:57], v[32:47]
	ds_read_b128 v[102:105], v106 offset:64
	s_waitcnt lgkmcnt(0)
	v_mfma_f32_32x32x16_bf16 v[32:47], v[102:105], v[58:61], v[32:47]
	ds_read_b128 v[102:105], v106 offset:96
	s_waitcnt lgkmcnt(0)
	v_mfma_f32_32x32x16_bf16 v[32:47], v[102:105], v[62:65], v[32:47]
	ds_read_b128 v[102:105], v106 offset:128
	s_waitcnt lgkmcnt(0)
	v_mfma_f32_32x32x16_bf16 v[32:47], v[102:105], v[66:69], v[32:47]
	ds_read_b128 v[102:105], v106 offset:160
	s_waitcnt lgkmcnt(0)
	v_mfma_f32_32x32x16_bf16 v[32:47], v[102:105], v[70:73], v[32:47]
	ds_read_b128 v[102:105], v106 offset:192
	s_waitcnt lgkmcnt(0)
	v_mfma_f32_32x32x16_bf16 v[32:47], v[102:105], v[74:77], v[32:47]
	ds_read_b128 v[102:105], v106 offset:224
	v_add_u32_e32 v106, 0x22800, v111
	ds_read_b128 v[106:109], v106
	s_waitcnt lgkmcnt(1)
	v_mfma_f32_32x32x16_bf16 v[32:47], v[102:105], v[78:81], v[32:47]
	v_add_u32_e32 v102, 0x22000, v111
	ds_read_b128 v[102:105], v102
	s_waitcnt lgkmcnt(0)
	v_sub_f32_e32 v102, v98, v102
	v_sub_f32_e32 v103, v98, v103
	v_min_f32_e32 v102, 0, v102
	v_min_f32_e32 v103, 0, v103
	v_mul_f32_e32 v102, 0x3fb8aa3b, v102
	v_mul_f32_e32 v103, 0x3fb8aa3b, v103
	v_exp_f32_e32 v102, v102
	v_exp_f32_e32 v103, v103
	s_nop 0
	v_mul_f32_e32 v32, v32, v102
	v_mul_f32_e32 v33, v33, v103
	v_mul_f32_e32 v32, v106, v32
	v_mul_f32_e32 v103, v107, v33
	v_add_u32_e32 v102, 1, v110
	v_cndmask_b32_e64 v33, 0, v32, s[0:1]
	v_cndmask_b32_e32 v32, 0, v103, vcc
	v_cmp_eq_u32_e32 vcc, v110, v90
	v_cmp_eq_u32_e64 s[0:1], v102, v49
	v_pk_add_f32 v[102:103], v[96:97], v[32:33]
	s_nop 0
	v_cndmask_b32_e64 v106, v32, v102, s[0:1]
	v_cndmask_b32_e32 v107, v33, v103, vcc
	v_sub_f32_e32 v32, v98, v104
	v_sub_f32_e32 v33, v98, v105
	v_min_f32_e32 v32, 0, v32
	v_min_f32_e32 v33, 0, v33
	v_mul_f32_e32 v32, 0x3fb8aa3b, v32
	v_mul_f32_e32 v33, 0x3fb8aa3b, v33
	v_exp_f32_e32 v32, v32
	v_exp_f32_e32 v33, v33
	v_or_b32_e32 v102, 3, v110
	v_or_b32_e32 v103, 2, v110
	v_cmp_le_u32_e32 vcc, v102, v49
	v_pk_mul_f32 v[32:33], v[34:35], v[32:33]
	v_cmp_eq_u32_e64 s[0:1], v102, v49
	v_pk_mul_f32 v[32:33], v[108:109], v[32:33]
	v_add_u32_e32 v102, 0x22810, v111
	v_cndmask_b32_e32 v33, 0, v33, vcc
	v_cmp_le_u32_e32 vcc, v103, v90
	s_nop 1
	v_cndmask_b32_e32 v32, 0, v32, vcc
	v_cmp_eq_u32_e32 vcc, v103, v90
	v_pk_add_f32 v[34:35], v[96:97], v[32:33]
	ds_read_b128 v[102:105], v102
	v_cndmask_b32_e32 v109, v32, v34, vcc
	v_add_u32_e32 v32, 0x22010, v111
	v_cndmask_b32_e64 v108, v33, v35, s[0:1]
	ds_read_b128 v[32:35], v32
	v_cmp_gt_u32_e32 vcc, v90, v112
	v_cmp_le_u32_e64 s[0:1], v112, v90
	s_waitcnt lgkmcnt(0)
	v_sub_f32_e32 v32, v98, v32
	v_sub_f32_e32 v33, v98, v33
	v_min_f32_e32 v32, 0, v32
	v_min_f32_e32 v33, 0, v33
	v_mul_f32_e32 v32, 0x3fb8aa3b, v32
	v_mul_f32_e32 v33, 0x3fb8aa3b, v33
	v_exp_f32_e32 v32, v32
	v_exp_f32_e32 v33, v33
	v_mul_f32_e32 v32, v36, v32
	v_mul_f32_e32 v33, v37, v33
	v_mul_f32_e32 v32, v102, v32
	v_mul_f32_e32 v37, v103, v33
	v_add_u32_e32 v36, 5, v110
	v_cndmask_b32_e64 v33, 0, v32, s[0:1]
	v_cndmask_b32_e32 v32, 0, v37, vcc
	v_cmp_eq_u32_e32 vcc, v112, v90
	v_cmp_eq_u32_e64 s[0:1], v36, v49
	v_pk_add_f32 v[36:37], v[96:97], v[32:33]
	s_nop 0
	v_cndmask_b32_e64 v102, v32, v36, s[0:1]
	v_cndmask_b32_e32 v103, v33, v37, vcc
	v_sub_f32_e32 v32, v98, v34
	v_sub_f32_e32 v33, v98, v35
	v_min_f32_e32 v32, 0, v32
	v_min_f32_e32 v33, 0, v33
	v_mul_f32_e32 v32, 0x3fb8aa3b, v32
	v_mul_f32_e32 v33, 0x3fb8aa3b, v33
	v_exp_f32_e32 v32, v32
	v_exp_f32_e32 v33, v33
	v_or_b32_e32 v34, 3, v112
	v_or_b32_e32 v35, 2, v112
	v_cmp_le_u32_e32 vcc, v34, v49
	v_pk_mul_f32 v[32:33], v[38:39], v[32:33]
	v_cmp_eq_u32_e64 s[0:1], v34, v49
	v_pk_mul_f32 v[32:33], v[104:105], v[32:33]
	v_add_u32_e32 v36, 0x22840, v111
	v_cndmask_b32_e32 v33, 0, v33, vcc
	v_cmp_le_u32_e32 vcc, v35, v90
	ds_read_b128 v[36:39], v36
	v_add_u32_e32 v112, 16, v110
	v_cndmask_b32_e32 v32, 0, v32, vcc
	v_cmp_eq_u32_e32 vcc, v35, v90
	v_pk_add_f32 v[34:35], v[96:97], v[32:33]
	s_nop 0
	v_cndmask_b32_e32 v105, v32, v34, vcc
	v_add_u32_e32 v32, 0x22040, v111
	v_cndmask_b32_e64 v104, v33, v35, s[0:1]
	ds_read_b128 v[32:35], v32
	v_cmp_gt_u32_e32 vcc, v90, v112
	v_cmp_le_u32_e64 s[0:1], v112, v90
	s_waitcnt lgkmcnt(0)
	v_sub_f32_e32 v32, v98, v32
	v_sub_f32_e32 v33, v98, v33
	v_min_f32_e32 v32, 0, v32
	v_min_f32_e32 v33, 0, v33
	v_mul_f32_e32 v32, 0x3fb8aa3b, v32
	v_mul_f32_e32 v33, 0x3fb8aa3b, v33
	v_exp_f32_e32 v32, v32
	v_exp_f32_e32 v33, v33
	v_mul_f32_e32 v32, v40, v32
	v_mul_f32_e32 v33, v41, v33
	v_mul_f32_e32 v32, v36, v32
	v_mul_f32_e32 v37, v37, v33
	v_add_u32_e32 v36, 17, v110
	v_cndmask_b32_e64 v33, 0, v32, s[0:1]
	v_cndmask_b32_e32 v32, 0, v37, vcc
	v_cmp_eq_u32_e32 vcc, v112, v90
	v_cmp_eq_u32_e64 s[0:1], v36, v49
	v_pk_add_f32 v[36:37], v[96:97], v[32:33]
	s_nop 0
	v_cndmask_b32_e64 v40, v32, v36, s[0:1]
	v_cndmask_b32_e32 v41, v33, v37, vcc
	v_sub_f32_e32 v32, v98, v34
	v_sub_f32_e32 v33, v98, v35
	v_min_f32_e32 v32, 0, v32
	v_min_f32_e32 v33, 0, v33
	v_mul_f32_e32 v32, 0x3fb8aa3b, v32
	v_mul_f32_e32 v33, 0x3fb8aa3b, v33
	v_exp_f32_e32 v32, v32
	v_exp_f32_e32 v33, v33
	v_or_b32_e32 v34, 3, v112
	v_or_b32_e32 v35, 2, v112
	v_cmp_le_u32_e32 vcc, v34, v49
	v_pk_mul_f32 v[32:33], v[42:43], v[32:33]
	v_cmp_eq_u32_e64 s[0:1], v34, v49
	v_pk_mul_f32 v[32:33], v[38:39], v[32:33]
	v_add_u32_e32 v36, 0x22850, v111
	v_cndmask_b32_e32 v33, 0, v33, vcc
	v_cmp_le_u32_e32 vcc, v35, v90
	ds_read_b128 v[36:39], v36
	v_add_u32_e32 v112, 20, v110
	v_cndmask_b32_e32 v32, 0, v32, vcc
	v_cmp_eq_u32_e32 vcc, v35, v90
	v_pk_add_f32 v[34:35], v[96:97], v[32:33]
	s_nop 0
	v_cndmask_b32_e32 v43, v32, v34, vcc
	v_add_u32_e32 v32, 0x22050, v111
	v_cndmask_b32_e64 v42, v33, v35, s[0:1]
	ds_read_b128 v[32:35], v32
	v_cmp_gt_u32_e32 vcc, v90, v112
	v_cmp_le_u32_e64 s[0:1], v112, v90
	s_waitcnt lgkmcnt(0)
; DI_ float bf_lo(unsigned w) { return __uint_as_float(w << 16); }
; DI_ float bf_hi(unsigned w) { return __uint_as_float(w & 0xffff0000u); }
; DI_ bf16x8 pack8(float a0, float a1, float a2, float a3, float a4, float a5, float a6, float a7) { u32x4 p; p.x = pk2(a0, a1); p.y = pk2(a2, a3); p.z = pk2(a4, a5); p.w = pk2(a6, a7); return __builtin_bit_cast(bf16x8, p); }
; #define MFMA32(a, b, c) __builtin_amdgcn_mfma_f32_32x32x16_bf16((a), (b), (c), 0, 0, 0)
; DI_ float silu_f(float v) { return v / (1.f + __expf(-v)); }
; DI_ void ssd_passC(const bf16_t* xsT, const bf16_t* Btok, const bf16_t* Ctok, const bf16_t* Sc, const float* dt, const float* acum, const float* Dskip, const float* norm_w, bf16_t* Z, unsigned char* lds, int tid, int lane, int wid) {
;     ...
;                     for (int e = 0; e < 4; ++e) { const int sl = sl0 + e; float v = cb[4 * q4 + e] * __expf(fminf(at - as4[e], 0.f)) * ds4[e]; v = (sl <= tl) ? v : 0.f; if (sl == tl) v += Dh; m[4 * q4 + e] = v; }
;                 }
;                 const bf16x8 pf0 = pack8(m[0], m[1], m[2], m[3], m[4], m[5], m[6], m[7]), pf1 = pack8(m[8], m[9], m[10], m[11], m[12], m[13], m[14], m[15]);
; #pragma unroll
;                 for (int pb = 0; pb < 2; ++pb) {
;                     const unsigned char* xp = lds + PC_X + (hl * 64 + 32 * pb + r32) * PC_RS + (32 * sb + 8 * hi) * 2;
;                     yv[it][pb] = MFMA32(*(const bf16x8*)xp, pf0, yv[it][pb]); yv[it][pb] = MFMA32(*(const bf16x8*)(xp + 32), pf1, yv[it][pb]);
;                 }
;             }
;             const int tg = t0 + tl; float sq = 0.f;
; #pragma unroll
;             for (int pb = 0; pb < 2; ++pb)
; #pragma unroll
;                 for (int q4 = 0; q4 < 4; ++q4) {
;                     const int chn = hh * 64 + 32 * pb + 8 * q4 + 4 * hi;
;                     const u32x2 zw = *(const u32x2*)(Z + (size_t)tg * DI + chn);
;                     const float a0 = yv[it][pb][4 * q4] * silu_f(bf_lo(zw.x)), a1 = yv[it][pb][4 * q4 + 1] * silu_f(bf_hi(zw.x)), a2 = yv[it][pb][4 * q4 + 2] * silu_f(bf_lo(zw.y)), a3 = yv[it][pb][4 * q4 + 3] * silu_f(bf_hi(zw.y));
;                     sq += (a0 * a0 + a1 * a1) + (a2 * a2 + a3 * a3);
;                     yv[it][pb][4 * q4] = a0; yv[it][pb][4 * q4 + 1] = a1; yv[it][pb][4 * q4 + 2] = a2; yv[it][pb][4 * q4 + 3] = a3;
	v_sub_f32_e32 v32, v98, v32
	v_sub_f32_e32 v33, v98, v33
	v_min_f32_e32 v32, 0, v32
	v_min_f32_e32 v33, 0, v33
	v_mul_f32_e32 v32, 0x3fb8aa3b, v32
	v_mul_f32_e32 v33, 0x3fb8aa3b, v33
	v_exp_f32_e32 v32, v32
	v_exp_f32_e32 v33, v33
	v_mul_f32_e32 v32, v44, v32
	v_mul_f32_e32 v33, v45, v33
	v_mul_f32_e32 v32, v36, v32
	v_mul_f32_e32 v37, v37, v33
	v_add_u32_e32 v36, 21, v110
	v_cndmask_b32_e64 v33, 0, v32, s[0:1]
	v_cndmask_b32_e32 v32, 0, v37, vcc
	v_cmp_eq_u32_e32 vcc, v112, v90
	v_cmp_eq_u32_e64 s[0:1], v36, v49
	v_pk_add_f32 v[36:37], v[96:97], v[32:33]
	s_nop 0
	v_cndmask_b32_e64 v44, v32, v36, s[0:1]
	v_cndmask_b32_e32 v45, v33, v37, vcc
	v_sub_f32_e32 v32, v98, v34
	v_sub_f32_e32 v33, v98, v35
	v_min_f32_e32 v32, 0, v32
	v_min_f32_e32 v33, 0, v33
	v_mul_f32_e32 v32, 0x3fb8aa3b, v32
	v_mul_f32_e32 v33, 0x3fb8aa3b, v33
	v_exp_f32_e32 v32, v32
	v_exp_f32_e32 v33, v33
	v_or_b32_e32 v34, 3, v112
	v_or_b32_e32 v35, 2, v112
	v_cmp_le_u32_e32 vcc, v34, v49
	v_pk_mul_f32 v[32:33], v[46:47], v[32:33]
	v_cmp_eq_u32_e64 s[0:1], v34, v49
	v_pk_mul_f32 v[32:33], v[38:39], v[32:33]
	v_cvt_pk_bf16_f32 v36, v107, v106
	v_cndmask_b32_e32 v33, 0, v33, vcc
	v_cmp_le_u32_e32 vcc, v35, v90
	v_cvt_pk_bf16_f32 v37, v109, v108
	v_cvt_pk_bf16_f32 v38, v103, v102
	v_cndmask_b32_e32 v32, 0, v32, vcc
	v_cmp_eq_u32_e32 vcc, v35, v90
	v_pk_add_f32 v[34:35], v[96:97], v[32:33]
	v_cvt_pk_bf16_f32 v39, v105, v104
	v_cndmask_b32_e32 v46, v32, v34, vcc
	v_cvt_pk_bf16_f32 v34, v45, v44
	v_add_u32_e32 v44, 0, v101
	v_cvt_pk_bf16_f32 v32, v41, v40
	v_add_u32_e32 v40, 0x11000, v44
	v_cndmask_b32_e64 v35, v33, v35, s[0:1]
	v_cvt_pk_bf16_f32 v33, v43, v42
	ds_read_b128 v[40:43], v40
	s_waitcnt lgkmcnt(0)
	v_mfma_f32_32x32x16_bf16 v[16:31], v[40:43], v[36:39], v[16:31]
	v_add_u32_e32 v40, 0x11020, v44
	ds_read_b128 v[40:43], v40
	v_cvt_pk_bf16_f32 v35, v46, v35
	v_add_u32_e32 v101, 64, v101
	s_waitcnt lgkmcnt(0)
	v_mfma_f32_32x32x16_bf16 v[16:31], v[40:43], v[32:35], v[16:31]
	v_add_u32_e32 v40, 0x13200, v44
	ds_read_b128 v[40:43], v40
	s_waitcnt lgkmcnt(0)
	v_mfma_f32_32x32x16_bf16 v[0:15], v[40:43], v[36:39], v[0:15]
	v_add_u32_e32 v36, 0x13220, v44
	ds_read_b128 v[36:39], v36
	s_waitcnt lgkmcnt(0)
	v_mfma_f32_32x32x16_bf16 v[0:15], v[36:39], v[32:35], v[0:15]
	s_cbranch_scc1 .LBB0_765
	v_or_b32_e32 v102, s42, v90
	v_ashrrev_i32_e32 v103, 31, v102
	v_lshl_or_b32 v96, s6, 6, v138
	v_lshlrev_b64 v[32:33], 12, v[102:103]
	v_lshl_add_u64 v[32:33], s[56:57], 0, v[32:33]
	v_ashrrev_i32_e32 v97, 31, v96
	v_lshl_add_u64 v[32:33], v[96:97], 1, v[32:33]
	global_load_dwordx2 v[206:207], v[32:33], off
	global_load_dwordx2 v[208:209], v[32:33], off offset:16
	global_load_dwordx2 v[210:211], v[32:33], off offset:32
	global_load_dwordx2 v[212:213], v[32:33], off offset:48
	global_load_dwordx2 v[214:215], v[32:33], off offset:64
	global_load_dwordx2 v[216:217], v[32:33], off offset:80
	global_load_dwordx2 v[218:219], v[32:33], off offset:96
	global_load_dwordx2 v[220:221], v[32:33], off offset:112
	s_waitcnt vmcnt(7)
	v_mov_b32_e32 v34, v206
	v_mov_b32_e32 v35, v207
	v_lshlrev_b32_e32 v38, 16, v34
	v_and_b32_e32 v34, 0xffff0000, v34
	v_mul_f32_e32 v36, 0xbfb8aa3b, v38
	v_mul_f32_e32 v37, 0xbfb8aa3b, v34
	v_exp_f32_e32 v36, v36
	v_exp_f32_e32 v37, v37
	s_nop 0
	v_pk_add_f32 v[36:37], v[36:37], 1.0 op_sel_hi:[1,0]
	s_nop 0
	v_rcp_f32_e32 v40, v37
	s_nop 0
	v_mul_f32_e32 v37, v34, v40
	v_rcp_f32_e32 v39, v36
	s_nop 0
	v_mul_f32_e32 v36, v38, v39
	v_lshlrev_b32_e32 v34, 16, v35
	v_and_b32_e32 v35, 0xffff0000, v35
	v_pk_mul_f32 v[98:99], v[16:17], v[36:37]
	v_mul_f32_e32 v16, 0xbfb8aa3b, v34
	v_mul_f32_e32 v17, 0xbfb8aa3b, v35
	v_exp_f32_e32 v16, v16
	v_exp_f32_e32 v17, v17
	s_nop 0
	v_pk_add_f32 v[16:17], v[16:17], 1.0 op_sel_hi:[1,0]
	s_nop 0
	v_rcp_f32_e32 v37, v17
	s_nop 0
	v_mul_f32_e32 v17, v35, v37
	v_rcp_f32_e32 v36, v16
	s_nop 0
	v_mul_f32_e32 v16, v34, v36
	v_pk_mul_f32 v[100:101], v[18:19], v[16:17]
	v_pk_mul_f32 v[16:17], v[98:99], v[98:99]
	v_pk_mul_f32 v[18:19], v[100:101], v[100:101]
	v_add_f32_e32 v16, v16, v17
	v_add_f32_e32 v18, v18, v19
	v_add_f32_e32 v16, v16, v18
	s_waitcnt vmcnt(6)
	v_mov_b32_e32 v34, v208
	v_mov_b32_e32 v35, v209
	v_lshlrev_b32_e32 v38, 16, v34
	v_and_b32_e32 v34, 0xffff0000, v34
	v_mul_f32_e32 v36, 0xbfb8aa3b, v38
	v_mul_f32_e32 v37, 0xbfb8aa3b, v34
	v_exp_f32_e32 v36, v36
	v_exp_f32_e32 v37, v37
	s_nop 0
	v_pk_add_f32 v[36:37], v[36:37], 1.0 op_sel_hi:[1,0]
	s_nop 0
	v_rcp_f32_e32 v40, v37
	s_nop 0
	v_mul_f32_e32 v37, v34, v40
	v_rcp_f32_e32 v39, v36
	s_nop 0
	v_mul_f32_e32 v36, v38, v39
	v_lshlrev_b32_e32 v34, 16, v35
	v_and_b32_e32 v35, 0xffff0000, v35
	v_pk_mul_f32 v[104:105], v[20:21], v[36:37]
	v_mul_f32_e32 v20, 0xbfb8aa3b, v34
	v_mul_f32_e32 v21, 0xbfb8aa3b, v35
	v_exp_f32_e32 v20, v20
	v_exp_f32_e32 v21, v21
	s_nop 0
	v_pk_add_f32 v[20:21], v[20:21], 1.0 op_sel_hi:[1,0]
	s_nop 0
	v_rcp_f32_e32 v37, v21
	s_nop 0
	v_mul_f32_e32 v21, v35, v37
	v_rcp_f32_e32 v36, v20
	s_nop 0
	v_mul_f32_e32 v20, v34, v36
	v_pk_mul_f32 v[106:107], v[22:23], v[20:21]
	v_pk_mul_f32 v[20:21], v[104:105], v[104:105]
	v_pk_mul_f32 v[22:23], v[106:107], v[106:107]
	v_add_f32_e32 v20, v20, v21
	v_add_f32_e32 v22, v22, v23
	v_add_f32_e32 v20, v20, v22
	v_add_f32_e32 v16, v16, v20
	s_waitcnt vmcnt(5)
; DI_ float bf_lo(unsigned w) { return __uint_as_float(w << 16); }
; DI_ float bf_hi(unsigned w) { return __uint_as_float(w & 0xffff0000u); }
; DI_ float silu_f(float v) { return v / (1.f + __expf(-v)); }
; DI_ void ssd_passC(const bf16_t* xsT, const bf16_t* Btok, const bf16_t* Ctok, const bf16_t* Sc, const float* dt, const float* acum, const float* Dskip, const float* norm_w, bf16_t* Z, unsigned char* lds, int tid, int lane, int wid) {
;     ...
;             const int tg = t0 + tl; float sq = 0.f;
; #pragma unroll
;             for (int pb = 0; pb < 2; ++pb)
; #pragma unroll
;                 for (int q4 = 0; q4 < 4; ++q4) {
;                     const int chn = hh * 64 + 32 * pb + 8 * q4 + 4 * hi;
;                     const u32x2 zw = *(const u32x2*)(Z + (size_t)tg * DI + chn);
;                     const float a0 = yv[it][pb][4 * q4] * silu_f(bf_lo(zw.x)), a1 = yv[it][pb][4 * q4 + 1] * silu_f(bf_hi(zw.x)), a2 = yv[it][pb][4 * q4 + 2] * silu_f(bf_lo(zw.y)), a3 = yv[it][pb][4 * q4 + 3] * silu_f(bf_hi(zw.y));
;                     sq += (a0 * a0 + a1 * a1) + (a2 * a2 + a3 * a3);
;                     yv[it][pb][4 * q4] = a0; yv[it][pb][4 * q4 + 1] = a1; yv[it][pb][4 * q4 + 2] = a2; yv[it][pb][4 * q4 + 3] = a3;
;                 }
;             sq += __shfl_xor(sq, 32);
;             if (hi == 0) ex[hl * 128 + tl] = sq;
	v_mov_b32_e32 v34, v210
	v_mov_b32_e32 v35, v211
	v_lshlrev_b32_e32 v38, 16, v34
	v_and_b32_e32 v34, 0xffff0000, v34
	v_mul_f32_e32 v36, 0xbfb8aa3b, v38
	v_mul_f32_e32 v37, 0xbfb8aa3b, v34
	v_exp_f32_e32 v36, v36
	v_exp_f32_e32 v37, v37
	s_nop 0
	v_pk_add_f32 v[36:37], v[36:37], 1.0 op_sel_hi:[1,0]
	s_nop 0
	v_rcp_f32_e32 v40, v37
	s_nop 0
	v_mul_f32_e32 v37, v34, v40
	v_rcp_f32_e32 v39, v36
	s_nop 0
	v_mul_f32_e32 v36, v38, v39
	v_lshlrev_b32_e32 v34, 16, v35
	v_and_b32_e32 v35, 0xffff0000, v35
	v_pk_mul_f32 v[108:109], v[24:25], v[36:37]
	v_mul_f32_e32 v24, 0xbfb8aa3b, v34
	v_mul_f32_e32 v25, 0xbfb8aa3b, v35
	v_exp_f32_e32 v24, v24
	v_exp_f32_e32 v25, v25
	s_nop 0
	v_pk_add_f32 v[24:25], v[24:25], 1.0 op_sel_hi:[1,0]
	s_nop 0
	v_rcp_f32_e32 v37, v25
	s_nop 0
	v_mul_f32_e32 v25, v35, v37
	v_rcp_f32_e32 v36, v24
	s_nop 0
	v_mul_f32_e32 v24, v34, v36
	v_pk_mul_f32 v[110:111], v[26:27], v[24:25]
	v_pk_mul_f32 v[24:25], v[108:109], v[108:109]
	v_pk_mul_f32 v[26:27], v[110:111], v[110:111]
	v_add_f32_e32 v18, v24, v25
	v_add_f32_e32 v17, v26, v27
	v_add_f32_e32 v17, v18, v17
	v_add_f32_e32 v16, v16, v17
	s_waitcnt vmcnt(4)
	v_mov_b32_e32 v34, v212
	v_mov_b32_e32 v35, v213
	v_lshlrev_b32_e32 v38, 16, v34
	v_and_b32_e32 v34, 0xffff0000, v34
	v_mul_f32_e32 v36, 0xbfb8aa3b, v38
	v_mul_f32_e32 v37, 0xbfb8aa3b, v34
	v_exp_f32_e32 v36, v36
	v_exp_f32_e32 v37, v37
	s_nop 0
	v_pk_add_f32 v[36:37], v[36:37], 1.0 op_sel_hi:[1,0]
	s_nop 0
	v_rcp_f32_e32 v40, v37
	s_nop 0
	v_mul_f32_e32 v37, v34, v40
	v_rcp_f32_e32 v39, v36
	s_nop 0
	v_mul_f32_e32 v36, v38, v39
	v_lshlrev_b32_e32 v34, 16, v35
	v_and_b32_e32 v35, 0xffff0000, v35
	v_pk_mul_f32 v[112:113], v[28:29], v[36:37]
	v_mul_f32_e32 v28, 0xbfb8aa3b, v34
	v_mul_f32_e32 v29, 0xbfb8aa3b, v35
	v_exp_f32_e32 v28, v28
	v_exp_f32_e32 v29, v29
	s_nop 0
	v_pk_add_f32 v[28:29], v[28:29], 1.0 op_sel_hi:[1,0]
	s_nop 0
	v_rcp_f32_e32 v37, v29
	s_nop 0
	v_mul_f32_e32 v29, v35, v37
	v_rcp_f32_e32 v36, v28
	s_nop 0
	v_mul_f32_e32 v28, v34, v36
	v_pk_mul_f32 v[114:115], v[30:31], v[28:29]
	v_pk_mul_f32 v[28:29], v[112:113], v[112:113]
	v_pk_mul_f32 v[30:31], v[114:115], v[114:115]
	v_add_f32_e32 v18, v28, v29
	v_add_f32_e32 v17, v30, v31
	v_add_f32_e32 v17, v18, v17
	v_add_f32_e32 v16, v16, v17
	s_waitcnt vmcnt(3)
	v_mov_b32_e32 v34, v214
	v_mov_b32_e32 v35, v215
	v_lshlrev_b32_e32 v38, 16, v34
	v_and_b32_e32 v34, 0xffff0000, v34
	v_mul_f32_e32 v36, 0xbfb8aa3b, v38
	v_mul_f32_e32 v37, 0xbfb8aa3b, v34
	v_exp_f32_e32 v36, v36
	v_exp_f32_e32 v37, v37
	s_nop 0
	v_pk_add_f32 v[36:37], v[36:37], 1.0 op_sel_hi:[1,0]
	s_nop 0
	v_rcp_f32_e32 v40, v37
	s_nop 0
	v_mul_f32_e32 v37, v34, v40
	v_rcp_f32_e32 v39, v36
	s_nop 0
	v_mul_f32_e32 v36, v38, v39
	v_lshlrev_b32_e32 v34, 16, v35
	v_and_b32_e32 v35, 0xffff0000, v35
	v_pk_mul_f32 v[116:117], v[0:1], v[36:37]
	v_mul_f32_e32 v0, 0xbfb8aa3b, v34
	v_mul_f32_e32 v1, 0xbfb8aa3b, v35
	v_exp_f32_e32 v0, v0
	v_exp_f32_e32 v1, v1
	s_nop 0
	v_pk_add_f32 v[0:1], v[0:1], 1.0 op_sel_hi:[1,0]
	s_nop 0
	v_rcp_f32_e32 v37, v1
	s_nop 0
	v_mul_f32_e32 v1, v35, v37
	v_rcp_f32_e32 v36, v0
	s_nop 0
	v_mul_f32_e32 v0, v34, v36
	v_pk_mul_f32 v[118:119], v[2:3], v[0:1]
	v_pk_mul_f32 v[0:1], v[116:117], v[116:117]
	v_pk_mul_f32 v[2:3], v[118:119], v[118:119]
	v_add_f32_e32 v0, v0, v1
	v_add_f32_e32 v2, v2, v3
	v_add_f32_e32 v0, v0, v2
	v_add_f32_e32 v0, v16, v0
	s_waitcnt vmcnt(2)
	v_mov_b32_e32 v34, v216
	v_mov_b32_e32 v35, v217
	v_lshlrev_b32_e32 v38, 16, v34
	v_and_b32_e32 v34, 0xffff0000, v34
	v_mul_f32_e32 v36, 0xbfb8aa3b, v38
	v_mul_f32_e32 v37, 0xbfb8aa3b, v34
	v_exp_f32_e32 v36, v36
	v_exp_f32_e32 v37, v37
	s_nop 0
	v_pk_add_f32 v[36:37], v[36:37], 1.0 op_sel_hi:[1,0]
	s_nop 0
	v_rcp_f32_e32 v40, v37
	s_nop 0
	v_mul_f32_e32 v37, v34, v40
	v_rcp_f32_e32 v39, v36
	s_nop 0
	v_mul_f32_e32 v36, v38, v39
	v_lshlrev_b32_e32 v34, 16, v35
	v_and_b32_e32 v35, 0xffff0000, v35
	v_pk_mul_f32 v[120:121], v[4:5], v[36:37]
	v_mul_f32_e32 v4, 0xbfb8aa3b, v34
	v_mul_f32_e32 v5, 0xbfb8aa3b, v35
	v_exp_f32_e32 v4, v4
	v_exp_f32_e32 v5, v5
	s_nop 0
	v_pk_add_f32 v[4:5], v[4:5], 1.0 op_sel_hi:[1,0]
	s_nop 0
	v_rcp_f32_e32 v37, v5
	s_nop 0
	v_mul_f32_e32 v5, v35, v37
	v_rcp_f32_e32 v36, v4
	s_nop 0
	v_mul_f32_e32 v4, v34, v36
	v_pk_mul_f32 v[122:123], v[6:7], v[4:5]
	v_pk_mul_f32 v[4:5], v[120:121], v[120:121]
	v_pk_mul_f32 v[6:7], v[122:123], v[122:123]
	v_add_f32_e32 v2, v4, v5
	v_add_f32_e32 v1, v6, v7
	v_add_f32_e32 v1, v2, v1
	v_add_f32_e32 v0, v0, v1
	s_waitcnt vmcnt(1)
	v_mov_b32_e32 v34, v218
	v_mov_b32_e32 v35, v219
	v_lshlrev_b32_e32 v38, 16, v34
	v_and_b32_e32 v34, 0xffff0000, v34
	v_mul_f32_e32 v36, 0xbfb8aa3b, v38
	v_mul_f32_e32 v37, 0xbfb8aa3b, v34
	v_exp_f32_e32 v36, v36
	v_exp_f32_e32 v37, v37
	s_nop 0
	v_pk_add_f32 v[36:37], v[36:37], 1.0 op_sel_hi:[1,0]
	s_nop 0
	v_rcp_f32_e32 v40, v37
	s_nop 0
	v_mul_f32_e32 v37, v34, v40
	v_rcp_f32_e32 v39, v36
	s_nop 0
	v_mul_f32_e32 v36, v38, v39
	v_lshlrev_b32_e32 v34, 16, v35
	v_and_b32_e32 v35, 0xffff0000, v35
	v_pk_mul_f32 v[124:125], v[8:9], v[36:37]
	v_mul_f32_e32 v8, 0xbfb8aa3b, v34
	v_mul_f32_e32 v9, 0xbfb8aa3b, v35
	v_exp_f32_e32 v8, v8
	v_exp_f32_e32 v9, v9
	s_nop 0
	v_pk_add_f32 v[8:9], v[8:9], 1.0 op_sel_hi:[1,0]
	s_nop 0
	v_rcp_f32_e32 v37, v9
	s_nop 0
	v_mul_f32_e32 v9, v35, v37
	v_rcp_f32_e32 v36, v8
	s_nop 0
	v_mul_f32_e32 v38, v34, v36
	v_mov_b32_e32 v35, v38
	s_waitcnt vmcnt(0)
	v_mov_b32_e32 v32, v220
	v_mov_b32_e32 v33, v221
	v_lshlrev_b32_e32 v36, 16, v32
	v_and_b32_e32 v32, 0xffff0000, v32
	v_mov_b32_e32 v8, v35
	v_mul_f32_e32 v34, 0xbfb8aa3b, v36
	v_mul_f32_e32 v35, 0xbfb8aa3b, v32
	v_exp_f32_e32 v34, v34
	v_exp_f32_e32 v35, v35
	v_pk_mul_f32 v[126:127], v[10:11], v[8:9]
	v_pk_mul_f32 v[8:9], v[124:125], v[124:125]
	v_pk_mul_f32 v[10:11], v[126:127], v[126:127]
	v_pk_add_f32 v[34:35], v[34:35], 1.0 op_sel_hi:[1,0]
	v_add_f32_e32 v1, v10, v11
	v_rcp_f32_e32 v38, v35
	v_add_f32_e32 v2, v8, v9
	v_add_f32_e32 v1, v2, v1
	v_add_f32_e32 v0, v0, v1
	v_mul_f32_e32 v35, v32, v38
	v_rcp_f32_e32 v37, v34
	s_nop 0
	v_mul_f32_e32 v34, v36, v37
	v_lshlrev_b32_e32 v32, 16, v33
	v_and_b32_e32 v33, 0xffff0000, v33
	v_pk_mul_f32 v[128:129], v[12:13], v[34:35]
	v_mul_f32_e32 v12, 0xbfb8aa3b, v32
	v_mul_f32_e32 v13, 0xbfb8aa3b, v33
	v_exp_f32_e32 v12, v12
	v_exp_f32_e32 v13, v13
	s_nop 0
	v_pk_add_f32 v[12:13], v[12:13], 1.0 op_sel_hi:[1,0]
	s_nop 0
	v_rcp_f32_e32 v35, v13
	s_nop 0
	v_mul_f32_e32 v13, v33, v35
	v_rcp_f32_e32 v34, v12
	s_nop 0
	v_mul_f32_e32 v12, v32, v34
	v_pk_mul_f32 v[130:131], v[14:15], v[12:13]
	v_pk_mul_f32 v[12:13], v[128:129], v[128:129]
	v_pk_mul_f32 v[14:15], v[130:131], v[130:131]
	v_add_f32_e32 v2, v12, v13
	v_add_f32_e32 v1, v14, v15
	v_add_f32_e32 v1, v2, v1
	v_add_f32_e32 v0, v0, v1
	ds_bpermute_b32 v1, v139, v0
	s_and_saveexec_b64 s[0:1], s[40:41]
	s_cbranch_execz .LBB0_768
	s_waitcnt lgkmcnt(0)
	v_add_f32_e32 v0, v0, v1
	ds_write_b32 v141, v0

; DI_ bf16x8 pack8(float a0, float a1, float a2, float a3, float a4, float a5, float a6, float a7) { u32x4 p; p.x = pk2(a0, a1); p.y = pk2(a2, a3); p.z = pk2(a4, a5); p.w = pk2(a6, a7); return __builtin_bit_cast(bf16x8, p); }
; #define MFMA32(a, b, c) __builtin_amdgcn_mfma_f32_32x32x16_bf16((a), (b), (c), 0, 0, 0)
; DI_ int kvmap(int rho) { return (rho & 0x13) | ((rho & 4) << 1) | ((rho & 8) >> 1); }
; DI_ void ssd_passC(const bf16_t* xsT, const bf16_t* Btok, const bf16_t* Ctok, const bf16_t* Sc, const float* dt, const float* acum, const float* Dskip, const float* norm_w, bf16_t* Z, unsigned char* lds, int tid, int lane, int wid) {
;     ...
;             for (int sb = 0; sb <= tb; ++sb) {
;                 f32x16 cb;
; #pragma unroll
;                 for (int i = 0; i < 16; ++i) cb[i] = 0.f;
;                 const unsigned char* bp = lds + PC_B + (32 * sb + kvmap(r32)) * PC_RS + hi * 16;
; #pragma unroll
;                 for (int ks = 0; ks < 8; ++ks) cb = MFMA32(*(const bf16x8*)(bp + 32 * ks), *(const bf16x8*)(cfp + 32 * ks), cb);
;                 float m[16];
; #pragma unroll
;                 for (int q4 = 0; q4 < 4; ++q4) {
;                     const int sl0 = 32 * sb + 16 * (q4 >> 1) + 8 * hi + 4 * (q4 & 1);
;                     const f32x4 as4 = *(const f32x4*)(sa + hl * 128 + sl0), ds4 = *(const f32x4*)(sd + hl * 128 + sl0);
; #pragma unroll
;                     for (int e = 0; e < 4; ++e) { const int sl = sl0 + e; float v = cb[4 * q4 + e] * __expf(fminf(at - as4[e], 0.f)) * ds4[e]; v = (sl <= tl) ? v : 0.f; if (sl == tl) v += Dh; m[4 * q4 + e] = v; }
;                 }
;                 const bf16x8 pf0 = pack8(m[0], m[1], m[2], m[3], m[4], m[5], m[6], m[7]), pf1 = pack8(m[8], m[9], m[10], m[11], m[12], m[13], m[14], m[15]);
.LBB0_769:
	v_add_u32_e32 v159, 0, v156
	ds_read_b128 v[32:35], v159
	ds_read_b128 v[160:163], v159 offset:32
	v_add_u32_e32 v177, 0, v157
	v_add_u32_e32 v164, 0x22800, v177
	v_add_u32_e32 v157, 0x80, v157
	s_waitcnt lgkmcnt(1)
	v_mfma_f32_32x32x16_bf16 v[32:47], v[32:35], v[50:53], 0
	v_add_u32_e32 v156, 0x2200, v156
	ds_read_b128 v[164:167], v164
	s_waitcnt lgkmcnt(1)
	v_mfma_f32_32x32x16_bf16 v[32:47], v[160:163], v[54:57], v[32:47]
	ds_read_b128 v[160:163], v159 offset:64
	s_waitcnt lgkmcnt(0)
	v_mfma_f32_32x32x16_bf16 v[32:47], v[160:163], v[58:61], v[32:47]
	ds_read_b128 v[160:163], v159 offset:96
	s_waitcnt lgkmcnt(0)
	v_mfma_f32_32x32x16_bf16 v[32:47], v[160:163], v[62:65], v[32:47]
	ds_read_b128 v[160:163], v159 offset:128
	s_waitcnt lgkmcnt(0)
	v_mfma_f32_32x32x16_bf16 v[32:47], v[160:163], v[66:69], v[32:47]
	ds_read_b128 v[160:163], v159 offset:160
	s_waitcnt lgkmcnt(0)
	v_mfma_f32_32x32x16_bf16 v[32:47], v[160:163], v[70:73], v[32:47]
	ds_read_b128 v[160:163], v159 offset:192
	s_waitcnt lgkmcnt(0)
	v_mfma_f32_32x32x16_bf16 v[32:47], v[160:163], v[74:77], v[32:47]
	ds_read_b128 v[160:163], v159 offset:224
	v_add_u32_e32 v159, s7, v137
	v_cmp_gt_u32_e32 vcc, v92, v159
	v_cmp_le_u32_e64 s[0:1], v159, v92
	v_add_u32_e32 v178, 4, v159
	s_add_i32 s7, s7, 32
	s_waitcnt lgkmcnt(0)
	v_mfma_f32_32x32x16_bf16 v[32:47], v[160:163], v[78:81], v[32:47]
	v_add_u32_e32 v160, 0x22000, v177
	ds_read_b128 v[160:163], v160
	s_waitcnt lgkmcnt(0)
	v_sub_f32_e32 v160, v155, v160
	v_sub_f32_e32 v161, v155, v161
	v_min_f32_e32 v160, 0, v160
	v_min_f32_e32 v161, 0, v161
	v_mul_f32_e32 v160, 0x3fb8aa3b, v160
	v_mul_f32_e32 v161, 0x3fb8aa3b, v161
	v_exp_f32_e32 v160, v160
	v_exp_f32_e32 v161, v161
	s_nop 0
	v_mul_f32_e32 v32, v32, v160
	v_mul_f32_e32 v33, v33, v161
	v_mul_f32_e32 v32, v164, v32
	v_mul_f32_e32 v161, v165, v33
	v_add_u32_e32 v160, 1, v159
	v_cndmask_b32_e64 v33, 0, v32, s[0:1]
	v_cndmask_b32_e32 v32, 0, v161, vcc
	v_cmp_eq_u32_e32 vcc, v159, v92
	v_cmp_eq_u32_e64 s[0:1], v160, v91
	v_pk_add_f32 v[160:161], v[132:133], v[32:33]
	s_nop 0
	v_cndmask_b32_e64 v164, v32, v160, s[0:1]
	v_cndmask_b32_e32 v165, v33, v161, vcc
	v_sub_f32_e32 v32, v155, v162
	v_sub_f32_e32 v33, v155, v163
	v_min_f32_e32 v32, 0, v32
	v_min_f32_e32 v33, 0, v33
	v_mul_f32_e32 v32, 0x3fb8aa3b, v32
	v_mul_f32_e32 v33, 0x3fb8aa3b, v33
	v_exp_f32_e32 v32, v32
	v_exp_f32_e32 v33, v33
	v_or_b32_e32 v160, 3, v159
	v_or_b32_e32 v161, 2, v159
	v_cmp_le_u32_e32 vcc, v160, v91
	v_pk_mul_f32 v[32:33], v[34:35], v[32:33]
	v_cmp_eq_u32_e64 s[0:1], v160, v91
	v_pk_mul_f32 v[32:33], v[166:167], v[32:33]
	v_add_u32_e32 v160, 0x22810, v177
	v_cndmask_b32_e32 v33, 0, v33, vcc
	v_cmp_le_u32_e32 vcc, v161, v92
	s_nop 1
	v_cndmask_b32_e32 v32, 0, v32, vcc
	v_cmp_eq_u32_e32 vcc, v161, v92
	v_pk_add_f32 v[34:35], v[132:133], v[32:33]
	ds_read_b128 v[160:163], v160
	v_cndmask_b32_e32 v167, v32, v34, vcc
	v_add_u32_e32 v32, 0x22010, v177
	v_cndmask_b32_e64 v166, v33, v35, s[0:1]
	ds_read_b128 v[32:35], v32
	v_cmp_gt_u32_e32 vcc, v92, v178
	v_cmp_le_u32_e64 s[0:1], v178, v92
	s_waitcnt lgkmcnt(0)
	v_sub_f32_e32 v32, v155, v32
	v_sub_f32_e32 v33, v155, v33
	v_min_f32_e32 v32, 0, v32
	v_min_f32_e32 v33, 0, v33
	v_mul_f32_e32 v32, 0x3fb8aa3b, v32
	v_mul_f32_e32 v33, 0x3fb8aa3b, v33
	v_exp_f32_e32 v32, v32
	v_exp_f32_e32 v33, v33
	v_mul_f32_e32 v32, v36, v32
	v_mul_f32_e32 v33, v37, v33
	v_mul_f32_e32 v32, v160, v32
	v_mul_f32_e32 v37, v161, v33
	v_add_u32_e32 v36, 5, v159
	v_cndmask_b32_e64 v33, 0, v32, s[0:1]
	v_cndmask_b32_e32 v32, 0, v37, vcc
	v_cmp_eq_u32_e32 vcc, v178, v92
	v_cmp_eq_u32_e64 s[0:1], v36, v91
	v_pk_add_f32 v[36:37], v[132:133], v[32:33]
	s_nop 0
	v_cndmask_b32_e64 v160, v32, v36, s[0:1]
	v_cndmask_b32_e32 v161, v33, v37, vcc
	v_sub_f32_e32 v32, v155, v34
	v_sub_f32_e32 v33, v155, v35
	v_min_f32_e32 v32, 0, v32
	v_min_f32_e32 v33, 0, v33
	v_mul_f32_e32 v32, 0x3fb8aa3b, v32
	v_mul_f32_e32 v33, 0x3fb8aa3b, v33
	v_exp_f32_e32 v32, v32
	v_exp_f32_e32 v33, v33
	v_or_b32_e32 v34, 3, v178
	v_or_b32_e32 v35, 2, v178
	v_cmp_le_u32_e32 vcc, v34, v91
	v_pk_mul_f32 v[32:33], v[38:39], v[32:33]
	v_cmp_eq_u32_e64 s[0:1], v34, v91
	v_pk_mul_f32 v[32:33], v[162:163], v[32:33]
	v_add_u32_e32 v36, 0x22840, v177
	v_cndmask_b32_e32 v33, 0, v33, vcc
	v_cmp_le_u32_e32 vcc, v35, v92
	ds_read_b128 v[36:39], v36
	v_add_u32_e32 v178, 16, v159
	v_cndmask_b32_e32 v32, 0, v32, vcc
	v_cmp_eq_u32_e32 vcc, v35, v92
	v_pk_add_f32 v[34:35], v[132:133], v[32:33]
	s_nop 0
	v_cndmask_b32_e32 v163, v32, v34, vcc
	v_add_u32_e32 v32, 0x22040, v177
	v_cndmask_b32_e64 v162, v33, v35, s[0:1]
	ds_read_b128 v[32:35], v32
	v_cmp_gt_u32_e32 vcc, v92, v178
	v_cmp_le_u32_e64 s[0:1], v178, v92
	s_waitcnt lgkmcnt(0)
	v_sub_f32_e32 v32, v155, v32
	v_sub_f32_e32 v33, v155, v33
	v_min_f32_e32 v32, 0, v32
	v_min_f32_e32 v33, 0, v33
	v_mul_f32_e32 v32, 0x3fb8aa3b, v32
	v_mul_f32_e32 v33, 0x3fb8aa3b, v33
	v_exp_f32_e32 v32, v32
	v_exp_f32_e32 v33, v33
	v_mul_f32_e32 v32, v40, v32
	v_mul_f32_e32 v33, v41, v33
	v_mul_f32_e32 v32, v36, v32
	v_mul_f32_e32 v37, v37, v33
	v_add_u32_e32 v36, 17, v159
	v_cndmask_b32_e64 v33, 0, v32, s[0:1]
	v_cndmask_b32_e32 v32, 0, v37, vcc
	v_cmp_eq_u32_e32 vcc, v178, v92
	v_cmp_eq_u32_e64 s[0:1], v36, v91
	v_pk_add_f32 v[36:37], v[132:133], v[32:33]
	s_nop 0
	v_cndmask_b32_e64 v40, v32, v36, s[0:1]
	v_cndmask_b32_e32 v41, v33, v37, vcc
	v_sub_f32_e32 v32, v155, v34
	v_sub_f32_e32 v33, v155, v35
	v_min_f32_e32 v32, 0, v32
	v_min_f32_e32 v33, 0, v33
	v_mul_f32_e32 v32, 0x3fb8aa3b, v32
	v_mul_f32_e32 v33, 0x3fb8aa3b, v33
	v_exp_f32_e32 v32, v32
	v_exp_f32_e32 v33, v33
	v_or_b32_e32 v34, 3, v178
	v_or_b32_e32 v35, 2, v178
	v_cmp_le_u32_e32 vcc, v34, v91
	v_pk_mul_f32 v[32:33], v[42:43], v[32:33]
	v_cmp_eq_u32_e64 s[0:1], v34, v91
	v_pk_mul_f32 v[32:33], v[38:39], v[32:33]
	v_add_u32_e32 v36, 0x22850, v177
	v_cndmask_b32_e32 v33, 0, v33, vcc
	v_cmp_le_u32_e32 vcc, v35, v92
	ds_read_b128 v[36:39], v36
	v_add_u32_e32 v178, 20, v159
	v_cndmask_b32_e32 v32, 0, v32, vcc
	v_cmp_eq_u32_e32 vcc, v35, v92
	v_pk_add_f32 v[34:35], v[132:133], v[32:33]
	s_nop 0
	v_cndmask_b32_e32 v43, v32, v34, vcc
	v_add_u32_e32 v32, 0x22050, v177
	v_cndmask_b32_e64 v42, v33, v35, s[0:1]
	ds_read_b128 v[32:35], v32
	v_cmp_gt_u32_e32 vcc, v92, v178
	v_cmp_le_u32_e64 s[0:1], v178, v92
	s_waitcnt lgkmcnt(0)
; DI_ float bf_lo(unsigned w) { return __uint_as_float(w << 16); }
; DI_ float bf_hi(unsigned w) { return __uint_as_float(w & 0xffff0000u); }
; DI_ bf16x8 pack8(float a0, float a1, float a2, float a3, float a4, float a5, float a6, float a7) { u32x4 p; p.x = pk2(a0, a1); p.y = pk2(a2, a3); p.z = pk2(a4, a5); p.w = pk2(a6, a7); return __builtin_bit_cast(bf16x8, p); }
; #define MFMA32(a, b, c) __builtin_amdgcn_mfma_f32_32x32x16_bf16((a), (b), (c), 0, 0, 0)
; DI_ float silu_f(float v) { return v / (1.f + __expf(-v)); }
; DI_ void ssd_passC(const bf16_t* xsT, const bf16_t* Btok, const bf16_t* Ctok, const bf16_t* Sc, const float* dt, const float* acum, const float* Dskip, const float* norm_w, bf16_t* Z, unsigned char* lds, int tid, int lane, int wid) {
;     ...
;                 const bf16x8 pf0 = pack8(m[0], m[1], m[2], m[3], m[4], m[5], m[6], m[7]), pf1 = pack8(m[8], m[9], m[10], m[11], m[12], m[13], m[14], m[15]);
; #pragma unroll
;                 for (int pb = 0; pb < 2; ++pb) {
;                     const unsigned char* xp = lds + PC_X + (hl * 64 + 32 * pb + r32) * PC_RS + (32 * sb + 8 * hi) * 2;
;                     yv[it][pb] = MFMA32(*(const bf16x8*)xp, pf0, yv[it][pb]); yv[it][pb] = MFMA32(*(const bf16x8*)(xp + 32), pf1, yv[it][pb]);
;                 }
;     ...
;             const int tg = t0 + tl; float sq = 0.f;
; #pragma unroll
;             for (int pb = 0; pb < 2; ++pb)
; #pragma unroll
;                 for (int q4 = 0; q4 < 4; ++q4) {
;                     const int chn = hh * 64 + 32 * pb + 8 * q4 + 4 * hi;
;                     const u32x2 zw = *(const u32x2*)(Z + (size_t)tg * DI + chn);
;                     const float a0 = yv[it][pb][4 * q4] * silu_f(bf_lo(zw.x)), a1 = yv[it][pb][4 * q4 + 1] * silu_f(bf_hi(zw.x)), a2 = yv[it][pb][4 * q4 + 2] * silu_f(bf_lo(zw.y)), a3 = yv[it][pb][4 * q4 + 3] * silu_f(bf_hi(zw.y));
;                     sq += (a0 * a0 + a1 * a1) + (a2 * a2 + a3 * a3);
;                     yv[it][pb][4 * q4] = a0; yv[it][pb][4 * q4 + 1] = a1; yv[it][pb][4 * q4 + 2] = a2; yv[it][pb][4 * q4 + 3] = a3;
;                 }
	v_sub_f32_e32 v32, v155, v32
	v_sub_f32_e32 v33, v155, v33
	v_min_f32_e32 v32, 0, v32
	v_min_f32_e32 v33, 0, v33
	v_mul_f32_e32 v32, 0x3fb8aa3b, v32
	v_mul_f32_e32 v33, 0x3fb8aa3b, v33
	v_exp_f32_e32 v32, v32
	v_exp_f32_e32 v33, v33
	v_mul_f32_e32 v32, v44, v32
	v_mul_f32_e32 v33, v45, v33
	v_mul_f32_e32 v32, v36, v32
	v_mul_f32_e32 v37, v37, v33
	v_add_u32_e32 v36, 21, v159
	v_cndmask_b32_e64 v33, 0, v32, s[0:1]
	v_cndmask_b32_e32 v32, 0, v37, vcc
	v_cmp_eq_u32_e32 vcc, v178, v92
	v_cmp_eq_u32_e64 s[0:1], v36, v91
	v_pk_add_f32 v[36:37], v[132:133], v[32:33]
	s_nop 0
	v_cndmask_b32_e64 v44, v32, v36, s[0:1]
	v_cndmask_b32_e32 v45, v33, v37, vcc
	v_sub_f32_e32 v32, v155, v34
	v_sub_f32_e32 v33, v155, v35
	v_min_f32_e32 v32, 0, v32
	v_min_f32_e32 v33, 0, v33
	v_mul_f32_e32 v32, 0x3fb8aa3b, v32
	v_mul_f32_e32 v33, 0x3fb8aa3b, v33
	v_exp_f32_e32 v32, v32
	v_exp_f32_e32 v33, v33
	v_or_b32_e32 v34, 3, v178
	v_or_b32_e32 v35, 2, v178
	v_cmp_le_u32_e32 vcc, v34, v91
	v_pk_mul_f32 v[32:33], v[46:47], v[32:33]
	v_cmp_eq_u32_e64 s[0:1], v34, v91
	v_pk_mul_f32 v[32:33], v[38:39], v[32:33]
	v_cvt_pk_bf16_f32 v36, v165, v164
	v_cndmask_b32_e32 v33, 0, v33, vcc
	v_cmp_le_u32_e32 vcc, v35, v92
	v_cvt_pk_bf16_f32 v37, v167, v166
	v_cvt_pk_bf16_f32 v38, v161, v160
	v_cndmask_b32_e32 v32, 0, v32, vcc
	v_cmp_eq_u32_e32 vcc, v35, v92
	v_pk_add_f32 v[34:35], v[132:133], v[32:33]
	v_cvt_pk_bf16_f32 v39, v163, v162
	v_cndmask_b32_e32 v46, v32, v34, vcc
	v_cvt_pk_bf16_f32 v34, v45, v44
	v_add_u32_e32 v44, 0, v158
	v_cvt_pk_bf16_f32 v32, v41, v40
	v_add_u32_e32 v40, 0x11000, v44
	v_cndmask_b32_e64 v35, v33, v35, s[0:1]
	v_cvt_pk_bf16_f32 v33, v43, v42
	ds_read_b128 v[40:43], v40
	s_waitcnt lgkmcnt(0)
	v_mfma_f32_32x32x16_bf16 v[16:31], v[40:43], v[36:39], v[16:31]
	v_add_u32_e32 v40, 0x11020, v44
	ds_read_b128 v[40:43], v40
	v_cvt_pk_bf16_f32 v35, v46, v35
	s_add_i32 s0, s19, s7
	v_add_u32_e32 v158, 64, v158
	s_cmp_lg_u32 s0, 0
	s_waitcnt lgkmcnt(0)
	v_mfma_f32_32x32x16_bf16 v[16:31], v[40:43], v[32:35], v[16:31]
	v_add_u32_e32 v40, 0x13200, v44
	ds_read_b128 v[40:43], v40
	s_waitcnt lgkmcnt(0)
	v_mfma_f32_32x32x16_bf16 v[0:15], v[40:43], v[36:39], v[0:15]
	v_add_u32_e32 v36, 0x13220, v44
	ds_read_b128 v[36:39], v36
	s_waitcnt lgkmcnt(0)
	v_mfma_f32_32x32x16_bf16 v[0:15], v[36:39], v[32:35], v[0:15]
	s_cbranch_scc1 .LBB0_769
	v_or_b32_e32 v32, s42, v92
	v_ashrrev_i32_e32 v33, 31, v32
	v_lshl_or_b32 v34, s6, 6, v138
	v_lshlrev_b64 v[32:33], 12, v[32:33]
	v_lshl_add_u64 v[32:33], s[56:57], 0, v[32:33]
	v_ashrrev_i32_e32 v35, 31, v34
	v_lshl_add_u64 v[46:47], v[34:35], 1, v[32:33]
	global_load_dwordx2 v[206:207], v[46:47], off
	global_load_dwordx2 v[208:209], v[46:47], off offset:16
	global_load_dwordx2 v[210:211], v[46:47], off offset:32
	global_load_dwordx2 v[212:213], v[46:47], off offset:48
	global_load_dwordx2 v[214:215], v[46:47], off offset:64
	global_load_dwordx2 v[216:217], v[46:47], off offset:80
	global_load_dwordx2 v[218:219], v[46:47], off offset:96
	global_load_dwordx2 v[220:221], v[46:47], off offset:112
	s_waitcnt vmcnt(7)
	v_mov_b32_e32 v34, v206
	v_mov_b32_e32 v35, v207
	v_lshlrev_b32_e32 v38, 16, v34
	v_and_b32_e32 v34, 0xffff0000, v34
	v_mul_f32_e32 v36, 0xbfb8aa3b, v38
	v_mul_f32_e32 v37, 0xbfb8aa3b, v34
	v_exp_f32_e32 v36, v36
	v_exp_f32_e32 v37, v37
	s_nop 0
	v_pk_add_f32 v[36:37], v[36:37], 1.0 op_sel_hi:[1,0]
	s_nop 0
	v_rcp_f32_e32 v40, v37
	s_nop 0
	v_mul_f32_e32 v37, v34, v40
	v_rcp_f32_e32 v39, v36
	s_nop 0
	v_mul_f32_e32 v36, v38, v39
	v_pk_mul_f32 v[16:17], v[16:17], v[36:37]
	v_lshlrev_b32_e32 v36, 16, v35
	v_and_b32_e32 v37, 0xffff0000, v35
	v_mul_f32_e32 v34, 0xbfb8aa3b, v36
	v_mul_f32_e32 v35, 0xbfb8aa3b, v37
	v_exp_f32_e32 v34, v34
	v_exp_f32_e32 v35, v35
	s_nop 0
	v_pk_add_f32 v[34:35], v[34:35], 1.0 op_sel_hi:[1,0]
	s_nop 0
	v_rcp_f32_e32 v39, v35
	s_nop 0
	v_mul_f32_e32 v35, v37, v39
	v_rcp_f32_e32 v38, v34
	s_nop 0
	v_mul_f32_e32 v34, v36, v38
	v_pk_mul_f32 v[18:19], v[18:19], v[34:35]
	v_pk_mul_f32 v[34:35], v[16:17], v[16:17]
	v_pk_mul_f32 v[36:37], v[18:19], v[18:19]
	v_add_f32_e32 v34, v34, v35
	v_add_f32_e32 v36, v36, v37
	v_add_f32_e32 v34, v34, v36
	s_waitcnt vmcnt(6)
	v_mov_b32_e32 v38, v208
	v_mov_b32_e32 v39, v209
	v_lshlrev_b32_e32 v42, 16, v38
	v_and_b32_e32 v38, 0xffff0000, v38
	v_mul_f32_e32 v40, 0xbfb8aa3b, v42
	v_mul_f32_e32 v41, 0xbfb8aa3b, v38
	v_exp_f32_e32 v40, v40
	v_exp_f32_e32 v41, v41
	s_nop 0
	v_pk_add_f32 v[40:41], v[40:41], 1.0 op_sel_hi:[1,0]
	s_nop 0
	v_rcp_f32_e32 v44, v41
	s_nop 0
	v_mul_f32_e32 v41, v38, v44
	v_rcp_f32_e32 v43, v40
	s_nop 0
	v_mul_f32_e32 v40, v42, v43
	v_pk_mul_f32 v[20:21], v[20:21], v[40:41]
	v_lshlrev_b32_e32 v40, 16, v39
	v_and_b32_e32 v41, 0xffff0000, v39
	v_mul_f32_e32 v38, 0xbfb8aa3b, v40
	v_mul_f32_e32 v39, 0xbfb8aa3b, v41
	v_exp_f32_e32 v38, v38
	v_exp_f32_e32 v39, v39
	s_nop 0
	v_pk_add_f32 v[38:39], v[38:39], 1.0 op_sel_hi:[1,0]
	s_nop 0
	v_rcp_f32_e32 v43, v39
	s_nop 0
	v_mul_f32_e32 v39, v41, v43
	v_rcp_f32_e32 v42, v38
	s_nop 0
	v_mul_f32_e32 v38, v40, v42
	v_pk_mul_f32 v[22:23], v[22:23], v[38:39]
	v_pk_mul_f32 v[38:39], v[20:21], v[20:21]
	v_pk_mul_f32 v[40:41], v[22:23], v[22:23]
	v_add_f32_e32 v38, v38, v39
	v_add_f32_e32 v40, v40, v41
	v_add_f32_e32 v38, v38, v40
	v_add_f32_e32 v34, v34, v38
	s_waitcnt vmcnt(5)
; DI_ float bf_lo(unsigned w) { return __uint_as_float(w << 16); }
; DI_ float bf_hi(unsigned w) { return __uint_as_float(w & 0xffff0000u); }
; DI_ float silu_f(float v) { return v / (1.f + __expf(-v)); }
; DI_ void ssd_passC(const bf16_t* xsT, const bf16_t* Btok, const bf16_t* Ctok, const bf16_t* Sc, const float* dt, const float* acum, const float* Dskip, const float* norm_w, bf16_t* Z, unsigned char* lds, int tid, int lane, int wid) {
;     ...
;             const int tg = t0 + tl; float sq = 0.f;
; #pragma unroll
;             for (int pb = 0; pb < 2; ++pb)
; #pragma unroll
;                 for (int q4 = 0; q4 < 4; ++q4) {
;                     const int chn = hh * 64 + 32 * pb + 8 * q4 + 4 * hi;
;                     const u32x2 zw = *(const u32x2*)(Z + (size_t)tg * DI + chn);
;                     const float a0 = yv[it][pb][4 * q4] * silu_f(bf_lo(zw.x)), a1 = yv[it][pb][4 * q4 + 1] * silu_f(bf_hi(zw.x)), a2 = yv[it][pb][4 * q4 + 2] * silu_f(bf_lo(zw.y)), a3 = yv[it][pb][4 * q4 + 3] * silu_f(bf_hi(zw.y));
;                     sq += (a0 * a0 + a1 * a1) + (a2 * a2 + a3 * a3);
;                     yv[it][pb][4 * q4] = a0; yv[it][pb][4 * q4 + 1] = a1; yv[it][pb][4 * q4 + 2] = a2; yv[it][pb][4 * q4 + 3] = a3;
;                 }
;             sq += __shfl_xor(sq, 32);
;             if (hi == 0) ex[hl * 128 + tl] = sq;
;             ssq[it] = sq;
	v_mov_b32_e32 v42, v210
	v_mov_b32_e32 v43, v211
	v_lshlrev_b32_e32 v50, 16, v42
	v_and_b32_e32 v42, 0xffff0000, v42
	v_mul_f32_e32 v44, 0xbfb8aa3b, v50
	v_mul_f32_e32 v45, 0xbfb8aa3b, v42
	v_exp_f32_e32 v44, v44
	v_exp_f32_e32 v45, v45
	s_nop 0
	v_pk_add_f32 v[44:45], v[44:45], 1.0 op_sel_hi:[1,0]
	s_nop 0
	v_rcp_f32_e32 v52, v45
	s_nop 0
	v_mul_f32_e32 v45, v42, v52
	v_rcp_f32_e32 v51, v44
	s_nop 0
	v_mul_f32_e32 v44, v50, v51
	v_pk_mul_f32 v[24:25], v[24:25], v[44:45]
	v_lshlrev_b32_e32 v44, 16, v43
	v_and_b32_e32 v45, 0xffff0000, v43
	v_mul_f32_e32 v42, 0xbfb8aa3b, v44
	v_mul_f32_e32 v43, 0xbfb8aa3b, v45
	v_exp_f32_e32 v42, v42
	v_exp_f32_e32 v43, v43
	s_nop 0
	v_pk_add_f32 v[42:43], v[42:43], 1.0 op_sel_hi:[1,0]
	s_nop 0
	v_rcp_f32_e32 v51, v43
	s_nop 0
	v_mul_f32_e32 v43, v45, v51
	v_rcp_f32_e32 v50, v42
	s_nop 0
	v_mul_f32_e32 v42, v44, v50
	v_pk_mul_f32 v[26:27], v[26:27], v[42:43]
	v_pk_mul_f32 v[42:43], v[24:25], v[24:25]
	v_pk_mul_f32 v[44:45], v[26:27], v[26:27]
	v_add_f32_e32 v36, v42, v43
	v_add_f32_e32 v35, v44, v45
	v_add_f32_e32 v35, v36, v35
	v_add_f32_e32 v34, v34, v35
	s_waitcnt vmcnt(4)
	v_mov_b32_e32 v50, v212
	v_mov_b32_e32 v51, v213
	v_lshlrev_b32_e32 v54, 16, v50
	v_and_b32_e32 v50, 0xffff0000, v50
	v_mul_f32_e32 v52, 0xbfb8aa3b, v54
	v_mul_f32_e32 v53, 0xbfb8aa3b, v50
	v_exp_f32_e32 v52, v52
	v_exp_f32_e32 v53, v53
	s_nop 0
	v_pk_add_f32 v[52:53], v[52:53], 1.0 op_sel_hi:[1,0]
	s_nop 0
	v_rcp_f32_e32 v56, v53
	s_nop 0
	v_mul_f32_e32 v53, v50, v56
	v_rcp_f32_e32 v55, v52
	s_nop 0
	v_mul_f32_e32 v52, v54, v55
	v_pk_mul_f32 v[28:29], v[28:29], v[52:53]
	v_lshlrev_b32_e32 v52, 16, v51
	v_and_b32_e32 v53, 0xffff0000, v51
	v_mul_f32_e32 v50, 0xbfb8aa3b, v52
	v_mul_f32_e32 v51, 0xbfb8aa3b, v53
	v_exp_f32_e32 v50, v50
	v_exp_f32_e32 v51, v51
	s_nop 0
	v_pk_add_f32 v[50:51], v[50:51], 1.0 op_sel_hi:[1,0]
	s_nop 0
	v_rcp_f32_e32 v55, v51
	s_nop 0
	v_mul_f32_e32 v51, v53, v55
	v_rcp_f32_e32 v54, v50
	s_nop 0
	v_mul_f32_e32 v50, v52, v54
	v_pk_mul_f32 v[30:31], v[30:31], v[50:51]
	v_pk_mul_f32 v[50:51], v[28:29], v[28:29]
	v_pk_mul_f32 v[52:53], v[30:31], v[30:31]
	v_add_f32_e32 v36, v50, v51
	v_add_f32_e32 v35, v52, v53
	v_add_f32_e32 v35, v36, v35
	v_add_f32_e32 v34, v34, v35
	s_waitcnt vmcnt(3)
	v_mov_b32_e32 v54, v214
	v_mov_b32_e32 v55, v215
	v_lshlrev_b32_e32 v58, 16, v54
	v_and_b32_e32 v54, 0xffff0000, v54
	v_mul_f32_e32 v56, 0xbfb8aa3b, v58
	v_mul_f32_e32 v57, 0xbfb8aa3b, v54
	v_exp_f32_e32 v56, v56
	v_exp_f32_e32 v57, v57
	s_nop 0
	v_pk_add_f32 v[56:57], v[56:57], 1.0 op_sel_hi:[1,0]
	s_nop 0
	v_rcp_f32_e32 v60, v57
	s_nop 0
	v_mul_f32_e32 v57, v54, v60
	v_rcp_f32_e32 v59, v56
	s_nop 0
	v_mul_f32_e32 v56, v58, v59
	v_pk_mul_f32 v[0:1], v[0:1], v[56:57]
	v_lshlrev_b32_e32 v56, 16, v55
	v_and_b32_e32 v57, 0xffff0000, v55
	v_mul_f32_e32 v54, 0xbfb8aa3b, v56
	v_mul_f32_e32 v55, 0xbfb8aa3b, v57
	v_exp_f32_e32 v54, v54
	v_exp_f32_e32 v55, v55
	s_nop 0
	v_pk_add_f32 v[54:55], v[54:55], 1.0 op_sel_hi:[1,0]
	s_nop 0
	v_rcp_f32_e32 v59, v55
	s_nop 0
	v_mul_f32_e32 v55, v57, v59
	v_rcp_f32_e32 v58, v54
	s_nop 0
	v_mul_f32_e32 v54, v56, v58
	v_pk_mul_f32 v[2:3], v[2:3], v[54:55]
	v_pk_mul_f32 v[54:55], v[0:1], v[0:1]
	v_pk_mul_f32 v[56:57], v[2:3], v[2:3]
	v_add_f32_e32 v36, v54, v55
	v_add_f32_e32 v35, v56, v57
	v_add_f32_e32 v35, v36, v35
	v_add_f32_e32 v34, v34, v35
	s_waitcnt vmcnt(2)
	v_mov_b32_e32 v58, v216
	v_mov_b32_e32 v59, v217
	v_lshlrev_b32_e32 v62, 16, v58
	v_and_b32_e32 v58, 0xffff0000, v58
	v_mul_f32_e32 v60, 0xbfb8aa3b, v62
	v_mul_f32_e32 v61, 0xbfb8aa3b, v58
	v_exp_f32_e32 v60, v60
	v_exp_f32_e32 v61, v61
	s_nop 0
	v_pk_add_f32 v[60:61], v[60:61], 1.0 op_sel_hi:[1,0]
	s_nop 0
	v_rcp_f32_e32 v64, v61
	s_nop 0
	v_mul_f32_e32 v61, v58, v64
	v_rcp_f32_e32 v63, v60
	s_nop 0
	v_mul_f32_e32 v60, v62, v63
	v_pk_mul_f32 v[4:5], v[4:5], v[60:61]
	v_lshlrev_b32_e32 v60, 16, v59
	v_and_b32_e32 v61, 0xffff0000, v59
	v_mul_f32_e32 v58, 0xbfb8aa3b, v60
	v_mul_f32_e32 v59, 0xbfb8aa3b, v61
	v_exp_f32_e32 v58, v58
	v_exp_f32_e32 v59, v59
	s_nop 0
	v_pk_add_f32 v[58:59], v[58:59], 1.0 op_sel_hi:[1,0]
	s_nop 0
	v_rcp_f32_e32 v63, v59
	s_nop 0
	v_mul_f32_e32 v59, v61, v63
	v_rcp_f32_e32 v62, v58
	s_nop 0
	v_mul_f32_e32 v58, v60, v62
	v_pk_mul_f32 v[6:7], v[6:7], v[58:59]
	v_pk_mul_f32 v[58:59], v[4:5], v[4:5]
	v_pk_mul_f32 v[60:61], v[6:7], v[6:7]
	v_add_f32_e32 v36, v58, v59
	v_add_f32_e32 v35, v60, v61
	v_add_f32_e32 v35, v36, v35
	v_add_f32_e32 v34, v34, v35
	s_waitcnt vmcnt(1)
	v_mov_b32_e32 v62, v218
	v_mov_b32_e32 v63, v219
	v_lshlrev_b32_e32 v66, 16, v62
	v_and_b32_e32 v62, 0xffff0000, v62
	v_mul_f32_e32 v64, 0xbfb8aa3b, v66
	v_mul_f32_e32 v65, 0xbfb8aa3b, v62
	v_exp_f32_e32 v64, v64
	v_exp_f32_e32 v65, v65
	s_nop 0
	v_pk_add_f32 v[64:65], v[64:65], 1.0 op_sel_hi:[1,0]
	s_nop 0
	v_rcp_f32_e32 v68, v65
	s_nop 0
	v_mul_f32_e32 v65, v62, v68
	v_rcp_f32_e32 v67, v64
	s_nop 0
	v_mul_f32_e32 v64, v66, v67
	v_pk_mul_f32 v[8:9], v[8:9], v[64:65]
	v_lshlrev_b32_e32 v64, 16, v63
	v_and_b32_e32 v65, 0xffff0000, v63
	v_mul_f32_e32 v62, 0xbfb8aa3b, v64
	v_mul_f32_e32 v63, 0xbfb8aa3b, v65
	v_exp_f32_e32 v62, v62
	v_exp_f32_e32 v63, v63
	s_nop 0
	v_pk_add_f32 v[62:63], v[62:63], 1.0 op_sel_hi:[1,0]
	s_nop 0
	v_rcp_f32_e32 v67, v63
	s_nop 0
	v_mul_f32_e32 v63, v65, v67
	v_rcp_f32_e32 v66, v62
	s_nop 0
	v_mul_f32_e32 v68, v64, v66
	v_mov_b32_e32 v65, v68
	s_waitcnt vmcnt(0)
	v_mov_b32_e32 v46, v220
	v_mov_b32_e32 v47, v221
	v_lshlrev_b32_e32 v68, 16, v46
	v_and_b32_e32 v46, 0xffff0000, v46
	v_mul_f32_e32 v66, 0xbfb8aa3b, v68
	v_mul_f32_e32 v67, 0xbfb8aa3b, v46
	v_exp_f32_e32 v66, v66
	v_exp_f32_e32 v67, v67
	v_mov_b32_e32 v62, v65
	v_pk_mul_f32 v[10:11], v[10:11], v[62:63]
	v_pk_mul_f32 v[62:63], v[8:9], v[8:9]
	v_pk_add_f32 v[66:67], v[66:67], 1.0 op_sel_hi:[1,0]
	v_pk_mul_f32 v[64:65], v[10:11], v[10:11]
	v_rcp_f32_e32 v70, v67
	v_add_f32_e32 v35, v64, v65
	v_add_f32_e32 v36, v62, v63
	v_add_f32_e32 v35, v36, v35
	v_mul_f32_e32 v67, v46, v70
	v_rcp_f32_e32 v69, v66
	v_add_f32_e32 v34, v34, v35
	v_mul_f32_e32 v66, v68, v69
	v_pk_mul_f32 v[12:13], v[12:13], v[66:67]
	v_lshlrev_b32_e32 v66, 16, v47
	v_and_b32_e32 v67, 0xffff0000, v47
	v_mul_f32_e32 v46, 0xbfb8aa3b, v66
	v_mul_f32_e32 v47, 0xbfb8aa3b, v67
	v_exp_f32_e32 v46, v46
	v_exp_f32_e32 v47, v47
	s_nop 0
	v_pk_add_f32 v[46:47], v[46:47], 1.0 op_sel_hi:[1,0]
	s_nop 0
	v_rcp_f32_e32 v69, v47
	s_nop 0
	v_mul_f32_e32 v47, v67, v69
	v_rcp_f32_e32 v68, v46
	s_nop 0
	v_mul_f32_e32 v46, v66, v68
	v_pk_mul_f32 v[14:15], v[14:15], v[46:47]
	v_pk_mul_f32 v[46:47], v[12:13], v[12:13]
	v_pk_mul_f32 v[66:67], v[14:15], v[14:15]
	v_add_f32_e32 v36, v46, v47
	v_add_f32_e32 v35, v66, v67
	v_add_f32_e32 v35, v36, v35
	v_add_f32_e32 v34, v34, v35
	ds_bpermute_b32 v35, v139, v34
	s_and_saveexec_b64 s[0:1], s[40:41]
	s_cbranch_execz .LBB0_763
	s_waitcnt lgkmcnt(0)
	v_add_f32_e32 v34, v34, v35
	ds_write_b32 v143, v34
	s_branch .LBB0_763

; __device__ __forceinline__ unsigned cvt_pk_bf16(float lo, float hi) { unsigned r; asm volatile("v_cvt_pk_bf16_f32 %0, %1, %2" : "=v"(r) : "v"(lo), "v"(hi)); return r; }
;     __device__ __forceinline__ void operator()(const f32x4 (&acc)[2][2][4][2], const Unit& u, int wr, int wc, int fr, int fq) const {
;         const int col0 = u.pn * BM + wc * 32 + 8 * fq;
; #pragma unroll
;         for (int bj = 0; bj < 2; ++bj) { const f32x4 b0 = *(const f32x4*)(bg + col0 + bj * HALF), b1 = *(const f32x4*)(bg + col0 + bj * HALF + 4);
; #pragma unroll
;             for (int ai = 0; ai < 2; ++ai)
; #pragma unroll
;                 for (int m = 0; m < 4; ++m) { const size_t off = (size_t)(u.pm * BM + ai * HALF + wr * 64 + m * 16 + fr) * ldc + col0 + bj * HALF;
;                     const u32x4 xr = *(const u32x4*)(XB + off), pr = *(const u32x4*)(Pp + off); const f32x4 a0 = acc[ai][bj][m][0] + b0, a1 = acc[ai][bj][m][1] + b1;
;                     float x[8], p[8], o[8];
; #pragma unroll
;                     for (int e = 0; e < 4; ++e) { x[2 * e] = __uint_as_float(xr[e] << 16); x[2 * e + 1] = __uint_as_float(xr[e] & 0xffff0000u); p[2 * e] = __uint_as_float(pr[e] << 16); p[2 * e + 1] = __uint_as_float(pr[e] & 0xffff0000u); }
; #pragma unroll
;                     for (int e = 0; e < 4; ++e) { o[e] = x[e] + p[e] / (1.0f + __expf(-a0[e])); o[4 + e] = x[4 + e] + p[4 + e] / (1.0f + __expf(-a1[e])); }
;                     if (OutF) { *(f32x4*)(OutF + off) = (f32x4){o[0], o[1], o[2], o[3]}; *(f32x4*)(OutF + off + 4) = (f32x4){o[4], o[5], o[6], o[7]}; }
;                     else { u32x4 w; w.x = cvt_pk_bf16(o[0], o[1]); w.y = cvt_pk_bf16(o[2], o[3]); w.z = cvt_pk_bf16(o[4], o[5]); w.w = cvt_pk_bf16(o[6], o[7]); *(u32x4*)(XBout + off) = w; } } }
.LBB0_1246:
	v_lshl_or_b32 v158, s26, 8, v178
	v_ashrrev_i32_e32 v159, 31, v158
	v_lshl_add_u64 v[160:161], v[158:159], 2, s[86:87]
	v_lshl_add_u32 v164, s27, 8, v49
	global_load_dwordx4 v[74:77], v[160:161], off offset:16
	global_load_dwordx4 v[82:85], v[160:161], off
	v_ashrrev_i32_e32 v165, 31, v164
	v_lshlrev_b64 v[162:163], 10, v[164:165]
	v_lshl_add_u64 v[166:167], v[162:163], 0, v[158:159]
	v_lshlrev_b64 v[138:139], 1, v[166:167]
	v_lshl_add_u64 v[140:141], s[36:37], 0, v[138:139]
	v_lshl_add_u64 v[138:139], s[60:61], 0, v[138:139]
	global_load_dwordx4 v[142:145], v[140:141], off
	v_readlane_b32 s28, v254, 32
	global_load_dwordx4 v[138:141], v[138:139], off
	v_readlane_b32 s29, v254, 33
	v_readlane_b32 s30, v254, 42
	v_readlane_b32 s31, v254, 43
	s_waitcnt vmcnt(0)
	v_add_f32_e32 v130, v130, v74
	v_add_f32_e32 v134, v134, v82
	v_add_f32_e32 v135, v135, v83
	v_mul_f32_e32 v134, 0xbfb8aa3b, v134
	v_mul_f32_e32 v135, 0xbfb8aa3b, v135
	v_exp_f32_e32 v134, v134
	v_exp_f32_e32 v135, v135
	v_add_f32_e32 v131, v131, v75
	v_lshlrev_b32_e32 v180, 16, v142
	v_and_b32_e32 v181, 0xffff0000, v142
	v_lshlrev_b32_e32 v142, 16, v138
	v_and_b32_e32 v138, 0xffff0000, v138
	v_pk_add_f32 v[134:135], v[134:135], 1.0 op_sel_hi:[1,0]
	v_mul_f32_e32 v130, 0xbfb8aa3b, v130
	v_rcp_f32_e32 v182, v135
	v_mul_f32_e32 v131, 0xbfb8aa3b, v131
	v_exp_f32_e32 v130, v130
	v_exp_f32_e32 v131, v131
	v_mul_f32_e32 v135, v138, v182
	v_rcp_f32_e32 v165, v134
	v_pk_add_f32 v[130:131], v[130:131], 1.0 op_sel_hi:[1,0]
	v_add_f32_e32 v136, v136, v84
	v_mul_f32_e32 v136, 0xbfb8aa3b, v136
	v_mul_f32_e32 v134, v142, v165
	v_lshlrev_b32_e32 v138, 16, v140
	v_and_b32_e32 v140, 0xffff0000, v140
	v_pk_add_f32 v[134:135], v[134:135], v[180:181]
	v_lshlrev_b32_e32 v180, 16, v144
	v_and_b32_e32 v181, 0xffff0000, v144
	v_rcp_f32_e32 v144, v131
	v_add_f32_e32 v132, v132, v76
	v_add_f32_e32 v133, v133, v77
	v_mul_f32_e32 v132, 0xbfb8aa3b, v132
	v_mul_f32_e32 v131, v140, v144
	v_rcp_f32_e32 v142, v130
	v_mul_f32_e32 v133, 0xbfb8aa3b, v133
	v_exp_f32_e32 v132, v132
	v_exp_f32_e32 v133, v133
	v_mul_f32_e32 v130, v138, v142
	v_pk_add_f32 v[130:131], v[130:131], v[180:181]
	v_exp_f32_e32 v180, v136
	v_add_f32_e32 v136, v137, v85
	v_mul_f32_e32 v136, 0xbfb8aa3b, v136
	v_exp_f32_e32 v181, v136
	v_lshlrev_b32_e32 v140, 16, v139
	v_and_b32_e32 v142, 0xffff0000, v139
	v_lshlrev_b32_e32 v136, 16, v143
	v_pk_add_f32 v[138:139], v[180:181], 1.0 op_sel_hi:[1,0]
	v_and_b32_e32 v137, 0xffff0000, v143
	v_rcp_f32_e32 v144, v139
	v_pk_add_f32 v[132:133], v[132:133], 1.0 op_sel_hi:[1,0]
	v_mul_f32_e32 v139, v142, v144
	v_rcp_f32_e32 v143, v138
	s_nop 0
	v_mul_f32_e32 v138, v140, v143
	v_lshlrev_b32_e32 v140, 16, v141
	v_and_b32_e32 v141, 0xffff0000, v141
	v_rcp_f32_e32 v143, v133
	v_pk_add_f32 v[136:137], v[138:139], v[136:137]
	v_lshlrev_b32_e32 v138, 16, v145
	v_and_b32_e32 v139, 0xffff0000, v145
	v_mul_f32_e32 v133, v141, v143
	v_rcp_f32_e32 v142, v132
	s_nop 0
	v_mul_f32_e32 v132, v140, v142
	v_pk_add_f32 v[132:133], v[132:133], v[138:139]
	v_cndmask_b32_e64 v138, 0, 1, s[50:51]
	v_cmp_ne_u32_e64 s[40:41], 1, v138
	s_andn2_b64 vcc, exec, s[50:51]
	v_lshl_add_u64 v[138:139], v[166:167], 2, s[44:45]
	s_cbranch_vccnz .LBB0_1293
	global_store_dwordx4 v[138:139], v[134:137], off
	global_store_dwordx4 v[138:139], v[130:133], off offset:16
	s_cbranch_execnz .LBB0_1249

; __device__ __forceinline__ unsigned cvt_pk_bf16(float lo, float hi) { unsigned r; asm volatile("v_cvt_pk_bf16_f32 %0, %1, %2" : "=v"(r) : "v"(lo), "v"(hi)); return r; }
;     __device__ __forceinline__ void operator()(const f32x4 (&acc)[2][2][4][2], const Unit& u, int wr, int wc, int fr, int fq) const {
;     ...
;                 for (int m = 0; m < 4; ++m) { const size_t off = (size_t)(u.pm * BM + ai * HALF + wr * 64 + m * 16 + fr) * ldc + col0 + bj * HALF;
;                     const u32x4 xr = *(const u32x4*)(XB + off), pr = *(const u32x4*)(Pp + off); const f32x4 a0 = acc[ai][bj][m][0] + b0, a1 = acc[ai][bj][m][1] + b1;
;                     float x[8], p[8], o[8];
; #pragma unroll
;                     for (int e = 0; e < 4; ++e) { x[2 * e] = __uint_as_float(xr[e] << 16); x[2 * e + 1] = __uint_as_float(xr[e] & 0xffff0000u); p[2 * e] = __uint_as_float(pr[e] << 16); p[2 * e + 1] = __uint_as_float(pr[e] & 0xffff0000u); }
; #pragma unroll
;                     for (int e = 0; e < 4; ++e) { o[e] = x[e] + p[e] / (1.0f + __expf(-a0[e])); o[4 + e] = x[4 + e] + p[4 + e] / (1.0f + __expf(-a1[e])); }
;                     if (OutF) { *(f32x4*)(OutF + off) = (f32x4){o[0], o[1], o[2], o[3]}; *(f32x4*)(OutF + off + 4) = (f32x4){o[4], o[5], o[6], o[7]}; }
;                     else { u32x4 w; w.x = cvt_pk_bf16(o[0], o[1]); w.y = cvt_pk_bf16(o[2], o[3]); w.z = cvt_pk_bf16(o[4], o[5]); w.w = cvt_pk_bf16(o[6], o[7]); *(u32x4*)(XBout + off) = w; } } }
.LBB0_1249:
	s_nop 0
	v_or_b32_e32 v130, 16, v164
	v_ashrrev_i32_e32 v131, 31, v130
	v_lshlrev_b64 v[140:141], 10, v[130:131]
	v_lshl_add_u64 v[142:143], v[140:141], 0, v[158:159]
	v_lshlrev_b64 v[130:131], 1, v[142:143]
	v_lshl_add_u64 v[132:133], s[36:37], 0, v[130:131]
	v_lshl_add_u64 v[130:131], s[60:61], 0, v[130:131]
	global_load_dwordx4 v[134:137], v[132:133], off
	v_add_f32_e32 v126, v126, v82
	global_load_dwordx4 v[130:133], v[130:131], off
	v_add_f32_e32 v127, v127, v83
	v_mul_f32_e32 v126, 0xbfb8aa3b, v126
	v_mul_f32_e32 v127, 0xbfb8aa3b, v127
	v_exp_f32_e32 v126, v126
	v_exp_f32_e32 v127, v127
	v_add_f32_e32 v122, v122, v74
	v_add_f32_e32 v123, v123, v75
	v_mul_f32_e32 v122, 0xbfb8aa3b, v122
	v_pk_add_f32 v[126:127], v[126:127], 1.0 op_sel_hi:[1,0]
	v_mul_f32_e32 v123, 0xbfb8aa3b, v123
	v_exp_f32_e32 v122, v122
	v_exp_f32_e32 v123, v123
	v_add_f32_e32 v128, v128, v84
	v_mul_f32_e32 v128, 0xbfb8aa3b, v128
	v_add_f32_e32 v124, v124, v76
	v_pk_add_f32 v[122:123], v[122:123], 1.0 op_sel_hi:[1,0]
	v_add_f32_e32 v125, v125, v77
	v_mul_f32_e32 v124, 0xbfb8aa3b, v124
	v_mul_f32_e32 v125, 0xbfb8aa3b, v125
	v_exp_f32_e32 v124, v124
	v_exp_f32_e32 v125, v125
	s_waitcnt vmcnt(1)
	v_lshlrev_b32_e32 v144, 16, v134
	v_and_b32_e32 v145, 0xffff0000, v134
	s_waitcnt vmcnt(0)
	v_lshlrev_b32_e32 v134, 16, v130
	v_and_b32_e32 v130, 0xffff0000, v130
	v_rcp_f32_e32 v166, v127
	v_pk_add_f32 v[124:125], v[124:125], 1.0 op_sel_hi:[1,0]
	v_mul_f32_e32 v127, v130, v166
	v_rcp_f32_e32 v165, v126
	s_nop 0
	v_mul_f32_e32 v126, v134, v165
	v_lshlrev_b32_e32 v130, 16, v132
	v_and_b32_e32 v132, 0xffff0000, v132
	v_pk_add_f32 v[126:127], v[126:127], v[144:145]
	v_lshlrev_b32_e32 v144, 16, v136
	v_and_b32_e32 v145, 0xffff0000, v136
	v_rcp_f32_e32 v136, v123
	s_nop 0
	v_mul_f32_e32 v123, v132, v136
	v_rcp_f32_e32 v134, v122
	s_nop 0
	v_mul_f32_e32 v122, v130, v134
	v_pk_add_f32 v[122:123], v[122:123], v[144:145]
	v_exp_f32_e32 v144, v128
	v_add_f32_e32 v128, v129, v85
	v_mul_f32_e32 v128, 0xbfb8aa3b, v128
	v_exp_f32_e32 v145, v128
	v_lshlrev_b32_e32 v132, 16, v131
	v_and_b32_e32 v134, 0xffff0000, v131
	v_lshlrev_b32_e32 v128, 16, v135
	v_pk_add_f32 v[130:131], v[144:145], 1.0 op_sel_hi:[1,0]
	v_and_b32_e32 v129, 0xffff0000, v135
	v_rcp_f32_e32 v136, v131
	s_nop 0
	v_mul_f32_e32 v131, v134, v136
	v_rcp_f32_e32 v135, v130
	s_nop 0
	v_mul_f32_e32 v130, v132, v135
	v_lshlrev_b32_e32 v132, 16, v133
	v_and_b32_e32 v133, 0xffff0000, v133
	v_rcp_f32_e32 v135, v125
	v_pk_add_f32 v[128:129], v[130:131], v[128:129]
	v_lshlrev_b32_e32 v130, 16, v137
	v_and_b32_e32 v131, 0xffff0000, v137
	v_mul_f32_e32 v125, v133, v135
	v_rcp_f32_e32 v134, v124
	s_nop 0
	v_mul_f32_e32 v124, v132, v134
	v_pk_add_f32 v[124:125], v[124:125], v[130:131]
	s_and_b64 vcc, exec, s[40:41]
	v_lshl_add_u64 v[130:131], v[142:143], 2, s[44:45]
	s_cbranch_vccnz .LBB0_1294
	global_store_dwordx4 v[130:131], v[126:129], off
	global_store_dwordx4 v[130:131], v[122:125], off offset:16
	s_cbranch_execnz .LBB0_1252

; __device__ __forceinline__ unsigned cvt_pk_bf16(float lo, float hi) { unsigned r; asm volatile("v_cvt_pk_bf16_f32 %0, %1, %2" : "=v"(r) : "v"(lo), "v"(hi)); return r; }
;     __device__ __forceinline__ void operator()(const f32x4 (&acc)[2][2][4][2], const Unit& u, int wr, int wc, int fr, int fq) const {
;     ...
;                 for (int m = 0; m < 4; ++m) { const size_t off = (size_t)(u.pm * BM + ai * HALF + wr * 64 + m * 16 + fr) * ldc + col0 + bj * HALF;
;                     const u32x4 xr = *(const u32x4*)(XB + off), pr = *(const u32x4*)(Pp + off); const f32x4 a0 = acc[ai][bj][m][0] + b0, a1 = acc[ai][bj][m][1] + b1;
;                     float x[8], p[8], o[8];
; #pragma unroll
;                     for (int e = 0; e < 4; ++e) { x[2 * e] = __uint_as_float(xr[e] << 16); x[2 * e + 1] = __uint_as_float(xr[e] & 0xffff0000u); p[2 * e] = __uint_as_float(pr[e] << 16); p[2 * e + 1] = __uint_as_float(pr[e] & 0xffff0000u); }
; #pragma unroll
;                     for (int e = 0; e < 4; ++e) { o[e] = x[e] + p[e] / (1.0f + __expf(-a0[e])); o[4 + e] = x[4 + e] + p[4 + e] / (1.0f + __expf(-a1[e])); }
;                     if (OutF) { *(f32x4*)(OutF + off) = (f32x4){o[0], o[1], o[2], o[3]}; *(f32x4*)(OutF + off + 4) = (f32x4){o[4], o[5], o[6], o[7]}; }
;                     else { u32x4 w; w.x = cvt_pk_bf16(o[0], o[1]); w.y = cvt_pk_bf16(o[2], o[3]); w.z = cvt_pk_bf16(o[4], o[5]); w.w = cvt_pk_bf16(o[6], o[7]); *(u32x4*)(XBout + off) = w; } } }
.LBB0_1252:
	s_nop 0
	v_or_b32_e32 v122, 32, v164
	v_ashrrev_i32_e32 v123, 31, v122
	v_lshlrev_b64 v[132:133], 10, v[122:123]
	v_lshl_add_u64 v[134:135], v[132:133], 0, v[158:159]
	v_lshlrev_b64 v[122:123], 1, v[134:135]
	v_lshl_add_u64 v[124:125], s[36:37], 0, v[122:123]
	v_lshl_add_u64 v[122:123], s[60:61], 0, v[122:123]
	global_load_dwordx4 v[126:129], v[124:125], off
	v_add_f32_e32 v118, v118, v82
	global_load_dwordx4 v[122:125], v[122:123], off
	v_add_f32_e32 v119, v119, v83
	v_mul_f32_e32 v118, 0xbfb8aa3b, v118
	v_mul_f32_e32 v119, 0xbfb8aa3b, v119
	v_exp_f32_e32 v118, v118
	v_exp_f32_e32 v119, v119
	v_add_f32_e32 v114, v114, v74
	v_add_f32_e32 v115, v115, v75
	v_mul_f32_e32 v114, 0xbfb8aa3b, v114
	v_pk_add_f32 v[118:119], v[118:119], 1.0 op_sel_hi:[1,0]
	v_mul_f32_e32 v115, 0xbfb8aa3b, v115
	v_exp_f32_e32 v114, v114
	v_exp_f32_e32 v115, v115
	v_add_f32_e32 v120, v120, v84
	v_mul_f32_e32 v120, 0xbfb8aa3b, v120
	v_add_f32_e32 v116, v116, v76
	v_pk_add_f32 v[114:115], v[114:115], 1.0 op_sel_hi:[1,0]
	v_add_f32_e32 v117, v117, v77
	v_mul_f32_e32 v116, 0xbfb8aa3b, v116
	v_mul_f32_e32 v117, 0xbfb8aa3b, v117
	v_exp_f32_e32 v116, v116
	v_exp_f32_e32 v117, v117
	s_waitcnt vmcnt(1)
	v_lshlrev_b32_e32 v136, 16, v126
	v_and_b32_e32 v137, 0xffff0000, v126
	s_waitcnt vmcnt(0)
	v_lshlrev_b32_e32 v126, 16, v122
	v_and_b32_e32 v122, 0xffff0000, v122
	v_rcp_f32_e32 v143, v119
	v_pk_add_f32 v[116:117], v[116:117], 1.0 op_sel_hi:[1,0]
	v_mul_f32_e32 v119, v122, v143
	v_rcp_f32_e32 v142, v118
	s_nop 0
	v_mul_f32_e32 v118, v126, v142
	v_lshlrev_b32_e32 v122, 16, v124
	v_and_b32_e32 v124, 0xffff0000, v124
	v_pk_add_f32 v[118:119], v[118:119], v[136:137]
	v_lshlrev_b32_e32 v136, 16, v128
	v_and_b32_e32 v137, 0xffff0000, v128
	v_rcp_f32_e32 v128, v115
	s_nop 0
	v_mul_f32_e32 v115, v124, v128
	v_rcp_f32_e32 v126, v114
	s_nop 0
	v_mul_f32_e32 v114, v122, v126
	v_pk_add_f32 v[114:115], v[114:115], v[136:137]
	v_exp_f32_e32 v136, v120
	v_add_f32_e32 v120, v121, v85
	v_mul_f32_e32 v120, 0xbfb8aa3b, v120
	v_exp_f32_e32 v137, v120
	v_lshlrev_b32_e32 v124, 16, v123
	v_and_b32_e32 v126, 0xffff0000, v123
	v_lshlrev_b32_e32 v120, 16, v127
	v_pk_add_f32 v[122:123], v[136:137], 1.0 op_sel_hi:[1,0]
	v_and_b32_e32 v121, 0xffff0000, v127
	v_rcp_f32_e32 v128, v123
	s_nop 0
	v_mul_f32_e32 v123, v126, v128
	v_rcp_f32_e32 v127, v122
	s_nop 0
	v_mul_f32_e32 v122, v124, v127
	v_lshlrev_b32_e32 v124, 16, v125
	v_and_b32_e32 v125, 0xffff0000, v125
	v_rcp_f32_e32 v127, v117
	v_pk_add_f32 v[120:121], v[122:123], v[120:121]
	v_lshlrev_b32_e32 v122, 16, v129
	v_and_b32_e32 v123, 0xffff0000, v129
	v_mul_f32_e32 v117, v125, v127
	v_rcp_f32_e32 v126, v116
	s_nop 0
	v_mul_f32_e32 v116, v124, v126
	v_pk_add_f32 v[116:117], v[116:117], v[122:123]
	s_and_b64 vcc, exec, s[40:41]
	v_lshl_add_u64 v[122:123], v[134:135], 2, s[44:45]
	s_cbranch_vccnz .LBB0_1295
	global_store_dwordx4 v[122:123], v[118:121], off
	global_store_dwordx4 v[122:123], v[114:117], off offset:16
	s_cbranch_execnz .LBB0_1255

; __device__ __forceinline__ unsigned cvt_pk_bf16(float lo, float hi) { unsigned r; asm volatile("v_cvt_pk_bf16_f32 %0, %1, %2" : "=v"(r) : "v"(lo), "v"(hi)); return r; }
;     __device__ __forceinline__ void operator()(const f32x4 (&acc)[2][2][4][2], const Unit& u, int wr, int wc, int fr, int fq) const {
;     ...
;                 for (int m = 0; m < 4; ++m) { const size_t off = (size_t)(u.pm * BM + ai * HALF + wr * 64 + m * 16 + fr) * ldc + col0 + bj * HALF;
;                     const u32x4 xr = *(const u32x4*)(XB + off), pr = *(const u32x4*)(Pp + off); const f32x4 a0 = acc[ai][bj][m][0] + b0, a1 = acc[ai][bj][m][1] + b1;
;                     float x[8], p[8], o[8];
; #pragma unroll
;                     for (int e = 0; e < 4; ++e) { x[2 * e] = __uint_as_float(xr[e] << 16); x[2 * e + 1] = __uint_as_float(xr[e] & 0xffff0000u); p[2 * e] = __uint_as_float(pr[e] << 16); p[2 * e + 1] = __uint_as_float(pr[e] & 0xffff0000u); }
; #pragma unroll
;                     for (int e = 0; e < 4; ++e) { o[e] = x[e] + p[e] / (1.0f + __expf(-a0[e])); o[4 + e] = x[4 + e] + p[4 + e] / (1.0f + __expf(-a1[e])); }
;                     if (OutF) { *(f32x4*)(OutF + off) = (f32x4){o[0], o[1], o[2], o[3]}; *(f32x4*)(OutF + off + 4) = (f32x4){o[4], o[5], o[6], o[7]}; }
;                     else { u32x4 w; w.x = cvt_pk_bf16(o[0], o[1]); w.y = cvt_pk_bf16(o[2], o[3]); w.z = cvt_pk_bf16(o[4], o[5]); w.w = cvt_pk_bf16(o[6], o[7]); *(u32x4*)(XBout + off) = w; } } }
.LBB0_1255:
	s_nop 0
	v_or_b32_e32 v114, 48, v164
	v_ashrrev_i32_e32 v115, 31, v114
	v_lshlrev_b64 v[124:125], 10, v[114:115]
	v_lshl_add_u64 v[126:127], v[124:125], 0, v[158:159]
	v_lshlrev_b64 v[114:115], 1, v[126:127]
	v_lshl_add_u64 v[116:117], s[36:37], 0, v[114:115]
	v_lshl_add_u64 v[114:115], s[60:61], 0, v[114:115]
	global_load_dwordx4 v[118:121], v[116:117], off
	v_add_f32_e32 v110, v110, v82
	global_load_dwordx4 v[114:117], v[114:115], off
	v_add_f32_e32 v111, v111, v83
	v_mul_f32_e32 v110, 0xbfb8aa3b, v110
	v_mul_f32_e32 v111, 0xbfb8aa3b, v111
	v_exp_f32_e32 v110, v110
	v_exp_f32_e32 v111, v111
	v_add_f32_e32 v106, v106, v74
	v_add_f32_e32 v107, v107, v75
	v_mul_f32_e32 v106, 0xbfb8aa3b, v106
	v_pk_add_f32 v[110:111], v[110:111], 1.0 op_sel_hi:[1,0]
	v_mul_f32_e32 v107, 0xbfb8aa3b, v107
	v_exp_f32_e32 v106, v106
	v_exp_f32_e32 v107, v107
	v_add_f32_e32 v112, v112, v84
	v_mul_f32_e32 v112, 0xbfb8aa3b, v112
	v_add_f32_e32 v108, v108, v76
	v_pk_add_f32 v[106:107], v[106:107], 1.0 op_sel_hi:[1,0]
	v_add_f32_e32 v109, v109, v77
	v_mul_f32_e32 v108, 0xbfb8aa3b, v108
	v_mul_f32_e32 v109, 0xbfb8aa3b, v109
	v_exp_f32_e32 v108, v108
	v_exp_f32_e32 v109, v109
	s_waitcnt vmcnt(1)
	v_lshlrev_b32_e32 v128, 16, v118
	v_and_b32_e32 v129, 0xffff0000, v118
	s_waitcnt vmcnt(0)
	v_lshlrev_b32_e32 v118, 16, v114
	v_and_b32_e32 v114, 0xffff0000, v114
	v_rcp_f32_e32 v135, v111
	v_pk_add_f32 v[108:109], v[108:109], 1.0 op_sel_hi:[1,0]
	v_mul_f32_e32 v111, v114, v135
	v_rcp_f32_e32 v134, v110
	s_nop 0
	v_mul_f32_e32 v110, v118, v134
	v_lshlrev_b32_e32 v114, 16, v116
	v_and_b32_e32 v116, 0xffff0000, v116
	v_pk_add_f32 v[110:111], v[110:111], v[128:129]
	v_lshlrev_b32_e32 v128, 16, v120
	v_and_b32_e32 v129, 0xffff0000, v120
	v_rcp_f32_e32 v120, v107
	s_nop 0
	v_mul_f32_e32 v107, v116, v120
	v_rcp_f32_e32 v118, v106
	s_nop 0
	v_mul_f32_e32 v106, v114, v118
	v_pk_add_f32 v[106:107], v[106:107], v[128:129]
	v_exp_f32_e32 v128, v112
	v_add_f32_e32 v112, v113, v85
	v_mul_f32_e32 v112, 0xbfb8aa3b, v112
	v_exp_f32_e32 v129, v112
	v_lshlrev_b32_e32 v116, 16, v115
	v_and_b32_e32 v118, 0xffff0000, v115
	v_lshlrev_b32_e32 v112, 16, v119
	v_pk_add_f32 v[114:115], v[128:129], 1.0 op_sel_hi:[1,0]
	v_and_b32_e32 v113, 0xffff0000, v119
	v_rcp_f32_e32 v120, v115
	s_nop 0
	v_mul_f32_e32 v115, v118, v120
	v_rcp_f32_e32 v119, v114
	s_nop 0
	v_mul_f32_e32 v114, v116, v119
	v_lshlrev_b32_e32 v116, 16, v117
	v_and_b32_e32 v117, 0xffff0000, v117
	v_rcp_f32_e32 v119, v109
	v_pk_add_f32 v[112:113], v[114:115], v[112:113]
	v_lshlrev_b32_e32 v114, 16, v121
	v_and_b32_e32 v115, 0xffff0000, v121
	v_mul_f32_e32 v109, v117, v119
	v_rcp_f32_e32 v118, v108
	s_nop 0
	v_mul_f32_e32 v108, v116, v118
	v_pk_add_f32 v[108:109], v[108:109], v[114:115]
	s_and_b64 vcc, exec, s[40:41]
	v_lshl_add_u64 v[114:115], v[126:127], 2, s[44:45]
	s_cbranch_vccnz .LBB0_1296
	global_store_dwordx4 v[114:115], v[110:113], off
	global_store_dwordx4 v[114:115], v[106:109], off offset:16
	s_cbranch_execnz .LBB0_1258

; __device__ __forceinline__ unsigned cvt_pk_bf16(float lo, float hi) { unsigned r; asm volatile("v_cvt_pk_bf16_f32 %0, %1, %2" : "=v"(r) : "v"(lo), "v"(hi)); return r; }
;     __device__ __forceinline__ void operator()(const f32x4 (&acc)[2][2][4][2], const Unit& u, int wr, int wc, int fr, int fq) const {
;     ...
;                 for (int m = 0; m < 4; ++m) { const size_t off = (size_t)(u.pm * BM + ai * HALF + wr * 64 + m * 16 + fr) * ldc + col0 + bj * HALF;
;                     const u32x4 xr = *(const u32x4*)(XB + off), pr = *(const u32x4*)(Pp + off); const f32x4 a0 = acc[ai][bj][m][0] + b0, a1 = acc[ai][bj][m][1] + b1;
;                     float x[8], p[8], o[8];
; #pragma unroll
;                     for (int e = 0; e < 4; ++e) { x[2 * e] = __uint_as_float(xr[e] << 16); x[2 * e + 1] = __uint_as_float(xr[e] & 0xffff0000u); p[2 * e] = __uint_as_float(pr[e] << 16); p[2 * e + 1] = __uint_as_float(pr[e] & 0xffff0000u); }
; #pragma unroll
;                     for (int e = 0; e < 4; ++e) { o[e] = x[e] + p[e] / (1.0f + __expf(-a0[e])); o[4 + e] = x[4 + e] + p[4 + e] / (1.0f + __expf(-a1[e])); }
;                     if (OutF) { *(f32x4*)(OutF + off) = (f32x4){o[0], o[1], o[2], o[3]}; *(f32x4*)(OutF + off + 4) = (f32x4){o[4], o[5], o[6], o[7]}; }
;                     else { u32x4 w; w.x = cvt_pk_bf16(o[0], o[1]); w.y = cvt_pk_bf16(o[2], o[3]); w.z = cvt_pk_bf16(o[4], o[5]); w.w = cvt_pk_bf16(o[6], o[7]); *(u32x4*)(XBout + off) = w; } } }
.LBB0_1258:
	s_nop 0
	v_add_u32_e32 v106, 0x80, v164
	v_ashrrev_i32_e32 v107, 31, v106
	v_lshlrev_b64 v[116:117], 10, v[106:107]
	v_lshl_add_u64 v[118:119], v[116:117], 0, v[158:159]
	v_lshlrev_b64 v[106:107], 1, v[118:119]
	v_lshl_add_u64 v[108:109], s[36:37], 0, v[106:107]
	v_lshl_add_u64 v[106:107], s[60:61], 0, v[106:107]
	global_load_dwordx4 v[110:113], v[108:109], off
	v_add_f32_e32 v102, v102, v82
	global_load_dwordx4 v[106:109], v[106:107], off
	v_add_f32_e32 v103, v103, v83
	v_mul_f32_e32 v102, 0xbfb8aa3b, v102
	v_mul_f32_e32 v103, 0xbfb8aa3b, v103
	v_exp_f32_e32 v102, v102
	v_exp_f32_e32 v103, v103
	v_add_f32_e32 v98, v98, v74
	v_add_f32_e32 v99, v99, v75
	v_mul_f32_e32 v98, 0xbfb8aa3b, v98
	v_pk_add_f32 v[102:103], v[102:103], 1.0 op_sel_hi:[1,0]
	v_mul_f32_e32 v99, 0xbfb8aa3b, v99
	v_exp_f32_e32 v98, v98
	v_exp_f32_e32 v99, v99
	v_add_f32_e32 v104, v104, v84
	v_mul_f32_e32 v104, 0xbfb8aa3b, v104
	v_add_f32_e32 v100, v100, v76
	v_pk_add_f32 v[98:99], v[98:99], 1.0 op_sel_hi:[1,0]
	v_add_f32_e32 v101, v101, v77
	v_mul_f32_e32 v100, 0xbfb8aa3b, v100
	v_mul_f32_e32 v101, 0xbfb8aa3b, v101
	v_exp_f32_e32 v100, v100
	v_exp_f32_e32 v101, v101
	s_waitcnt vmcnt(1)
	v_lshlrev_b32_e32 v120, 16, v110
	v_and_b32_e32 v121, 0xffff0000, v110
	s_waitcnt vmcnt(0)
	v_lshlrev_b32_e32 v110, 16, v106
	v_and_b32_e32 v106, 0xffff0000, v106
	v_rcp_f32_e32 v127, v103
	v_pk_add_f32 v[100:101], v[100:101], 1.0 op_sel_hi:[1,0]
	v_mul_f32_e32 v103, v106, v127
	v_rcp_f32_e32 v126, v102
	s_nop 0
	v_mul_f32_e32 v102, v110, v126
	v_lshlrev_b32_e32 v106, 16, v108
	v_and_b32_e32 v108, 0xffff0000, v108
	v_pk_add_f32 v[102:103], v[102:103], v[120:121]
	v_lshlrev_b32_e32 v120, 16, v112
	v_and_b32_e32 v121, 0xffff0000, v112
	v_rcp_f32_e32 v112, v99
	s_nop 0
	v_mul_f32_e32 v99, v108, v112
	v_rcp_f32_e32 v110, v98
	s_nop 0
	v_mul_f32_e32 v98, v106, v110
	v_pk_add_f32 v[98:99], v[98:99], v[120:121]
	v_exp_f32_e32 v120, v104
	v_add_f32_e32 v104, v105, v85
	v_mul_f32_e32 v104, 0xbfb8aa3b, v104
	v_exp_f32_e32 v121, v104
	v_lshlrev_b32_e32 v108, 16, v107
	v_and_b32_e32 v110, 0xffff0000, v107
	v_lshlrev_b32_e32 v104, 16, v111
	v_pk_add_f32 v[106:107], v[120:121], 1.0 op_sel_hi:[1,0]
	v_and_b32_e32 v105, 0xffff0000, v111
	v_rcp_f32_e32 v112, v107
	s_nop 0
	v_mul_f32_e32 v107, v110, v112
	v_rcp_f32_e32 v111, v106
	s_nop 0
	v_mul_f32_e32 v106, v108, v111
	v_lshlrev_b32_e32 v108, 16, v109
	v_and_b32_e32 v109, 0xffff0000, v109
	v_rcp_f32_e32 v111, v101
	v_pk_add_f32 v[104:105], v[106:107], v[104:105]
	v_lshlrev_b32_e32 v106, 16, v113
	v_and_b32_e32 v107, 0xffff0000, v113
	v_mul_f32_e32 v101, v109, v111
	v_rcp_f32_e32 v110, v100
	s_nop 0
	v_mul_f32_e32 v100, v108, v110
	v_pk_add_f32 v[100:101], v[100:101], v[106:107]
	s_and_b64 vcc, exec, s[40:41]
	v_lshl_add_u64 v[106:107], v[118:119], 2, s[44:45]
	s_cbranch_vccnz .LBB0_1297
	global_store_dwordx4 v[106:107], v[102:105], off
	global_store_dwordx4 v[106:107], v[98:101], off offset:16
	s_cbranch_execnz .LBB0_1261

; __device__ __forceinline__ unsigned cvt_pk_bf16(float lo, float hi) { unsigned r; asm volatile("v_cvt_pk_bf16_f32 %0, %1, %2" : "=v"(r) : "v"(lo), "v"(hi)); return r; }
;     __device__ __forceinline__ void operator()(const f32x4 (&acc)[2][2][4][2], const Unit& u, int wr, int wc, int fr, int fq) const {
;     ...
;                 for (int m = 0; m < 4; ++m) { const size_t off = (size_t)(u.pm * BM + ai * HALF + wr * 64 + m * 16 + fr) * ldc + col0 + bj * HALF;
;                     const u32x4 xr = *(const u32x4*)(XB + off), pr = *(const u32x4*)(Pp + off); const f32x4 a0 = acc[ai][bj][m][0] + b0, a1 = acc[ai][bj][m][1] + b1;
;                     float x[8], p[8], o[8];
; #pragma unroll
;                     for (int e = 0; e < 4; ++e) { x[2 * e] = __uint_as_float(xr[e] << 16); x[2 * e + 1] = __uint_as_float(xr[e] & 0xffff0000u); p[2 * e] = __uint_as_float(pr[e] << 16); p[2 * e + 1] = __uint_as_float(pr[e] & 0xffff0000u); }
; #pragma unroll
;                     for (int e = 0; e < 4; ++e) { o[e] = x[e] + p[e] / (1.0f + __expf(-a0[e])); o[4 + e] = x[4 + e] + p[4 + e] / (1.0f + __expf(-a1[e])); }
;                     if (OutF) { *(f32x4*)(OutF + off) = (f32x4){o[0], o[1], o[2], o[3]}; *(f32x4*)(OutF + off + 4) = (f32x4){o[4], o[5], o[6], o[7]}; }
;                     else { u32x4 w; w.x = cvt_pk_bf16(o[0], o[1]); w.y = cvt_pk_bf16(o[2], o[3]); w.z = cvt_pk_bf16(o[4], o[5]); w.w = cvt_pk_bf16(o[6], o[7]); *(u32x4*)(XBout + off) = w; } } }
.LBB0_1261:
	s_nop 0
	v_add_u32_e32 v98, 0x90, v164
	v_ashrrev_i32_e32 v99, 31, v98
	v_lshlrev_b64 v[108:109], 10, v[98:99]
	v_lshl_add_u64 v[110:111], v[108:109], 0, v[158:159]
	v_lshlrev_b64 v[98:99], 1, v[110:111]
	v_lshl_add_u64 v[100:101], s[36:37], 0, v[98:99]
	v_lshl_add_u64 v[98:99], s[60:61], 0, v[98:99]
	global_load_dwordx4 v[102:105], v[100:101], off
	v_add_f32_e32 v94, v94, v82
	global_load_dwordx4 v[98:101], v[98:99], off
	v_add_f32_e32 v95, v95, v83
	v_mul_f32_e32 v94, 0xbfb8aa3b, v94
	v_mul_f32_e32 v95, 0xbfb8aa3b, v95
	v_exp_f32_e32 v94, v94
	v_exp_f32_e32 v95, v95
	v_add_f32_e32 v90, v90, v74
	v_add_f32_e32 v91, v91, v75
	v_mul_f32_e32 v90, 0xbfb8aa3b, v90
	v_pk_add_f32 v[94:95], v[94:95], 1.0 op_sel_hi:[1,0]
	v_mul_f32_e32 v91, 0xbfb8aa3b, v91
	v_exp_f32_e32 v90, v90
	v_exp_f32_e32 v91, v91
	v_add_f32_e32 v96, v96, v84
	v_mul_f32_e32 v96, 0xbfb8aa3b, v96
	v_add_f32_e32 v92, v92, v76
	v_pk_add_f32 v[90:91], v[90:91], 1.0 op_sel_hi:[1,0]
	v_add_f32_e32 v93, v93, v77
	v_mul_f32_e32 v92, 0xbfb8aa3b, v92
	v_mul_f32_e32 v93, 0xbfb8aa3b, v93
	v_exp_f32_e32 v92, v92
	v_exp_f32_e32 v93, v93
	s_waitcnt vmcnt(1)
	v_lshlrev_b32_e32 v112, 16, v102
	v_and_b32_e32 v113, 0xffff0000, v102
	s_waitcnt vmcnt(0)
	v_lshlrev_b32_e32 v102, 16, v98
	v_and_b32_e32 v98, 0xffff0000, v98
	v_rcp_f32_e32 v119, v95
	v_pk_add_f32 v[92:93], v[92:93], 1.0 op_sel_hi:[1,0]
	v_mul_f32_e32 v95, v98, v119
	v_rcp_f32_e32 v118, v94
	s_nop 0
	v_mul_f32_e32 v94, v102, v118
	v_lshlrev_b32_e32 v98, 16, v100
	v_and_b32_e32 v100, 0xffff0000, v100
	v_pk_add_f32 v[94:95], v[94:95], v[112:113]
	v_lshlrev_b32_e32 v112, 16, v104
	v_and_b32_e32 v113, 0xffff0000, v104
	v_rcp_f32_e32 v104, v91
	s_nop 0
	v_mul_f32_e32 v91, v100, v104
	v_rcp_f32_e32 v102, v90
	s_nop 0
	v_mul_f32_e32 v90, v98, v102
	v_pk_add_f32 v[90:91], v[90:91], v[112:113]
	v_exp_f32_e32 v112, v96
	v_add_f32_e32 v96, v97, v85
	v_mul_f32_e32 v96, 0xbfb8aa3b, v96
	v_exp_f32_e32 v113, v96
	v_lshlrev_b32_e32 v100, 16, v99
	v_and_b32_e32 v102, 0xffff0000, v99
	v_lshlrev_b32_e32 v96, 16, v103
	v_pk_add_f32 v[98:99], v[112:113], 1.0 op_sel_hi:[1,0]
	v_and_b32_e32 v97, 0xffff0000, v103
	v_rcp_f32_e32 v104, v99
	s_nop 0
	v_mul_f32_e32 v99, v102, v104
	v_rcp_f32_e32 v103, v98
	s_nop 0
	v_mul_f32_e32 v98, v100, v103
	v_lshlrev_b32_e32 v100, 16, v101
	v_and_b32_e32 v101, 0xffff0000, v101
	v_rcp_f32_e32 v103, v93
	v_pk_add_f32 v[96:97], v[98:99], v[96:97]
	v_lshlrev_b32_e32 v98, 16, v105
	v_and_b32_e32 v99, 0xffff0000, v105
	v_mul_f32_e32 v93, v101, v103
	v_rcp_f32_e32 v102, v92
	s_nop 0
	v_mul_f32_e32 v92, v100, v102
	v_pk_add_f32 v[92:93], v[92:93], v[98:99]
	s_and_b64 vcc, exec, s[40:41]
	v_lshl_add_u64 v[98:99], v[110:111], 2, s[44:45]
	s_cbranch_vccnz .LBB0_1298
	global_store_dwordx4 v[98:99], v[94:97], off
	global_store_dwordx4 v[98:99], v[90:93], off offset:16
	s_cbranch_execnz .LBB0_1264

; __device__ __forceinline__ unsigned cvt_pk_bf16(float lo, float hi) { unsigned r; asm volatile("v_cvt_pk_bf16_f32 %0, %1, %2" : "=v"(r) : "v"(lo), "v"(hi)); return r; }
;     __device__ __forceinline__ void operator()(const f32x4 (&acc)[2][2][4][2], const Unit& u, int wr, int wc, int fr, int fq) const {
;     ...
;                 for (int m = 0; m < 4; ++m) { const size_t off = (size_t)(u.pm * BM + ai * HALF + wr * 64 + m * 16 + fr) * ldc + col0 + bj * HALF;
;                     const u32x4 xr = *(const u32x4*)(XB + off), pr = *(const u32x4*)(Pp + off); const f32x4 a0 = acc[ai][bj][m][0] + b0, a1 = acc[ai][bj][m][1] + b1;
;                     float x[8], p[8], o[8];
; #pragma unroll
;                     for (int e = 0; e < 4; ++e) { x[2 * e] = __uint_as_float(xr[e] << 16); x[2 * e + 1] = __uint_as_float(xr[e] & 0xffff0000u); p[2 * e] = __uint_as_float(pr[e] << 16); p[2 * e + 1] = __uint_as_float(pr[e] & 0xffff0000u); }
; #pragma unroll
;                     for (int e = 0; e < 4; ++e) { o[e] = x[e] + p[e] / (1.0f + __expf(-a0[e])); o[4 + e] = x[4 + e] + p[4 + e] / (1.0f + __expf(-a1[e])); }
;                     if (OutF) { *(f32x4*)(OutF + off) = (f32x4){o[0], o[1], o[2], o[3]}; *(f32x4*)(OutF + off + 4) = (f32x4){o[4], o[5], o[6], o[7]}; }
;                     else { u32x4 w; w.x = cvt_pk_bf16(o[0], o[1]); w.y = cvt_pk_bf16(o[2], o[3]); w.z = cvt_pk_bf16(o[4], o[5]); w.w = cvt_pk_bf16(o[6], o[7]); *(u32x4*)(XBout + off) = w; } } }
.LBB0_1264:
	s_nop 0
	v_add_u32_e32 v90, 0xa0, v164
	v_ashrrev_i32_e32 v91, 31, v90
	v_lshlrev_b64 v[100:101], 10, v[90:91]
	v_lshl_add_u64 v[102:103], v[100:101], 0, v[158:159]
	v_lshlrev_b64 v[90:91], 1, v[102:103]
	v_lshl_add_u64 v[92:93], s[36:37], 0, v[90:91]
	v_lshl_add_u64 v[90:91], s[60:61], 0, v[90:91]
	global_load_dwordx4 v[94:97], v[92:93], off
	v_add_f32_e32 v86, v86, v82
	global_load_dwordx4 v[90:93], v[90:91], off
	v_add_f32_e32 v87, v87, v83
	v_mul_f32_e32 v86, 0xbfb8aa3b, v86
	v_mul_f32_e32 v87, 0xbfb8aa3b, v87
	v_exp_f32_e32 v86, v86
	v_exp_f32_e32 v87, v87
	v_add_f32_e32 v78, v78, v74
	v_add_f32_e32 v79, v79, v75
	v_mul_f32_e32 v78, 0xbfb8aa3b, v78
	v_pk_add_f32 v[86:87], v[86:87], 1.0 op_sel_hi:[1,0]
	v_mul_f32_e32 v79, 0xbfb8aa3b, v79
	v_exp_f32_e32 v78, v78
	v_exp_f32_e32 v79, v79
	v_add_f32_e32 v88, v88, v84
	v_mul_f32_e32 v88, 0xbfb8aa3b, v88
	v_add_f32_e32 v80, v80, v76
	v_pk_add_f32 v[78:79], v[78:79], 1.0 op_sel_hi:[1,0]
	v_add_f32_e32 v81, v81, v77
	v_mul_f32_e32 v80, 0xbfb8aa3b, v80
	v_mul_f32_e32 v81, 0xbfb8aa3b, v81
	v_exp_f32_e32 v80, v80
	v_exp_f32_e32 v81, v81
	s_waitcnt vmcnt(1)
	v_lshlrev_b32_e32 v104, 16, v94
	v_and_b32_e32 v105, 0xffff0000, v94
	s_waitcnt vmcnt(0)
	v_lshlrev_b32_e32 v94, 16, v90
	v_and_b32_e32 v90, 0xffff0000, v90
	v_rcp_f32_e32 v111, v87
	v_pk_add_f32 v[80:81], v[80:81], 1.0 op_sel_hi:[1,0]
	v_mul_f32_e32 v87, v90, v111
	v_rcp_f32_e32 v110, v86
	s_nop 0
	v_mul_f32_e32 v86, v94, v110
	v_lshlrev_b32_e32 v90, 16, v92
	v_and_b32_e32 v92, 0xffff0000, v92
	v_pk_add_f32 v[86:87], v[86:87], v[104:105]
	v_lshlrev_b32_e32 v104, 16, v96
	v_and_b32_e32 v105, 0xffff0000, v96
	v_rcp_f32_e32 v96, v79
	s_nop 0
	v_mul_f32_e32 v79, v92, v96
	v_rcp_f32_e32 v94, v78
	s_nop 0
	v_mul_f32_e32 v78, v90, v94
	v_pk_add_f32 v[78:79], v[78:79], v[104:105]
	v_exp_f32_e32 v104, v88
	v_add_f32_e32 v88, v89, v85
	v_mul_f32_e32 v88, 0xbfb8aa3b, v88
	v_exp_f32_e32 v105, v88
	v_lshlrev_b32_e32 v92, 16, v91
	v_and_b32_e32 v94, 0xffff0000, v91
	v_lshlrev_b32_e32 v88, 16, v95
	v_pk_add_f32 v[90:91], v[104:105], 1.0 op_sel_hi:[1,0]
	v_and_b32_e32 v89, 0xffff0000, v95
	v_rcp_f32_e32 v96, v91
	s_nop 0
	v_mul_f32_e32 v91, v94, v96
	v_rcp_f32_e32 v95, v90
	s_nop 0
	v_mul_f32_e32 v90, v92, v95
	v_lshlrev_b32_e32 v92, 16, v93
	v_and_b32_e32 v93, 0xffff0000, v93
	v_rcp_f32_e32 v95, v81
	v_pk_add_f32 v[88:89], v[90:91], v[88:89]
	v_lshlrev_b32_e32 v90, 16, v97
	v_and_b32_e32 v91, 0xffff0000, v97
	v_mul_f32_e32 v81, v93, v95
	v_rcp_f32_e32 v94, v80
	s_nop 0
	v_mul_f32_e32 v80, v92, v94
	v_pk_add_f32 v[80:81], v[80:81], v[90:91]
	s_and_b64 vcc, exec, s[40:41]
	v_lshl_add_u64 v[90:91], v[102:103], 2, s[44:45]
	s_cbranch_vccnz .LBB0_1299
	global_store_dwordx4 v[90:91], v[86:89], off
	global_store_dwordx4 v[90:91], v[78:81], off offset:16
	s_cbranch_execnz .LBB0_1267

; __device__ __forceinline__ unsigned cvt_pk_bf16(float lo, float hi) { unsigned r; asm volatile("v_cvt_pk_bf16_f32 %0, %1, %2" : "=v"(r) : "v"(lo), "v"(hi)); return r; }
;     __device__ __forceinline__ void operator()(const f32x4 (&acc)[2][2][4][2], const Unit& u, int wr, int wc, int fr, int fq) const {
;     ...
;                 for (int m = 0; m < 4; ++m) { const size_t off = (size_t)(u.pm * BM + ai * HALF + wr * 64 + m * 16 + fr) * ldc + col0 + bj * HALF;
;                     const u32x4 xr = *(const u32x4*)(XB + off), pr = *(const u32x4*)(Pp + off); const f32x4 a0 = acc[ai][bj][m][0] + b0, a1 = acc[ai][bj][m][1] + b1;
;                     float x[8], p[8], o[8];
; #pragma unroll
;                     for (int e = 0; e < 4; ++e) { x[2 * e] = __uint_as_float(xr[e] << 16); x[2 * e + 1] = __uint_as_float(xr[e] & 0xffff0000u); p[2 * e] = __uint_as_float(pr[e] << 16); p[2 * e + 1] = __uint_as_float(pr[e] & 0xffff0000u); }
; #pragma unroll
;                     for (int e = 0; e < 4; ++e) { o[e] = x[e] + p[e] / (1.0f + __expf(-a0[e])); o[4 + e] = x[4 + e] + p[4 + e] / (1.0f + __expf(-a1[e])); }
;                     if (OutF) { *(f32x4*)(OutF + off) = (f32x4){o[0], o[1], o[2], o[3]}; *(f32x4*)(OutF + off + 4) = (f32x4){o[4], o[5], o[6], o[7]}; }
;                     else { u32x4 w; w.x = cvt_pk_bf16(o[0], o[1]); w.y = cvt_pk_bf16(o[2], o[3]); w.z = cvt_pk_bf16(o[4], o[5]); w.w = cvt_pk_bf16(o[6], o[7]); *(u32x4*)(XBout + off) = w; } } }
.LBB0_1267:
	s_nop 0
	v_add_u32_e32 v78, 0xb0, v164
	v_ashrrev_i32_e32 v79, 31, v78
	v_lshlrev_b64 v[92:93], 10, v[78:79]
	v_lshl_add_u64 v[94:95], v[92:93], 0, v[158:159]
	v_lshlrev_b64 v[78:79], 1, v[94:95]
	v_lshl_add_u64 v[80:81], s[36:37], 0, v[78:79]
	v_lshl_add_u64 v[78:79], s[60:61], 0, v[78:79]
	global_load_dwordx4 v[86:89], v[80:81], off
	v_add_f32_e32 v70, v70, v82
	global_load_dwordx4 v[78:81], v[78:79], off
	v_add_f32_e32 v71, v71, v83
	v_mul_f32_e32 v70, 0xbfb8aa3b, v70
	v_mul_f32_e32 v71, 0xbfb8aa3b, v71
	v_exp_f32_e32 v70, v70
	v_exp_f32_e32 v71, v71
	v_add_f32_e32 v66, v66, v74
	v_add_f32_e32 v67, v67, v75
	v_mul_f32_e32 v66, 0xbfb8aa3b, v66
	v_pk_add_f32 v[70:71], v[70:71], 1.0 op_sel_hi:[1,0]
	v_mul_f32_e32 v67, 0xbfb8aa3b, v67
	v_exp_f32_e32 v66, v66
	v_exp_f32_e32 v67, v67
	v_add_f32_e32 v72, v72, v84
	v_mul_f32_e32 v72, 0xbfb8aa3b, v72
	v_add_f32_e32 v68, v68, v76
	v_pk_add_f32 v[66:67], v[66:67], 1.0 op_sel_hi:[1,0]
	v_add_f32_e32 v69, v69, v77
	v_mul_f32_e32 v68, 0xbfb8aa3b, v68
	v_mul_f32_e32 v69, 0xbfb8aa3b, v69
	v_exp_f32_e32 v68, v68
	v_exp_f32_e32 v69, v69
	s_waitcnt vmcnt(1)
	v_lshlrev_b32_e32 v82, 16, v86
	v_and_b32_e32 v83, 0xffff0000, v86
	s_waitcnt vmcnt(0)
	v_lshlrev_b32_e32 v74, 16, v78
	v_and_b32_e32 v78, 0xffff0000, v78
	v_rcp_f32_e32 v96, v71
	v_and_b32_e32 v75, 0xffff0000, v88
	v_lshlrev_b32_e32 v76, 16, v79
	v_and_b32_e32 v77, 0xffff0000, v81
	v_mul_f32_e32 v71, v78, v96
	v_rcp_f32_e32 v86, v70
	v_pk_add_f32 v[68:69], v[68:69], 1.0 op_sel_hi:[1,0]
	v_mul_f32_e32 v70, v74, v86
	v_lshlrev_b32_e32 v78, 16, v80
	v_and_b32_e32 v80, 0xffff0000, v80
	v_pk_add_f32 v[70:71], v[70:71], v[82:83]
	v_rcp_f32_e32 v83, v67
	v_lshlrev_b32_e32 v74, 16, v88
	v_mul_f32_e32 v67, v80, v83
	v_rcp_f32_e32 v82, v66
	s_nop 0
	v_mul_f32_e32 v66, v78, v82
	v_pk_add_f32 v[66:67], v[66:67], v[74:75]
	v_exp_f32_e32 v74, v72
	v_add_f32_e32 v72, v73, v85
	v_mul_f32_e32 v72, 0xbfb8aa3b, v72
	v_exp_f32_e32 v75, v72
	v_and_b32_e32 v78, 0xffff0000, v79
	v_lshlrev_b32_e32 v72, 16, v87
	v_and_b32_e32 v73, 0xffff0000, v87
	v_pk_add_f32 v[74:75], v[74:75], 1.0 op_sel_hi:[1,0]
	s_nop 0
	v_rcp_f32_e32 v80, v75
	s_nop 0
	v_mul_f32_e32 v75, v78, v80
	v_rcp_f32_e32 v79, v74
	s_nop 0
	v_mul_f32_e32 v74, v76, v79
	v_rcp_f32_e32 v79, v69
	v_lshlrev_b32_e32 v76, 16, v81
	v_pk_add_f32 v[72:73], v[74:75], v[72:73]
	v_lshlrev_b32_e32 v74, 16, v89
	v_mul_f32_e32 v69, v77, v79
	v_rcp_f32_e32 v78, v68
	v_and_b32_e32 v75, 0xffff0000, v89
	v_lshl_add_u64 v[82:83], v[94:95], 2, s[44:45]
	v_mul_f32_e32 v68, v76, v78
	v_pk_add_f32 v[68:69], v[68:69], v[74:75]
	s_and_b64 vcc, exec, s[40:41]
	s_cbranch_vccnz .LBB0_1300
	global_store_dwordx4 v[82:83], v[70:73], off
	global_store_dwordx4 v[82:83], v[66:69], off offset:16
	s_cbranch_execnz .LBB0_1270

; __device__ __forceinline__ unsigned cvt_pk_bf16(float lo, float hi) { unsigned r; asm volatile("v_cvt_pk_bf16_f32 %0, %1, %2" : "=v"(r) : "v"(lo), "v"(hi)); return r; }
;     __device__ __forceinline__ void operator()(const f32x4 (&acc)[2][2][4][2], const Unit& u, int wr, int wc, int fr, int fq) const {
;     ...
;         for (int bj = 0; bj < 2; ++bj) { const f32x4 b0 = *(const f32x4*)(bg + col0 + bj * HALF), b1 = *(const f32x4*)(bg + col0 + bj * HALF + 4);
; #pragma unroll
;             for (int ai = 0; ai < 2; ++ai)
; #pragma unroll
;                 for (int m = 0; m < 4; ++m) { const size_t off = (size_t)(u.pm * BM + ai * HALF + wr * 64 + m * 16 + fr) * ldc + col0 + bj * HALF;
;                     const u32x4 xr = *(const u32x4*)(XB + off), pr = *(const u32x4*)(Pp + off); const f32x4 a0 = acc[ai][bj][m][0] + b0, a1 = acc[ai][bj][m][1] + b1;
;                     float x[8], p[8], o[8];
; #pragma unroll
;                     for (int e = 0; e < 4; ++e) { x[2 * e] = __uint_as_float(xr[e] << 16); x[2 * e + 1] = __uint_as_float(xr[e] & 0xffff0000u); p[2 * e] = __uint_as_float(pr[e] << 16); p[2 * e + 1] = __uint_as_float(pr[e] & 0xffff0000u); }
; #pragma unroll
;                     for (int e = 0; e < 4; ++e) { o[e] = x[e] + p[e] / (1.0f + __expf(-a0[e])); o[4 + e] = x[4 + e] + p[4 + e] / (1.0f + __expf(-a1[e])); }
;                     if (OutF) { *(f32x4*)(OutF + off) = (f32x4){o[0], o[1], o[2], o[3]}; *(f32x4*)(OutF + off + 4) = (f32x4){o[4], o[5], o[6], o[7]}; }
;                     else { u32x4 w; w.x = cvt_pk_bf16(o[0], o[1]); w.y = cvt_pk_bf16(o[2], o[3]); w.z = cvt_pk_bf16(o[4], o[5]); w.w = cvt_pk_bf16(o[6], o[7]); *(u32x4*)(XBout + off) = w; } } }
.LBB0_1270:
	global_load_dwordx4 v[66:69], v[160:161], off offset:528
	s_nop 0
	global_load_dwordx4 v[70:73], v[160:161], off offset:512
	v_or_b32_e32 v158, 0x80, v158
	v_lshl_add_u64 v[84:85], v[162:163], 0, v[158:159]
	v_lshlrev_b64 v[74:75], 1, v[84:85]
	v_lshl_add_u64 v[76:77], s[36:37], 0, v[74:75]
	v_lshl_add_u64 v[74:75], s[60:61], 0, v[74:75]
	global_load_dwordx4 v[78:81], v[76:77], off
	s_waitcnt vmcnt(2)
	v_add_f32_e32 v58, v58, v66
	global_load_dwordx4 v[74:77], v[74:75], off
	s_waitcnt vmcnt(2)
	v_add_f32_e32 v62, v62, v70
	v_add_f32_e32 v63, v63, v71
	v_mul_f32_e32 v62, 0xbfb8aa3b, v62
	v_mul_f32_e32 v63, 0xbfb8aa3b, v63
	v_exp_f32_e32 v62, v62
	v_exp_f32_e32 v63, v63
	s_waitcnt vmcnt(1)
	v_lshlrev_b32_e32 v86, 16, v78
	v_and_b32_e32 v87, 0xffff0000, v78
	v_add_f32_e32 v59, v59, v67
	v_pk_add_f32 v[62:63], v[62:63], 1.0 op_sel_hi:[1,0]
	v_mul_f32_e32 v58, 0xbfb8aa3b, v58
	v_mul_f32_e32 v59, 0xbfb8aa3b, v59
	v_exp_f32_e32 v58, v58
	v_exp_f32_e32 v59, v59
	v_add_f32_e32 v64, v64, v72
	v_mul_f32_e32 v64, 0xbfb8aa3b, v64
	v_add_f32_e32 v60, v60, v68
	v_pk_add_f32 v[58:59], v[58:59], 1.0 op_sel_hi:[1,0]
	v_add_f32_e32 v61, v61, v69
	v_mul_f32_e32 v60, 0xbfb8aa3b, v60
	v_mul_f32_e32 v61, 0xbfb8aa3b, v61
	v_exp_f32_e32 v60, v60
	v_exp_f32_e32 v61, v61
	s_waitcnt vmcnt(0)
	v_lshlrev_b32_e32 v78, 16, v74
	v_and_b32_e32 v74, 0xffff0000, v74
	v_rcp_f32_e32 v89, v63
	v_pk_add_f32 v[60:61], v[60:61], 1.0 op_sel_hi:[1,0]
	v_mul_f32_e32 v63, v74, v89
	v_rcp_f32_e32 v88, v62
	s_nop 0
	v_mul_f32_e32 v62, v78, v88
	v_lshlrev_b32_e32 v74, 16, v76
	v_and_b32_e32 v76, 0xffff0000, v76
	v_pk_add_f32 v[62:63], v[62:63], v[86:87]
	v_lshlrev_b32_e32 v86, 16, v80
	v_and_b32_e32 v87, 0xffff0000, v80
	v_rcp_f32_e32 v80, v59
	s_nop 0
	v_mul_f32_e32 v59, v76, v80
	v_rcp_f32_e32 v78, v58
	s_nop 0
	v_mul_f32_e32 v58, v74, v78
	v_pk_add_f32 v[58:59], v[58:59], v[86:87]
	v_exp_f32_e32 v86, v64
	v_add_f32_e32 v64, v65, v73
	v_mul_f32_e32 v64, 0xbfb8aa3b, v64
	v_exp_f32_e32 v87, v64
	v_lshlrev_b32_e32 v76, 16, v75
	v_and_b32_e32 v78, 0xffff0000, v75
	v_lshlrev_b32_e32 v64, 16, v79
	v_pk_add_f32 v[74:75], v[86:87], 1.0 op_sel_hi:[1,0]
	v_and_b32_e32 v65, 0xffff0000, v79
	v_rcp_f32_e32 v80, v75
	s_nop 0
	v_mul_f32_e32 v75, v78, v80
	v_rcp_f32_e32 v79, v74
	s_nop 0
	v_mul_f32_e32 v74, v76, v79
	v_lshlrev_b32_e32 v76, 16, v77
	v_and_b32_e32 v77, 0xffff0000, v77
	v_rcp_f32_e32 v79, v61
	v_pk_add_f32 v[64:65], v[74:75], v[64:65]
	v_lshlrev_b32_e32 v74, 16, v81
	v_and_b32_e32 v75, 0xffff0000, v81
	v_mul_f32_e32 v61, v77, v79
	v_rcp_f32_e32 v78, v60
	s_nop 0
	v_mul_f32_e32 v60, v76, v78
	v_pk_add_f32 v[60:61], v[60:61], v[74:75]
	s_and_b64 vcc, exec, s[40:41]
	s_cbranch_vccnz .LBB0_1301
	global_store_dwordx4 v[138:139], v[62:65], off offset:512
	global_store_dwordx4 v[138:139], v[58:61], off offset:528
	s_cbranch_execnz .LBB0_1273

; __device__ __forceinline__ unsigned cvt_pk_bf16(float lo, float hi) { unsigned r; asm volatile("v_cvt_pk_bf16_f32 %0, %1, %2" : "=v"(r) : "v"(lo), "v"(hi)); return r; }
;     __device__ __forceinline__ void operator()(const f32x4 (&acc)[2][2][4][2], const Unit& u, int wr, int wc, int fr, int fq) const {
;     ...
;                 for (int m = 0; m < 4; ++m) { const size_t off = (size_t)(u.pm * BM + ai * HALF + wr * 64 + m * 16 + fr) * ldc + col0 + bj * HALF;
;                     const u32x4 xr = *(const u32x4*)(XB + off), pr = *(const u32x4*)(Pp + off); const f32x4 a0 = acc[ai][bj][m][0] + b0, a1 = acc[ai][bj][m][1] + b1;
;                     float x[8], p[8], o[8];
; #pragma unroll
;                     for (int e = 0; e < 4; ++e) { x[2 * e] = __uint_as_float(xr[e] << 16); x[2 * e + 1] = __uint_as_float(xr[e] & 0xffff0000u); p[2 * e] = __uint_as_float(pr[e] << 16); p[2 * e + 1] = __uint_as_float(pr[e] & 0xffff0000u); }
; #pragma unroll
;                     for (int e = 0; e < 4; ++e) { o[e] = x[e] + p[e] / (1.0f + __expf(-a0[e])); o[4 + e] = x[4 + e] + p[4 + e] / (1.0f + __expf(-a1[e])); }
;                     if (OutF) { *(f32x4*)(OutF + off) = (f32x4){o[0], o[1], o[2], o[3]}; *(f32x4*)(OutF + off + 4) = (f32x4){o[4], o[5], o[6], o[7]}; }
;                     else { u32x4 w; w.x = cvt_pk_bf16(o[0], o[1]); w.y = cvt_pk_bf16(o[2], o[3]); w.z = cvt_pk_bf16(o[4], o[5]); w.w = cvt_pk_bf16(o[6], o[7]); *(u32x4*)(XBout + off) = w; } } }
.LBB0_1273:
	v_lshl_add_u64 v[74:75], v[140:141], 0, v[158:159]
	v_lshlrev_b64 v[58:59], 1, v[74:75]
	v_lshl_add_u64 v[60:61], s[36:37], 0, v[58:59]
	v_lshl_add_u64 v[58:59], s[60:61], 0, v[58:59]
	global_load_dwordx4 v[62:65], v[60:61], off
	v_add_f32_e32 v54, v54, v70
	global_load_dwordx4 v[58:61], v[58:59], off
	v_add_f32_e32 v55, v55, v71
	v_mul_f32_e32 v54, 0xbfb8aa3b, v54
	v_mul_f32_e32 v55, 0xbfb8aa3b, v55
	v_exp_f32_e32 v54, v54
	v_exp_f32_e32 v55, v55
	v_add_f32_e32 v50, v50, v66
	v_add_f32_e32 v51, v51, v67
	v_mul_f32_e32 v50, 0xbfb8aa3b, v50
	v_pk_add_f32 v[54:55], v[54:55], 1.0 op_sel_hi:[1,0]
	v_mul_f32_e32 v51, 0xbfb8aa3b, v51
	v_exp_f32_e32 v50, v50
	v_exp_f32_e32 v51, v51
	v_add_f32_e32 v56, v56, v72
	v_mul_f32_e32 v56, 0xbfb8aa3b, v56
	v_add_f32_e32 v52, v52, v68
	v_pk_add_f32 v[50:51], v[50:51], 1.0 op_sel_hi:[1,0]
	v_add_f32_e32 v53, v53, v69
	v_mul_f32_e32 v52, 0xbfb8aa3b, v52
	v_mul_f32_e32 v53, 0xbfb8aa3b, v53
	v_exp_f32_e32 v52, v52
	v_exp_f32_e32 v53, v53
	s_waitcnt vmcnt(1)
	v_lshlrev_b32_e32 v76, 16, v62
	v_and_b32_e32 v77, 0xffff0000, v62
	s_waitcnt vmcnt(0)
	v_lshlrev_b32_e32 v62, 16, v58
	v_and_b32_e32 v58, 0xffff0000, v58
	v_rcp_f32_e32 v79, v55
	v_pk_add_f32 v[52:53], v[52:53], 1.0 op_sel_hi:[1,0]
	v_mul_f32_e32 v55, v58, v79
	v_rcp_f32_e32 v78, v54
	s_nop 0
	v_mul_f32_e32 v54, v62, v78
	v_lshlrev_b32_e32 v58, 16, v60
	v_and_b32_e32 v60, 0xffff0000, v60
	v_pk_add_f32 v[54:55], v[54:55], v[76:77]
	v_lshlrev_b32_e32 v76, 16, v64
	v_and_b32_e32 v77, 0xffff0000, v64
	v_rcp_f32_e32 v64, v51
	s_nop 0
	v_mul_f32_e32 v51, v60, v64
	v_rcp_f32_e32 v62, v50
	s_nop 0
	v_mul_f32_e32 v50, v58, v62
	v_pk_add_f32 v[50:51], v[50:51], v[76:77]
	v_exp_f32_e32 v76, v56
	v_add_f32_e32 v56, v57, v73
	v_mul_f32_e32 v56, 0xbfb8aa3b, v56
	v_exp_f32_e32 v77, v56
	v_lshlrev_b32_e32 v60, 16, v59
	v_and_b32_e32 v62, 0xffff0000, v59
	v_lshlrev_b32_e32 v56, 16, v63
	v_pk_add_f32 v[58:59], v[76:77], 1.0 op_sel_hi:[1,0]
	v_and_b32_e32 v57, 0xffff0000, v63
	v_rcp_f32_e32 v64, v59
	s_nop 0
	v_mul_f32_e32 v59, v62, v64
	v_rcp_f32_e32 v63, v58
	s_nop 0
	v_mul_f32_e32 v58, v60, v63
	v_lshlrev_b32_e32 v60, 16, v61
	v_and_b32_e32 v61, 0xffff0000, v61
	v_rcp_f32_e32 v63, v53
	v_pk_add_f32 v[56:57], v[58:59], v[56:57]
	v_lshlrev_b32_e32 v58, 16, v65
	v_and_b32_e32 v59, 0xffff0000, v65
	v_mul_f32_e32 v53, v61, v63
	v_rcp_f32_e32 v62, v52
	s_nop 0
	v_mul_f32_e32 v52, v60, v62
	v_pk_add_f32 v[52:53], v[52:53], v[58:59]
	s_and_b64 vcc, exec, s[40:41]
	s_cbranch_vccnz .LBB0_1302
	global_store_dwordx4 v[130:131], v[54:57], off offset:512
	global_store_dwordx4 v[130:131], v[50:53], off offset:528
	s_cbranch_execnz .LBB0_1276

; __device__ __forceinline__ unsigned cvt_pk_bf16(float lo, float hi) { unsigned r; asm volatile("v_cvt_pk_bf16_f32 %0, %1, %2" : "=v"(r) : "v"(lo), "v"(hi)); return r; }
;     __device__ __forceinline__ void operator()(const f32x4 (&acc)[2][2][4][2], const Unit& u, int wr, int wc, int fr, int fq) const {
;     ...
;                 for (int m = 0; m < 4; ++m) { const size_t off = (size_t)(u.pm * BM + ai * HALF + wr * 64 + m * 16 + fr) * ldc + col0 + bj * HALF;
;                     const u32x4 xr = *(const u32x4*)(XB + off), pr = *(const u32x4*)(Pp + off); const f32x4 a0 = acc[ai][bj][m][0] + b0, a1 = acc[ai][bj][m][1] + b1;
;                     float x[8], p[8], o[8];
; #pragma unroll
;                     for (int e = 0; e < 4; ++e) { x[2 * e] = __uint_as_float(xr[e] << 16); x[2 * e + 1] = __uint_as_float(xr[e] & 0xffff0000u); p[2 * e] = __uint_as_float(pr[e] << 16); p[2 * e + 1] = __uint_as_float(pr[e] & 0xffff0000u); }
; #pragma unroll
;                     for (int e = 0; e < 4; ++e) { o[e] = x[e] + p[e] / (1.0f + __expf(-a0[e])); o[4 + e] = x[4 + e] + p[4 + e] / (1.0f + __expf(-a1[e])); }
;                     if (OutF) { *(f32x4*)(OutF + off) = (f32x4){o[0], o[1], o[2], o[3]}; *(f32x4*)(OutF + off + 4) = (f32x4){o[4], o[5], o[6], o[7]}; }
;                     else { u32x4 w; w.x = cvt_pk_bf16(o[0], o[1]); w.y = cvt_pk_bf16(o[2], o[3]); w.z = cvt_pk_bf16(o[4], o[5]); w.w = cvt_pk_bf16(o[6], o[7]); *(u32x4*)(XBout + off) = w; } } }
.LBB0_1276:
	v_lshl_add_u64 v[58:59], v[132:133], 0, v[158:159]
	v_lshlrev_b64 v[50:51], 1, v[58:59]
	v_lshl_add_u64 v[52:53], s[36:37], 0, v[50:51]
	v_lshl_add_u64 v[50:51], s[60:61], 0, v[50:51]
	global_load_dwordx4 v[54:57], v[52:53], off
	v_add_f32_e32 v44, v44, v70
	global_load_dwordx4 v[50:53], v[50:51], off
	v_add_f32_e32 v45, v45, v71
	v_mul_f32_e32 v44, 0xbfb8aa3b, v44
	v_mul_f32_e32 v45, 0xbfb8aa3b, v45
	v_exp_f32_e32 v44, v44
	v_exp_f32_e32 v45, v45
	v_add_f32_e32 v40, v40, v66
	v_add_f32_e32 v41, v41, v67
	v_mul_f32_e32 v40, 0xbfb8aa3b, v40
	v_pk_add_f32 v[44:45], v[44:45], 1.0 op_sel_hi:[1,0]
	v_mul_f32_e32 v41, 0xbfb8aa3b, v41
	v_exp_f32_e32 v40, v40
	v_exp_f32_e32 v41, v41
	v_add_f32_e32 v46, v46, v72
	v_mul_f32_e32 v46, 0xbfb8aa3b, v46
	v_add_f32_e32 v42, v42, v68
	v_pk_add_f32 v[40:41], v[40:41], 1.0 op_sel_hi:[1,0]
	v_add_f32_e32 v43, v43, v69
	v_mul_f32_e32 v42, 0xbfb8aa3b, v42
	v_mul_f32_e32 v43, 0xbfb8aa3b, v43
	v_exp_f32_e32 v42, v42
	v_exp_f32_e32 v43, v43
	s_waitcnt vmcnt(1)
	v_lshlrev_b32_e32 v60, 16, v54
	v_and_b32_e32 v61, 0xffff0000, v54
	s_waitcnt vmcnt(0)
	v_lshlrev_b32_e32 v54, 16, v50
	v_and_b32_e32 v50, 0xffff0000, v50
	v_rcp_f32_e32 v63, v45
	v_pk_add_f32 v[42:43], v[42:43], 1.0 op_sel_hi:[1,0]
	v_mul_f32_e32 v45, v50, v63
	v_rcp_f32_e32 v62, v44
	s_nop 0
	v_mul_f32_e32 v44, v54, v62
	v_lshlrev_b32_e32 v50, 16, v52
	v_and_b32_e32 v52, 0xffff0000, v52
	v_pk_add_f32 v[44:45], v[44:45], v[60:61]
	v_lshlrev_b32_e32 v60, 16, v56
	v_and_b32_e32 v61, 0xffff0000, v56
	v_rcp_f32_e32 v56, v41
	s_nop 0
	v_mul_f32_e32 v41, v52, v56
	v_rcp_f32_e32 v54, v40
	s_nop 0
	v_mul_f32_e32 v40, v50, v54
	v_pk_add_f32 v[40:41], v[40:41], v[60:61]
	v_exp_f32_e32 v60, v46
	v_add_f32_e32 v46, v47, v73
	v_mul_f32_e32 v46, 0xbfb8aa3b, v46
	v_exp_f32_e32 v61, v46
	v_lshlrev_b32_e32 v52, 16, v51
	v_and_b32_e32 v54, 0xffff0000, v51
	v_lshlrev_b32_e32 v46, 16, v55
	v_pk_add_f32 v[50:51], v[60:61], 1.0 op_sel_hi:[1,0]
	v_and_b32_e32 v47, 0xffff0000, v55
	v_rcp_f32_e32 v56, v51
	s_nop 0
	v_mul_f32_e32 v51, v54, v56
	v_rcp_f32_e32 v55, v50
	s_nop 0
	v_mul_f32_e32 v50, v52, v55
	v_lshlrev_b32_e32 v52, 16, v53
	v_and_b32_e32 v53, 0xffff0000, v53
	v_rcp_f32_e32 v55, v43
	v_pk_add_f32 v[46:47], v[50:51], v[46:47]
	v_lshlrev_b32_e32 v50, 16, v57
	v_and_b32_e32 v51, 0xffff0000, v57
	v_mul_f32_e32 v43, v53, v55
	v_rcp_f32_e32 v54, v42
	s_nop 0
	v_mul_f32_e32 v42, v52, v54
	v_pk_add_f32 v[42:43], v[42:43], v[50:51]
	s_and_b64 vcc, exec, s[40:41]
	s_cbranch_vccnz .LBB0_1303
	global_store_dwordx4 v[122:123], v[44:47], off offset:512
	global_store_dwordx4 v[122:123], v[40:43], off offset:528
	s_cbranch_execnz .LBB0_1279

; __device__ __forceinline__ unsigned cvt_pk_bf16(float lo, float hi) { unsigned r; asm volatile("v_cvt_pk_bf16_f32 %0, %1, %2" : "=v"(r) : "v"(lo), "v"(hi)); return r; }
;     __device__ __forceinline__ void operator()(const f32x4 (&acc)[2][2][4][2], const Unit& u, int wr, int wc, int fr, int fq) const {
;     ...
;                 for (int m = 0; m < 4; ++m) { const size_t off = (size_t)(u.pm * BM + ai * HALF + wr * 64 + m * 16 + fr) * ldc + col0 + bj * HALF;
;                     const u32x4 xr = *(const u32x4*)(XB + off), pr = *(const u32x4*)(Pp + off); const f32x4 a0 = acc[ai][bj][m][0] + b0, a1 = acc[ai][bj][m][1] + b1;
;                     float x[8], p[8], o[8];
; #pragma unroll
;                     for (int e = 0; e < 4; ++e) { x[2 * e] = __uint_as_float(xr[e] << 16); x[2 * e + 1] = __uint_as_float(xr[e] & 0xffff0000u); p[2 * e] = __uint_as_float(pr[e] << 16); p[2 * e + 1] = __uint_as_float(pr[e] & 0xffff0000u); }
; #pragma unroll
;                     for (int e = 0; e < 4; ++e) { o[e] = x[e] + p[e] / (1.0f + __expf(-a0[e])); o[4 + e] = x[4 + e] + p[4 + e] / (1.0f + __expf(-a1[e])); }
;                     if (OutF) { *(f32x4*)(OutF + off) = (f32x4){o[0], o[1], o[2], o[3]}; *(f32x4*)(OutF + off + 4) = (f32x4){o[4], o[5], o[6], o[7]}; }
;                     else { u32x4 w; w.x = cvt_pk_bf16(o[0], o[1]); w.y = cvt_pk_bf16(o[2], o[3]); w.z = cvt_pk_bf16(o[4], o[5]); w.w = cvt_pk_bf16(o[6], o[7]); *(u32x4*)(XBout + off) = w; } } }
.LBB0_1279:
	v_lshl_add_u64 v[50:51], v[124:125], 0, v[158:159]
	v_lshlrev_b64 v[40:41], 1, v[50:51]
	v_lshl_add_u64 v[42:43], s[36:37], 0, v[40:41]
	v_lshl_add_u64 v[40:41], s[60:61], 0, v[40:41]
	global_load_dwordx4 v[44:47], v[42:43], off
	v_add_f32_e32 v36, v36, v70
	global_load_dwordx4 v[40:43], v[40:41], off
	v_add_f32_e32 v37, v37, v71
	v_mul_f32_e32 v36, 0xbfb8aa3b, v36
	v_mul_f32_e32 v37, 0xbfb8aa3b, v37
	v_exp_f32_e32 v36, v36
	v_exp_f32_e32 v37, v37
	v_add_f32_e32 v32, v32, v66
	v_add_f32_e32 v33, v33, v67
	v_mul_f32_e32 v32, 0xbfb8aa3b, v32
	v_pk_add_f32 v[36:37], v[36:37], 1.0 op_sel_hi:[1,0]
	v_mul_f32_e32 v33, 0xbfb8aa3b, v33
	v_exp_f32_e32 v32, v32
	v_exp_f32_e32 v33, v33
	v_add_f32_e32 v38, v38, v72
	v_mul_f32_e32 v38, 0xbfb8aa3b, v38
	v_add_f32_e32 v34, v34, v68
	v_pk_add_f32 v[32:33], v[32:33], 1.0 op_sel_hi:[1,0]
	v_add_f32_e32 v35, v35, v69
	v_mul_f32_e32 v34, 0xbfb8aa3b, v34
	v_mul_f32_e32 v35, 0xbfb8aa3b, v35
	v_exp_f32_e32 v34, v34
	v_exp_f32_e32 v35, v35
	s_waitcnt vmcnt(1)
	v_lshlrev_b32_e32 v52, 16, v44
	v_and_b32_e32 v53, 0xffff0000, v44
	s_waitcnt vmcnt(0)
	v_lshlrev_b32_e32 v44, 16, v40
	v_and_b32_e32 v40, 0xffff0000, v40
	v_rcp_f32_e32 v55, v37
	v_pk_add_f32 v[34:35], v[34:35], 1.0 op_sel_hi:[1,0]
	v_mul_f32_e32 v37, v40, v55
	v_rcp_f32_e32 v54, v36
	s_nop 0
	v_mul_f32_e32 v36, v44, v54
	v_lshlrev_b32_e32 v40, 16, v42
	v_and_b32_e32 v42, 0xffff0000, v42
	v_pk_add_f32 v[36:37], v[36:37], v[52:53]
	v_lshlrev_b32_e32 v52, 16, v46
	v_and_b32_e32 v53, 0xffff0000, v46
	v_rcp_f32_e32 v46, v33
	s_nop 0
	v_mul_f32_e32 v33, v42, v46
	v_rcp_f32_e32 v44, v32
	s_nop 0
	v_mul_f32_e32 v32, v40, v44
	v_pk_add_f32 v[32:33], v[32:33], v[52:53]
	v_exp_f32_e32 v52, v38
	v_add_f32_e32 v38, v39, v73
	v_mul_f32_e32 v38, 0xbfb8aa3b, v38
	v_exp_f32_e32 v53, v38
	v_lshlrev_b32_e32 v42, 16, v41
	v_and_b32_e32 v44, 0xffff0000, v41
	v_lshlrev_b32_e32 v38, 16, v45
	v_pk_add_f32 v[40:41], v[52:53], 1.0 op_sel_hi:[1,0]
	v_and_b32_e32 v39, 0xffff0000, v45
	v_rcp_f32_e32 v46, v41
	s_nop 0
	v_mul_f32_e32 v41, v44, v46
	v_rcp_f32_e32 v45, v40
	s_nop 0
	v_mul_f32_e32 v40, v42, v45
	v_lshlrev_b32_e32 v42, 16, v43
	v_and_b32_e32 v43, 0xffff0000, v43
	v_rcp_f32_e32 v45, v35
	v_pk_add_f32 v[38:39], v[40:41], v[38:39]
	v_lshlrev_b32_e32 v40, 16, v47
	v_and_b32_e32 v41, 0xffff0000, v47
	v_mul_f32_e32 v35, v43, v45
	v_rcp_f32_e32 v44, v34
	s_nop 0
	v_mul_f32_e32 v34, v42, v44
	v_pk_add_f32 v[34:35], v[34:35], v[40:41]
	s_and_b64 vcc, exec, s[40:41]
	s_cbranch_vccnz .LBB0_1304
	global_store_dwordx4 v[114:115], v[36:39], off offset:512
	global_store_dwordx4 v[114:115], v[32:35], off offset:528
	s_cbranch_execnz .LBB0_1282

; __device__ __forceinline__ unsigned cvt_pk_bf16(float lo, float hi) { unsigned r; asm volatile("v_cvt_pk_bf16_f32 %0, %1, %2" : "=v"(r) : "v"(lo), "v"(hi)); return r; }
;     __device__ __forceinline__ void operator()(const f32x4 (&acc)[2][2][4][2], const Unit& u, int wr, int wc, int fr, int fq) const {
;     ...
;                 for (int m = 0; m < 4; ++m) { const size_t off = (size_t)(u.pm * BM + ai * HALF + wr * 64 + m * 16 + fr) * ldc + col0 + bj * HALF;
;                     const u32x4 xr = *(const u32x4*)(XB + off), pr = *(const u32x4*)(Pp + off); const f32x4 a0 = acc[ai][bj][m][0] + b0, a1 = acc[ai][bj][m][1] + b1;
;                     float x[8], p[8], o[8];
; #pragma unroll
;                     for (int e = 0; e < 4; ++e) { x[2 * e] = __uint_as_float(xr[e] << 16); x[2 * e + 1] = __uint_as_float(xr[e] & 0xffff0000u); p[2 * e] = __uint_as_float(pr[e] << 16); p[2 * e + 1] = __uint_as_float(pr[e] & 0xffff0000u); }
; #pragma unroll
;                     for (int e = 0; e < 4; ++e) { o[e] = x[e] + p[e] / (1.0f + __expf(-a0[e])); o[4 + e] = x[4 + e] + p[4 + e] / (1.0f + __expf(-a1[e])); }
;                     if (OutF) { *(f32x4*)(OutF + off) = (f32x4){o[0], o[1], o[2], o[3]}; *(f32x4*)(OutF + off + 4) = (f32x4){o[4], o[5], o[6], o[7]}; }
;                     else { u32x4 w; w.x = cvt_pk_bf16(o[0], o[1]); w.y = cvt_pk_bf16(o[2], o[3]); w.z = cvt_pk_bf16(o[4], o[5]); w.w = cvt_pk_bf16(o[6], o[7]); *(u32x4*)(XBout + off) = w; } } }
.LBB0_1282:
	v_lshl_add_u64 v[40:41], v[116:117], 0, v[158:159]
	v_lshlrev_b64 v[32:33], 1, v[40:41]
	v_lshl_add_u64 v[34:35], s[36:37], 0, v[32:33]
	v_lshl_add_u64 v[32:33], s[60:61], 0, v[32:33]
	global_load_dwordx4 v[36:39], v[34:35], off
	v_add_f32_e32 v28, v28, v70
	global_load_dwordx4 v[32:35], v[32:33], off
	v_add_f32_e32 v29, v29, v71
	v_mul_f32_e32 v28, 0xbfb8aa3b, v28
	v_mul_f32_e32 v29, 0xbfb8aa3b, v29
	v_exp_f32_e32 v28, v28
	v_exp_f32_e32 v29, v29
	v_add_f32_e32 v24, v24, v66
	v_add_f32_e32 v25, v25, v67
	v_mul_f32_e32 v24, 0xbfb8aa3b, v24
	v_pk_add_f32 v[28:29], v[28:29], 1.0 op_sel_hi:[1,0]
	v_mul_f32_e32 v25, 0xbfb8aa3b, v25
	v_exp_f32_e32 v24, v24
	v_exp_f32_e32 v25, v25
	v_add_f32_e32 v30, v30, v72
	v_mul_f32_e32 v30, 0xbfb8aa3b, v30
	v_add_f32_e32 v26, v26, v68
	v_pk_add_f32 v[24:25], v[24:25], 1.0 op_sel_hi:[1,0]
	v_add_f32_e32 v27, v27, v69
	v_mul_f32_e32 v26, 0xbfb8aa3b, v26
	v_mul_f32_e32 v27, 0xbfb8aa3b, v27
	v_exp_f32_e32 v26, v26
	v_exp_f32_e32 v27, v27
	s_waitcnt vmcnt(1)
	v_lshlrev_b32_e32 v42, 16, v36
	v_and_b32_e32 v43, 0xffff0000, v36
	s_waitcnt vmcnt(0)
	v_lshlrev_b32_e32 v36, 16, v32
	v_and_b32_e32 v32, 0xffff0000, v32
	v_rcp_f32_e32 v45, v29
	v_pk_add_f32 v[26:27], v[26:27], 1.0 op_sel_hi:[1,0]
	v_mul_f32_e32 v29, v32, v45
	v_rcp_f32_e32 v44, v28
	s_nop 0
	v_mul_f32_e32 v28, v36, v44
	v_lshlrev_b32_e32 v32, 16, v34
	v_and_b32_e32 v34, 0xffff0000, v34
	v_pk_add_f32 v[28:29], v[28:29], v[42:43]
	v_lshlrev_b32_e32 v42, 16, v38
	v_and_b32_e32 v43, 0xffff0000, v38
	v_rcp_f32_e32 v38, v25
	s_nop 0
	v_mul_f32_e32 v25, v34, v38
	v_rcp_f32_e32 v36, v24
	s_nop 0
	v_mul_f32_e32 v24, v32, v36
	v_pk_add_f32 v[24:25], v[24:25], v[42:43]
	v_exp_f32_e32 v42, v30
	v_add_f32_e32 v30, v31, v73
	v_mul_f32_e32 v30, 0xbfb8aa3b, v30
	v_exp_f32_e32 v43, v30
	v_lshlrev_b32_e32 v34, 16, v33
	v_and_b32_e32 v36, 0xffff0000, v33
	v_lshlrev_b32_e32 v30, 16, v37
	v_pk_add_f32 v[32:33], v[42:43], 1.0 op_sel_hi:[1,0]
	v_and_b32_e32 v31, 0xffff0000, v37
	v_rcp_f32_e32 v38, v33
	s_nop 0
	v_mul_f32_e32 v33, v36, v38
	v_rcp_f32_e32 v37, v32
	s_nop 0
	v_mul_f32_e32 v32, v34, v37
	v_lshlrev_b32_e32 v34, 16, v35
	v_and_b32_e32 v35, 0xffff0000, v35
	v_rcp_f32_e32 v37, v27
	v_pk_add_f32 v[30:31], v[32:33], v[30:31]
	v_lshlrev_b32_e32 v32, 16, v39
	v_and_b32_e32 v33, 0xffff0000, v39
	v_mul_f32_e32 v27, v35, v37
	v_rcp_f32_e32 v36, v26
	s_nop 0
	v_mul_f32_e32 v26, v34, v36
	v_pk_add_f32 v[26:27], v[26:27], v[32:33]
	s_and_b64 vcc, exec, s[40:41]
	s_cbranch_vccnz .LBB0_1305
	global_store_dwordx4 v[106:107], v[28:31], off offset:512
	global_store_dwordx4 v[106:107], v[24:27], off offset:528
	s_cbranch_execnz .LBB0_1285

; __device__ __forceinline__ unsigned cvt_pk_bf16(float lo, float hi) { unsigned r; asm volatile("v_cvt_pk_bf16_f32 %0, %1, %2" : "=v"(r) : "v"(lo), "v"(hi)); return r; }
;     __device__ __forceinline__ void operator()(const f32x4 (&acc)[2][2][4][2], const Unit& u, int wr, int wc, int fr, int fq) const {
;     ...
;                 for (int m = 0; m < 4; ++m) { const size_t off = (size_t)(u.pm * BM + ai * HALF + wr * 64 + m * 16 + fr) * ldc + col0 + bj * HALF;
;                     const u32x4 xr = *(const u32x4*)(XB + off), pr = *(const u32x4*)(Pp + off); const f32x4 a0 = acc[ai][bj][m][0] + b0, a1 = acc[ai][bj][m][1] + b1;
;                     float x[8], p[8], o[8];
; #pragma unroll
;                     for (int e = 0; e < 4; ++e) { x[2 * e] = __uint_as_float(xr[e] << 16); x[2 * e + 1] = __uint_as_float(xr[e] & 0xffff0000u); p[2 * e] = __uint_as_float(pr[e] << 16); p[2 * e + 1] = __uint_as_float(pr[e] & 0xffff0000u); }
; #pragma unroll
;                     for (int e = 0; e < 4; ++e) { o[e] = x[e] + p[e] / (1.0f + __expf(-a0[e])); o[4 + e] = x[4 + e] + p[4 + e] / (1.0f + __expf(-a1[e])); }
;                     if (OutF) { *(f32x4*)(OutF + off) = (f32x4){o[0], o[1], o[2], o[3]}; *(f32x4*)(OutF + off + 4) = (f32x4){o[4], o[5], o[6], o[7]}; }
;                     else { u32x4 w; w.x = cvt_pk_bf16(o[0], o[1]); w.y = cvt_pk_bf16(o[2], o[3]); w.z = cvt_pk_bf16(o[4], o[5]); w.w = cvt_pk_bf16(o[6], o[7]); *(u32x4*)(XBout + off) = w; } } }
.LBB0_1285:
	v_lshl_add_u64 v[32:33], v[108:109], 0, v[158:159]
	v_lshlrev_b64 v[24:25], 1, v[32:33]
	v_lshl_add_u64 v[26:27], s[36:37], 0, v[24:25]
	v_lshl_add_u64 v[24:25], s[60:61], 0, v[24:25]
	global_load_dwordx4 v[28:31], v[26:27], off
	v_add_f32_e32 v20, v20, v70
	global_load_dwordx4 v[24:27], v[24:25], off
	v_add_f32_e32 v21, v21, v71
	v_mul_f32_e32 v20, 0xbfb8aa3b, v20
	v_mul_f32_e32 v21, 0xbfb8aa3b, v21
	v_exp_f32_e32 v20, v20
	v_exp_f32_e32 v21, v21
	v_add_f32_e32 v16, v16, v66
	v_add_f32_e32 v17, v17, v67
	v_mul_f32_e32 v16, 0xbfb8aa3b, v16
	v_pk_add_f32 v[20:21], v[20:21], 1.0 op_sel_hi:[1,0]
	v_mul_f32_e32 v17, 0xbfb8aa3b, v17
	v_exp_f32_e32 v16, v16
	v_exp_f32_e32 v17, v17
	v_add_f32_e32 v22, v22, v72
	v_mul_f32_e32 v22, 0xbfb8aa3b, v22
	v_add_f32_e32 v18, v18, v68
	v_pk_add_f32 v[16:17], v[16:17], 1.0 op_sel_hi:[1,0]
	v_add_f32_e32 v19, v19, v69
	v_mul_f32_e32 v18, 0xbfb8aa3b, v18
	v_mul_f32_e32 v19, 0xbfb8aa3b, v19
	v_exp_f32_e32 v18, v18
	v_exp_f32_e32 v19, v19
	s_waitcnt vmcnt(1)
	v_lshlrev_b32_e32 v34, 16, v28
	v_and_b32_e32 v35, 0xffff0000, v28
	s_waitcnt vmcnt(0)
	v_lshlrev_b32_e32 v28, 16, v24
	v_and_b32_e32 v24, 0xffff0000, v24
	v_rcp_f32_e32 v37, v21
	v_pk_add_f32 v[18:19], v[18:19], 1.0 op_sel_hi:[1,0]
	v_mul_f32_e32 v21, v24, v37
	v_rcp_f32_e32 v36, v20
	s_nop 0
	v_mul_f32_e32 v20, v28, v36
	v_lshlrev_b32_e32 v24, 16, v26
	v_and_b32_e32 v26, 0xffff0000, v26
	v_pk_add_f32 v[20:21], v[20:21], v[34:35]
	v_lshlrev_b32_e32 v34, 16, v30
	v_and_b32_e32 v35, 0xffff0000, v30
	v_rcp_f32_e32 v30, v17
	s_nop 0
	v_mul_f32_e32 v17, v26, v30
	v_rcp_f32_e32 v28, v16
	s_nop 0
	v_mul_f32_e32 v16, v24, v28
	v_pk_add_f32 v[16:17], v[16:17], v[34:35]
	v_exp_f32_e32 v34, v22
	v_add_f32_e32 v22, v23, v73
	v_mul_f32_e32 v22, 0xbfb8aa3b, v22
	v_exp_f32_e32 v35, v22
	v_lshlrev_b32_e32 v26, 16, v25
	v_and_b32_e32 v28, 0xffff0000, v25
	v_lshlrev_b32_e32 v22, 16, v29
	v_pk_add_f32 v[24:25], v[34:35], 1.0 op_sel_hi:[1,0]
	v_and_b32_e32 v23, 0xffff0000, v29
	v_rcp_f32_e32 v30, v25
	s_nop 0
	v_mul_f32_e32 v25, v28, v30
	v_rcp_f32_e32 v29, v24
	s_nop 0
	v_mul_f32_e32 v24, v26, v29
	v_lshlrev_b32_e32 v26, 16, v27
	v_and_b32_e32 v27, 0xffff0000, v27
	v_rcp_f32_e32 v29, v19
	v_pk_add_f32 v[22:23], v[24:25], v[22:23]
	v_lshlrev_b32_e32 v24, 16, v31
	v_and_b32_e32 v25, 0xffff0000, v31
	v_mul_f32_e32 v19, v27, v29
	v_rcp_f32_e32 v28, v18
	s_nop 0
	v_mul_f32_e32 v18, v26, v28
	v_pk_add_f32 v[18:19], v[18:19], v[24:25]
	s_and_b64 vcc, exec, s[40:41]
	s_cbranch_vccnz .LBB0_1306
	global_store_dwordx4 v[98:99], v[20:23], off offset:512
	global_store_dwordx4 v[98:99], v[16:19], off offset:528
	s_cbranch_execnz .LBB0_1288

; __device__ __forceinline__ unsigned cvt_pk_bf16(float lo, float hi) { unsigned r; asm volatile("v_cvt_pk_bf16_f32 %0, %1, %2" : "=v"(r) : "v"(lo), "v"(hi)); return r; }
;     __device__ __forceinline__ void operator()(const f32x4 (&acc)[2][2][4][2], const Unit& u, int wr, int wc, int fr, int fq) const {
;     ...
;                 for (int m = 0; m < 4; ++m) { const size_t off = (size_t)(u.pm * BM + ai * HALF + wr * 64 + m * 16 + fr) * ldc + col0 + bj * HALF;
;                     const u32x4 xr = *(const u32x4*)(XB + off), pr = *(const u32x4*)(Pp + off); const f32x4 a0 = acc[ai][bj][m][0] + b0, a1 = acc[ai][bj][m][1] + b1;
;                     float x[8], p[8], o[8];
; #pragma unroll
;                     for (int e = 0; e < 4; ++e) { x[2 * e] = __uint_as_float(xr[e] << 16); x[2 * e + 1] = __uint_as_float(xr[e] & 0xffff0000u); p[2 * e] = __uint_as_float(pr[e] << 16); p[2 * e + 1] = __uint_as_float(pr[e] & 0xffff0000u); }
; #pragma unroll
;                     for (int e = 0; e < 4; ++e) { o[e] = x[e] + p[e] / (1.0f + __expf(-a0[e])); o[4 + e] = x[4 + e] + p[4 + e] / (1.0f + __expf(-a1[e])); }
;                     if (OutF) { *(f32x4*)(OutF + off) = (f32x4){o[0], o[1], o[2], o[3]}; *(f32x4*)(OutF + off + 4) = (f32x4){o[4], o[5], o[6], o[7]}; }
;                     else { u32x4 w; w.x = cvt_pk_bf16(o[0], o[1]); w.y = cvt_pk_bf16(o[2], o[3]); w.z = cvt_pk_bf16(o[4], o[5]); w.w = cvt_pk_bf16(o[6], o[7]); *(u32x4*)(XBout + off) = w; } } }
.LBB0_1288:
	v_lshl_add_u64 v[24:25], v[100:101], 0, v[158:159]
	v_lshlrev_b64 v[16:17], 1, v[24:25]
	v_lshl_add_u64 v[18:19], s[36:37], 0, v[16:17]
	v_lshl_add_u64 v[16:17], s[60:61], 0, v[16:17]
	global_load_dwordx4 v[20:23], v[18:19], off
	v_add_f32_e32 v12, v12, v70
	global_load_dwordx4 v[16:19], v[16:17], off
	v_add_f32_e32 v13, v13, v71
	v_mul_f32_e32 v12, 0xbfb8aa3b, v12
	v_mul_f32_e32 v13, 0xbfb8aa3b, v13
	v_exp_f32_e32 v12, v12
	v_exp_f32_e32 v13, v13
	v_add_f32_e32 v8, v8, v66
	v_add_f32_e32 v9, v9, v67
	v_mul_f32_e32 v8, 0xbfb8aa3b, v8
	v_pk_add_f32 v[12:13], v[12:13], 1.0 op_sel_hi:[1,0]
	v_mul_f32_e32 v9, 0xbfb8aa3b, v9
	v_exp_f32_e32 v8, v8
	v_exp_f32_e32 v9, v9
	v_add_f32_e32 v14, v14, v72
	v_mul_f32_e32 v14, 0xbfb8aa3b, v14
	v_add_f32_e32 v10, v10, v68
	v_pk_add_f32 v[8:9], v[8:9], 1.0 op_sel_hi:[1,0]
	v_add_f32_e32 v11, v11, v69
	v_mul_f32_e32 v10, 0xbfb8aa3b, v10
	v_mul_f32_e32 v11, 0xbfb8aa3b, v11
	v_exp_f32_e32 v10, v10
	v_exp_f32_e32 v11, v11
	s_waitcnt vmcnt(1)
	v_lshlrev_b32_e32 v26, 16, v20
	v_and_b32_e32 v27, 0xffff0000, v20
	s_waitcnt vmcnt(0)
	v_lshlrev_b32_e32 v20, 16, v16
	v_and_b32_e32 v16, 0xffff0000, v16
	v_rcp_f32_e32 v29, v13
	v_pk_add_f32 v[10:11], v[10:11], 1.0 op_sel_hi:[1,0]
	v_mul_f32_e32 v13, v16, v29
	v_rcp_f32_e32 v28, v12
	s_nop 0
	v_mul_f32_e32 v12, v20, v28
	v_lshlrev_b32_e32 v16, 16, v18
	v_and_b32_e32 v18, 0xffff0000, v18
	v_pk_add_f32 v[12:13], v[12:13], v[26:27]
	v_lshlrev_b32_e32 v26, 16, v22
	v_and_b32_e32 v27, 0xffff0000, v22
	v_rcp_f32_e32 v22, v9
	s_nop 0
	v_mul_f32_e32 v9, v18, v22
	v_rcp_f32_e32 v20, v8
	s_nop 0
	v_mul_f32_e32 v8, v16, v20
	v_pk_add_f32 v[8:9], v[8:9], v[26:27]
	v_exp_f32_e32 v26, v14
	v_add_f32_e32 v14, v15, v73
	v_mul_f32_e32 v14, 0xbfb8aa3b, v14
	v_exp_f32_e32 v27, v14
	v_lshlrev_b32_e32 v18, 16, v17
	v_and_b32_e32 v20, 0xffff0000, v17
	v_lshlrev_b32_e32 v14, 16, v21
	v_pk_add_f32 v[16:17], v[26:27], 1.0 op_sel_hi:[1,0]
	v_and_b32_e32 v15, 0xffff0000, v21
	v_rcp_f32_e32 v22, v17
	s_nop 0
	v_mul_f32_e32 v17, v20, v22
	v_rcp_f32_e32 v21, v16
	s_nop 0
	v_mul_f32_e32 v16, v18, v21
	v_lshlrev_b32_e32 v18, 16, v19
	v_and_b32_e32 v19, 0xffff0000, v19
	v_rcp_f32_e32 v21, v11
	v_pk_add_f32 v[14:15], v[16:17], v[14:15]
	v_lshlrev_b32_e32 v16, 16, v23
	v_and_b32_e32 v17, 0xffff0000, v23
	v_mul_f32_e32 v11, v19, v21
	v_rcp_f32_e32 v20, v10
	s_nop 0
	v_mul_f32_e32 v10, v18, v20
	v_pk_add_f32 v[10:11], v[10:11], v[16:17]
	s_and_b64 vcc, exec, s[40:41]
	s_cbranch_vccnz .LBB0_1307
	global_store_dwordx4 v[90:91], v[12:15], off offset:512
	global_store_dwordx4 v[90:91], v[8:11], off offset:528
	s_cbranch_execnz .LBB0_1291

; __device__ __forceinline__ unsigned cvt_pk_bf16(float lo, float hi) { unsigned r; asm volatile("v_cvt_pk_bf16_f32 %0, %1, %2" : "=v"(r) : "v"(lo), "v"(hi)); return r; }
;     __device__ __forceinline__ void operator()(const f32x4 (&acc)[2][2][4][2], const Unit& u, int wr, int wc, int fr, int fq) const {
;     ...
;                 for (int m = 0; m < 4; ++m) { const size_t off = (size_t)(u.pm * BM + ai * HALF + wr * 64 + m * 16 + fr) * ldc + col0 + bj * HALF;
;                     const u32x4 xr = *(const u32x4*)(XB + off), pr = *(const u32x4*)(Pp + off); const f32x4 a0 = acc[ai][bj][m][0] + b0, a1 = acc[ai][bj][m][1] + b1;
;                     float x[8], p[8], o[8];
; #pragma unroll
;                     for (int e = 0; e < 4; ++e) { x[2 * e] = __uint_as_float(xr[e] << 16); x[2 * e + 1] = __uint_as_float(xr[e] & 0xffff0000u); p[2 * e] = __uint_as_float(pr[e] << 16); p[2 * e + 1] = __uint_as_float(pr[e] & 0xffff0000u); }
; #pragma unroll
;                     for (int e = 0; e < 4; ++e) { o[e] = x[e] + p[e] / (1.0f + __expf(-a0[e])); o[4 + e] = x[4 + e] + p[4 + e] / (1.0f + __expf(-a1[e])); }
;                     if (OutF) { *(f32x4*)(OutF + off) = (f32x4){o[0], o[1], o[2], o[3]}; *(f32x4*)(OutF + off + 4) = (f32x4){o[4], o[5], o[6], o[7]}; }
;                     else { u32x4 w; w.x = cvt_pk_bf16(o[0], o[1]); w.y = cvt_pk_bf16(o[2], o[3]); w.z = cvt_pk_bf16(o[4], o[5]); w.w = cvt_pk_bf16(o[6], o[7]); *(u32x4*)(XBout + off) = w; } } }
.LBB0_1291:
	v_lshl_add_u64 v[16:17], v[92:93], 0, v[158:159]
	v_lshlrev_b64 v[8:9], 1, v[16:17]
	v_lshl_add_u64 v[10:11], s[36:37], 0, v[8:9]
	v_lshl_add_u64 v[8:9], s[60:61], 0, v[8:9]
	global_load_dwordx4 v[12:15], v[10:11], off
	v_add_f32_e32 v4, v4, v70
	global_load_dwordx4 v[8:11], v[8:9], off
	v_add_f32_e32 v5, v5, v71
	v_mul_f32_e32 v4, 0xbfb8aa3b, v4
	v_mul_f32_e32 v5, 0xbfb8aa3b, v5
	v_exp_f32_e32 v4, v4
	v_exp_f32_e32 v5, v5
	v_add_f32_e32 v0, v0, v66
	v_add_f32_e32 v1, v1, v67
	v_mul_f32_e32 v0, 0xbfb8aa3b, v0
	v_pk_add_f32 v[4:5], v[4:5], 1.0 op_sel_hi:[1,0]
	v_mul_f32_e32 v1, 0xbfb8aa3b, v1
	v_exp_f32_e32 v0, v0
	v_exp_f32_e32 v1, v1
	v_add_f32_e32 v6, v6, v72
	v_mul_f32_e32 v6, 0xbfb8aa3b, v6
	v_add_f32_e32 v2, v2, v68
	v_pk_add_f32 v[0:1], v[0:1], 1.0 op_sel_hi:[1,0]
	v_add_f32_e32 v3, v3, v69
	v_mul_f32_e32 v2, 0xbfb8aa3b, v2
	v_mul_f32_e32 v3, 0xbfb8aa3b, v3
	v_exp_f32_e32 v2, v2
	v_exp_f32_e32 v3, v3
	s_waitcnt vmcnt(1)
	v_lshlrev_b32_e32 v18, 16, v12
	v_and_b32_e32 v19, 0xffff0000, v12
	s_waitcnt vmcnt(0)
	v_lshlrev_b32_e32 v12, 16, v8
	v_and_b32_e32 v8, 0xffff0000, v8
	v_rcp_f32_e32 v21, v5
	v_pk_add_f32 v[2:3], v[2:3], 1.0 op_sel_hi:[1,0]
	v_mul_f32_e32 v5, v8, v21
	v_rcp_f32_e32 v20, v4
	s_nop 0
	v_mul_f32_e32 v4, v12, v20
	v_lshlrev_b32_e32 v8, 16, v10
	v_and_b32_e32 v10, 0xffff0000, v10
	v_pk_add_f32 v[4:5], v[4:5], v[18:19]
	v_lshlrev_b32_e32 v18, 16, v14
	v_and_b32_e32 v19, 0xffff0000, v14
	v_rcp_f32_e32 v14, v1
	s_nop 0
	v_mul_f32_e32 v1, v10, v14
	v_rcp_f32_e32 v12, v0
	s_nop 0
	v_mul_f32_e32 v0, v8, v12
	v_pk_add_f32 v[0:1], v[0:1], v[18:19]
	v_exp_f32_e32 v18, v6
	v_add_f32_e32 v6, v7, v73
	v_mul_f32_e32 v6, 0xbfb8aa3b, v6
	v_exp_f32_e32 v19, v6
	v_lshlrev_b32_e32 v10, 16, v9
	v_and_b32_e32 v12, 0xffff0000, v9
	v_lshlrev_b32_e32 v6, 16, v13
	v_pk_add_f32 v[8:9], v[18:19], 1.0 op_sel_hi:[1,0]
	v_and_b32_e32 v7, 0xffff0000, v13
	v_rcp_f32_e32 v14, v9
	s_nop 0
	v_mul_f32_e32 v9, v12, v14
	v_rcp_f32_e32 v13, v8
	s_nop 0
	v_mul_f32_e32 v8, v10, v13
	v_lshlrev_b32_e32 v10, 16, v11
	v_and_b32_e32 v11, 0xffff0000, v11
	v_rcp_f32_e32 v13, v3
	v_pk_add_f32 v[6:7], v[8:9], v[6:7]
	v_lshlrev_b32_e32 v8, 16, v15
	v_and_b32_e32 v9, 0xffff0000, v15
	v_mul_f32_e32 v3, v11, v13
	v_rcp_f32_e32 v12, v2
	s_nop 0
	v_mul_f32_e32 v2, v10, v12
	v_pk_add_f32 v[2:3], v[2:3], v[8:9]
	s_and_b64 vcc, exec, s[40:41]
	s_cbranch_vccnz .LBB0_1308
	s_mov_b64 s[6:7], 0
	global_store_dwordx4 v[82:83], v[4:7], off offset:512
	global_store_dwordx4 v[82:83], v[0:3], off offset:528
	s_branch .LBB0_1309
